# P8 per-token tail hand-rewritten: 8-expert batched transposing reduction (permlane32/16 swap tree on exact int dots), GELU once per 8 experts, gate*gelu scalars in SGPRs for fp4 V accumulate; same f32
# speedup vs baseline: 1.0178x; 1.0178x over previous
.LBB0_917:
	s_or_b64 exec, exec, s[6:7]
	v_lshrrev_b32_e32 v3, 6, v204
	v_lshl_add_u32 v4, s2, 2, v3
	s_movk_i32 s2, 0x2200
	v_cmp_gt_i32_e32 vcc, s2, v4
	s_and_saveexec_b64 s[2:3], vcc
	s_cbranch_execz .LBB0_930
	v_and_b32_e32 v6, 32, v204
	s_add_u32 s74, s94, 0x1cb18000
	v_cmp_eq_u32_e64 s[8:9], 0, v6
	v_lshlrev_b32_e32 v6, 5, v0
	v_mov_b32_e32 v7, 0
	s_addc_u32 s75, s95, 0
	v_lshl_add_u64 v[8:9], s[94:95], 0, v[6:7]
	s_mov_b64 s[10:11], 0x13288000
	v_and_b32_e32 v6, 2, v204
	v_and_b32_e32 v10, 1, v204
	s_add_u32 s76, s94, 0x1cb08000
	v_lshl_add_u64 v[8:9], v[8:9], 0, s[10:11]
	v_cmp_ne_u32_e32 vcc, 0, v6
	v_cmp_eq_u32_e64 s[10:11], 0, v10
	v_and_b32_e32 v10, 4, v204
	s_addc_u32 s77, s95, 0
	s_xor_b64 s[12:13], vcc, s[10:11]
	v_cmp_ne_u32_e32 vcc, 0, v10
	v_cmp_eq_u32_e64 s[14:15], 0, v6
	v_and_b32_e32 v6, 8, v204
	v_lshlrev_b32_e32 v5, 10, v3
	v_and_b32_e32 v3, 16, v204
	s_xor_b64 s[16:17], vcc, s[14:15]
	s_xor_b64 s[18:19], vcc, s[10:11]
	v_cmp_ne_u32_e32 vcc, 0, v6
	v_cmp_eq_u32_e64 s[20:21], 0, v10
	v_cmp_eq_u32_e64 s[6:7], 0, v3
	s_xor_b64 s[22:23], vcc, s[20:21]
	s_xor_b64 s[24:25], vcc, s[14:15]
	s_xor_b64 s[26:27], vcc, s[10:11]
	v_cmp_ne_u32_e32 vcc, 0, v3
	v_mbcnt_lo_u32_b32 v3, -1, 0
	v_mbcnt_hi_u32_b32 v3, -1, v3
	s_load_dword s33, s[0:1], 0x120
	v_and_b32_e32 v166, 64, v3
	v_cndmask_b32_e64 v2, v2, 0, s[4:5]
	v_cmp_eq_u32_e64 s[28:29], 0, v6
	v_or_b32_e32 v2, v166, v2
	v_lshlrev_b32_e32 v6, 3, v0
	v_lshlrev_b32_e32 v167, 2, v2
	v_cndmask_b32_e64 v1, v1, 0, s[4:5]
	v_lshl_add_u64 v[2:3], s[94:95], 0, v[6:7]
	s_mov_b64 s[60:61], 0x8000
	v_lshlrev_b32_e32 v6, 6, v0
	v_cmp_lt_u32_e64 s[40:41], 31, v0
	v_or_b32_e32 v1, v166, v1
	v_lshl_add_u64 v[10:11], v[2:3], 0, s[60:61]
	s_mov_b64 s[60:61], 0x4008000
	v_lshl_add_u64 v[14:15], s[92:93], 0, v[6:7]
	v_lshlrev_b32_e32 v6, 2, v0
	v_add_u32_e32 v169, 32, v5
	s_movk_i32 s78, 0x7f
	v_xor_b32_e32 v164, 0x7f, v0
	v_xor_b32_e32 v165, 63, v0
	s_xor_b64 s[30:31], vcc, s[28:29]
	s_xor_b64 s[34:35], vcc, s[20:21]
	s_xor_b64 s[36:37], vcc, s[14:15]
	s_xor_b64 s[38:39], vcc, s[10:11]
	s_xor_b64 s[42:43], s[40:41], s[6:7]
	s_xor_b64 s[44:45], s[40:41], s[28:29]
	s_xor_b64 s[46:47], s[40:41], s[20:21]
	s_xor_b64 s[48:49], s[40:41], s[14:15]
	s_xor_b64 s[50:51], s[40:41], s[10:11]
	v_cmp_gt_u32_e64 s[52:53], 32, v0
	v_lshlrev_b32_e32 v168, 2, v1
	v_cmp_gt_u32_e64 s[54:55], 16, v0
	v_lshl_add_u64 v[12:13], v[2:3], 0, s[60:61]
	s_waitcnt lgkmcnt(0)
	s_lshl_b32 s79, s33, 2
	v_add_u32_e32 v170, v169, v6
	v_lshl_add_u64 v[16:17], s[94:95], 0, v[6:7]
	v_add_u32_e32 v6, 16, v169
	s_mov_b64 s[60:61], 0
	s_mov_b64 s[62:63], 0x1000
	s_movk_i32 s80, 0x1000
	v_mov_b32_e32 v171, 0x358637bd
	s_mov_b32 s81, 0x800000
	s_mov_b32 s82, 0xc0e00000
	s_mov_b32 s83, 0x3e6d3388
	v_mov_b32_e32 v172, 0xbf3a00e3
	s_movk_i32 s84, 0x21ff
	v_bfrev_b32_e32 v173, 1
	v_mov_b32_e32 v174, 0x40e00000
	s_branch .LBB0_920
.LBB0_920:
	v_ashrrev_i32_e32 v5, 31, v4
	v_lshlrev_b64 v[0:1], 13, v[4:5]
	v_lshl_add_u64 v[18:19], v[14:15], 0, v[0:1]
	global_load_dwordx4 v[24:27], v[18:19], off offset:16
	global_load_dwordx4 v[28:31], v[18:19], off
	global_load_dwordx4 v[32:35], v[18:19], off offset:48
	global_load_dwordx4 v[60:63], v[18:19], off offset:32
	v_lshlrev_b64 v[2:3], 12, v[4:5]
	v_add_co_u32_e32 v20, vcc, s80, v18
	v_lshl_add_u64 v[2:3], v[8:9], 0, v[2:3]
	s_nop 0
	v_addc_co_u32_e32 v21, vcc, 0, v19, vcc
	global_load_dwordx4 v[36:39], v[2:3], off
	global_load_dwordx4 v[64:67], v[2:3], off offset:16
	global_load_dwordx4 v[68:71], v[2:3], off offset:2048
	v_lshl_add_u64 v[22:23], v[18:19], 0, s[62:63]
	global_load_dwordx4 v[72:75], v[20:21], off
	global_load_dwordx4 v[76:79], v[22:23], off offset:16
	global_load_dwordx4 v[80:83], v[22:23], off offset:32
	global_load_dwordx4 v[84:87], v[22:23], off offset:48
	global_load_dwordx4 v[88:91], v[2:3], off offset:2064
	v_lshl_add_u64 v[0:1], v[16:17], 0, v[0:1]
	s_mov_b64 s[64:65], 0
	s_waitcnt vmcnt(11)
	v_mul_f32_e32 v40, v25, v25
	s_waitcnt vmcnt(10)
	v_mul_f32_e32 v5, v29, v29
	v_fmac_f32_e32 v5, v28, v28
	s_waitcnt vmcnt(8)
	v_mul_f32_e32 v42, v61, v61
	v_fmac_f32_e32 v40, v24, v24
	v_mul_f32_e32 v44, v33, v33
	v_fmac_f32_e32 v42, v60, v60
	v_fmac_f32_e32 v5, v30, v30
	v_fmac_f32_e32 v40, v26, v26
	s_waitcnt vmcnt(3)
	v_mov_b32_e32 v3, v76
	v_mov_b32_e32 v76, v73
	v_fmac_f32_e32 v44, v32, v32
	v_mov_b32_e32 v2, v72
	v_fmac_f32_e32 v42, v62, v62
	v_pk_mul_f32 v[60:61], v[76:77], v[76:77]
	v_fmac_f32_e32 v5, v31, v31
	v_fmac_f32_e32 v40, v27, v27
	v_mov_b32_e32 v24, v74
	v_mov_b32_e32 v25, v78
	s_waitcnt vmcnt(1)
	v_mov_b32_e32 v29, v84
	v_mov_b32_e32 v84, v81
	v_fmac_f32_e32 v44, v34, v34
	v_fmac_f32_e32 v42, v63, v63
	v_pk_fma_f32 v[2:3], v[2:3], v[2:3], v[60:61]
	v_add_f32_e32 v5, v5, v40
	v_lshlrev_b32_e32 v50, 16, v64
	v_and_b32_e32 v49, 0xffff0000, v64
	v_lshlrev_b32_e32 v48, 16, v65
	v_and_b32_e32 v47, 0xffff0000, v65
	v_mov_b32_e32 v78, v75
	v_mov_b32_e32 v28, v80
	v_pk_mul_f32 v[64:65], v[84:85], v[84:85]
	v_fmac_f32_e32 v44, v35, v35
	v_pk_fma_f32 v[2:3], v[24:25], v[24:25], v[2:3]
	v_add_f32_e32 v5, v5, v42
	v_mov_b32_e32 v32, v82
	v_mov_b32_e32 v33, v86
	v_pk_fma_f32 v[26:27], v[28:29], v[28:29], v[64:65]
	v_pk_fma_f32 v[2:3], v[78:79], v[78:79], v[2:3]
	v_add_f32_e32 v5, v5, v44
	v_mov_b32_e32 v86, v83
	v_pk_fma_f32 v[24:25], v[32:33], v[32:33], v[26:27]
	v_add_f32_e32 v2, v5, v2
	v_pk_fma_f32 v[24:25], v[86:87], v[86:87], v[24:25]
	v_add_f32_e32 v2, v2, v3
	v_add_f32_e32 v2, v2, v24
	v_add_f32_e32 v2, v2, v25
	v_mov_b32_e32 v3, v2
	v_mov_b32_e32 v5, v2
	s_nop 1
	v_permlane32_swap_b32_e32 v3, v5
	v_cndmask_b32_e64 v3, v3, v5, s[8:9]
	v_add_f32_e32 v2, v2, v3
	v_mov_b32_e32 v3, v2
	v_mov_b32_e32 v5, v2
	s_nop 1
	v_permlane16_swap_b32_e32 v3, v5
	v_cndmask_b32_e64 v3, v3, v5, s[6:7]
	v_add_f32_e32 v2, v2, v3
	v_lshlrev_b32_e32 v58, 16, v36
	v_and_b32_e32 v57, 0xffff0000, v36
	v_add_f32_dpp v2, v2, v2 row_ror:8 row_mask:0xf bank_mask:0xf bound_ctrl:1
	v_lshlrev_b32_e32 v56, 16, v37
	v_and_b32_e32 v55, 0xffff0000, v37
	v_mov_b32_dpp v3, v2 row_half_mirror row_mask:0xf bank_mask:0xf bound_ctrl:1
	v_max3_f32 v36, |v58|, 0, |v57|
	v_lshlrev_b32_e32 v54, 16, v38
	v_add_f32_dpp v2, v3, v2 quad_perm:[3,2,1,0] row_mask:0xf bank_mask:0xf bound_ctrl:1
	v_and_b32_e32 v53, 0xffff0000, v38
	v_max3_f32 v30, v36, |v56|, |v55|
	v_add_f32_dpp v2, v2, v2 quad_perm:[2,3,0,1] row_mask:0xf bank_mask:0xf bound_ctrl:1
	v_lshlrev_b32_e32 v52, 16, v39
	v_and_b32_e32 v51, 0xffff0000, v39
	v_max3_f32 v28, v30, |v54|, |v53|
	v_add_f32_dpp v2, v2, v2 quad_perm:[1,0,3,2] row_mask:0xf bank_mask:0xf bound_ctrl:1
	v_max3_f32 v26, v28, |v52|, |v51|
	v_fmamk_f32 v2, v2, 0x3a000000, v171
	v_max3_f32 v26, v26, |v50|, |v49|
	v_mul_f32_e32 v3, 0x4b800000, v2
	v_cmp_gt_f32_e32 vcc, s81, v2
	v_lshlrev_b32_e32 v46, 16, v66
	v_and_b32_e32 v45, 0xffff0000, v66
	v_cndmask_b32_e32 v2, v2, v3, vcc
	v_max3_f32 v3, v26, |v48|, |v47|
	v_lshlrev_b32_e32 v43, 16, v67
	v_and_b32_e32 v41, 0xffff0000, v67
	v_max3_f32 v3, v3, |v46|, |v45|
	v_lshlrev_b32_e32 v39, 16, v68
	v_and_b32_e32 v37, 0xffff0000, v68
	v_max3_f32 v3, v3, |v43|, |v41|
	v_lshlrev_b32_e32 v44, 16, v69
	v_and_b32_e32 v42, 0xffff0000, v69
	v_max3_f32 v3, v3, |v39|, |v37|
	v_lshlrev_b32_e32 v40, 16, v70
	v_and_b32_e32 v38, 0xffff0000, v70
	v_max3_f32 v3, v3, |v44|, |v42|
	v_lshlrev_b32_e32 v36, 16, v71
	v_and_b32_e32 v35, 0xffff0000, v71
	v_max3_f32 v3, v3, |v40|, |v38|
	s_waitcnt vmcnt(0)
	v_lshlrev_b32_e32 v34, 16, v88
	v_and_b32_e32 v33, 0xffff0000, v88
	v_max3_f32 v3, v3, |v36|, |v35|
	v_lshlrev_b32_e32 v32, 16, v89
	v_and_b32_e32 v31, 0xffff0000, v89
	v_max3_f32 v3, v3, |v34|, |v33|
	v_lshlrev_b32_e32 v30, 16, v90
	v_and_b32_e32 v29, 0xffff0000, v90
	v_max3_f32 v3, v3, |v32|, |v31|
	v_lshlrev_b32_e32 v25, 16, v91
	v_and_b32_e32 v5, 0xffff0000, v91
	v_max3_f32 v3, v3, |v30|, |v29|
	v_max3_f32 v3, v3, |v25|, |v5|
	v_mov_b32_e32 v26, v3
	v_mov_b32_e32 v27, v3
	s_nop 1
	v_permlane32_swap_b32_e32 v26, v27
	v_cndmask_b32_e64 v26, v26, v27, s[8:9]
	v_max_f32_e32 v26, v26, v26
	v_max_f32_e32 v3, v3, v26
	v_mov_b32_e32 v26, v3
	v_mov_b32_e32 v27, v3
	s_nop 1
	v_permlane16_swap_b32_e32 v26, v27
	v_cndmask_b32_e64 v26, v26, v27, s[6:7]
	v_max_f32_e32 v26, v26, v26
	v_max_f32_e32 v3, v3, v26
	v_rsq_f32_e32 v2, v2
	v_mov_b32_e32 v28, v170
	v_mov_b32_dpp v26, v3 row_ror:8 row_mask:0xf bank_mask:0xf bound_ctrl:1
	v_max_f32_e32 v26, v26, v26
	v_max_f32_e32 v3, v3, v26
	v_mul_f32_e32 v24, 0x45800000, v2
	v_cndmask_b32_e32 v24, v2, v24, vcc
	v_mov_b32_dpp v26, v3 row_half_mirror row_mask:0xf bank_mask:0xf bound_ctrl:1
	s_nop 1
	v_mov_b32_dpp v26, v26 quad_perm:[3,2,1,0] row_mask:0xf bank_mask:0xf bound_ctrl:1
	v_max_f32_e32 v26, v26, v26
	v_max_f32_e32 v3, v3, v26
	s_nop 1
	v_mov_b32_dpp v26, v3 quad_perm:[2,3,0,1] row_mask:0xf bank_mask:0xf bound_ctrl:1
	v_max_f32_e32 v26, v26, v26
	v_max_f32_e32 v26, v3, v26
	s_nop 1
	v_mov_b32_dpp v27, v26 quad_perm:[1,0,3,2] row_mask:0xf bank_mask:0xf bound_ctrl:1
	s_branch .LBB0_922

.LBB0_926:
	s_waitcnt lgkmcnt(0)
	v_and_b32_e32 v0, 63, v204
	v_lshlrev_b32_e32 v1, 12, v4
	v_lshl_add_u32 v1, v0, 5, v1
	v_add_u32_e32 v1, 0x13288000, v1
	global_load_dwordx4 v[64:67], v1, s[94:95]
	global_load_dwordx4 v[68:71], v1, s[94:95] offset:16
	global_load_dwordx4 v[72:75], v1, s[94:95] offset:2048
	global_load_dwordx4 v[76:79], v1, s[94:95] offset:2064
	ds_read_b32 v80, v170
	ds_read_b32 v81, v170 offset:256
	ds_read_b32 v82, v170 offset:512
	ds_read_b32 v83, v170 offset:768
	v_lshlrev_b32_e32 v28, 3, v0
	v_add_u32_e32 v29, 0x4008000, v28
	v_add_u32_e32 v28, 0x8000, v28
	s_waitcnt lgkmcnt(0)
	v_lshlrev_b32_e32 v2, 2, v80
	v_lshlrev_b32_e32 v3, 2, v81
	global_load_dword v84, v2, s[74:75]
	global_load_dword v85, v3, s[74:75]
	global_load_dword v86, v2, s[76:77]
	global_load_dword v87, v3, s[76:77]
	v_mov_b32_e32 v32, 0
	v_mov_b32_e32 v33, 0
	v_mov_b32_e32 v34, 0
	v_mov_b32_e32 v35, 0
	v_mov_b32_e32 v36, 0
	v_mov_b32_e32 v37, 0
	v_mov_b32_e32 v38, 0
	v_mov_b32_e32 v39, 0
	v_mov_b32_e32 v40, 0
	v_mov_b32_e32 v41, 0
	v_mov_b32_e32 v42, 0
	v_mov_b32_e32 v43, 0
	v_mov_b32_e32 v44, 0
	v_mov_b32_e32 v45, 0
	v_mov_b32_e32 v46, 0
	v_mov_b32_e32 v47, 0
	v_mov_b32_e32 v48, 0
	v_mov_b32_e32 v49, 0
	v_mov_b32_e32 v50, 0
	v_mov_b32_e32 v51, 0
	v_mov_b32_e32 v52, 0
	v_mov_b32_e32 v53, 0
	v_mov_b32_e32 v54, 0
	v_mov_b32_e32 v55, 0
	v_mov_b32_e32 v56, 0
	v_mov_b32_e32 v57, 0
	v_mov_b32_e32 v58, 0
	v_mov_b32_e32 v59, 0
	v_mov_b32_e32 v60, 0
	v_mov_b32_e32 v61, 0
	v_mov_b32_e32 v62, 0
	v_mov_b32_e32 v63, 0
	v_lshlrev_b32_e32 v2, 2, v0
	v_sub_u32_e32 v25, v170, v2
	v_add_u32_e32 v5, 0x1000, v170
	v_lshrrev_b32_e32 v2, 4, v0
	v_lshrrev_b32_e32 v3, 5, v0
	v_and_b32_e32 v2, 1, v2
	v_lshl_or_b32 v2, v2, 1, v3
	v_add_u32_e32 v3, 0x1000, v25
	v_lshl_add_u32 v26, v2, 2, v3
	v_add_u32_e32 v27, 16, v26
	s_waitcnt vmcnt(4)
	v_lshlrev_b32_e32 v128, 16, v64
	v_and_b32_e32 v129, 0xffff0000, v64
	v_lshlrev_b32_e32 v130, 16, v65
	v_and_b32_e32 v131, 0xffff0000, v65
	v_lshlrev_b32_e32 v132, 16, v66
	v_and_b32_e32 v133, 0xffff0000, v66
	v_lshlrev_b32_e32 v134, 16, v67
	v_and_b32_e32 v135, 0xffff0000, v67
	v_lshlrev_b32_e32 v136, 16, v68
	v_and_b32_e32 v137, 0xffff0000, v68
	v_lshlrev_b32_e32 v138, 16, v69
	v_and_b32_e32 v139, 0xffff0000, v69
	v_lshlrev_b32_e32 v140, 16, v70
	v_and_b32_e32 v141, 0xffff0000, v70
	v_lshlrev_b32_e32 v142, 16, v71
	v_and_b32_e32 v143, 0xffff0000, v71
	v_lshlrev_b32_e32 v144, 16, v72
	v_and_b32_e32 v145, 0xffff0000, v72
	v_lshlrev_b32_e32 v146, 16, v73
	v_and_b32_e32 v147, 0xffff0000, v73
	v_lshlrev_b32_e32 v148, 16, v74
	v_and_b32_e32 v149, 0xffff0000, v74
	v_lshlrev_b32_e32 v150, 16, v75
	v_and_b32_e32 v151, 0xffff0000, v75
	v_lshlrev_b32_e32 v152, 16, v76
	v_and_b32_e32 v153, 0xffff0000, v76
	v_lshlrev_b32_e32 v154, 16, v77
	v_and_b32_e32 v155, 0xffff0000, v77
	v_lshlrev_b32_e32 v156, 16, v78
	v_and_b32_e32 v157, 0xffff0000, v78
	v_lshlrev_b32_e32 v158, 16, v79
	v_and_b32_e32 v159, 0xffff0000, v79
	v_max3_f32 v6, |v128|, |v129|, |v130|
	v_max3_f32 v6, v6, |v131|, |v132|
	v_max3_f32 v6, v6, |v133|, |v134|
	v_max3_f32 v6, v6, |v135|, |v136|
	v_max3_f32 v6, v6, |v137|, |v138|
	v_max3_f32 v6, v6, |v139|, |v140|
	v_max3_f32 v6, v6, |v141|, |v142|
	v_max3_f32 v6, v6, |v143|, |v144|
	v_max3_f32 v6, v6, |v145|, |v146|
	v_max3_f32 v6, v6, |v147|, |v148|
	v_max3_f32 v6, v6, |v149|, |v150|
	v_max3_f32 v6, v6, |v151|, |v152|
	v_max3_f32 v6, v6, |v153|, |v154|
	v_max3_f32 v6, v6, |v155|, |v156|
	v_max3_f32 v6, v6, |v157|, |v158|
	v_max_f32_e64 v6, v6, |v159|
	v_mov_b32_e32 v2, v6
	v_mov_b32_e32 v3, v6
	s_nop 1
	v_permlane32_swap_b32_e32 v2, v3
	v_max_f32_e32 v6, v2, v3
	v_mov_b32_e32 v2, v6
	v_mov_b32_e32 v3, v6
	s_nop 1
	v_permlane16_swap_b32_e32 v2, v3
	v_max_f32_e32 v6, v2, v3
	s_nop 1
	v_max_f32_dpp v6, v6, v6 row_ror:8 row_mask:0xf bank_mask:0xf
	s_nop 1
	v_max_f32_dpp v6, v6, v6 row_ror:4 row_mask:0xf bank_mask:0xf
	s_nop 1
	v_max_f32_dpp v6, v6, v6 row_ror:2 row_mask:0xf bank_mask:0xf
	s_nop 1
	v_max_f32_dpp v6, v6, v6 row_ror:1 row_mask:0xf bank_mask:0xf
	v_mul_f32_e32 v7, 0x3e124925, v6
	v_cmp_lt_f32_e32 vcc, 0, v6
	s_nop 1
	v_cndmask_b32_e32 v7, 1.0, v7, vcc
	v_mul_f32_e32 v10, 0x3d924925, v7
	v_rcp_f32_e32 v11, v7
	v_rcp_f32_e32 v12, v10
	s_mov_b32 s33, 0xc0e00000
	v_mov_b32_e32 v13, 0x40e00000
	v_mul_f32_e32 v21, v128, v11
	v_rndne_f32_e32 v21, v21
	v_med3_f32 v21, v21, s33, v13
	v_fma_f32 v22, -v7, v21, v128
	v_mul_f32_e32 v22, v22, v12
	v_rndne_f32_e32 v22, v22
	v_med3_f32 v22, v22, s33, v13
	v_cvt_i32_f32_e32 v21, v21
	v_cvt_i32_f32_e32 v22, v22
	v_and_b32_e32 v208, 15, v21
	v_and_b32_e32 v212, 15, v22
	v_mul_f32_e32 v23, v129, v11
	v_rndne_f32_e32 v23, v23
	v_med3_f32 v23, v23, s33, v13
	v_fma_f32 v30, -v7, v23, v129
	v_mul_f32_e32 v30, v30, v12
	v_rndne_f32_e32 v30, v30
	v_med3_f32 v30, v30, s33, v13
	v_cvt_i32_f32_e32 v23, v23
	v_cvt_i32_f32_e32 v30, v30
	v_and_b32_e32 v23, 15, v23
	v_and_b32_e32 v30, 15, v30
	v_lshl_or_b32 v208, v23, 4, v208
	v_lshl_or_b32 v212, v30, 4, v212
	v_mul_f32_e32 v21, v130, v11
	v_rndne_f32_e32 v21, v21
	v_med3_f32 v21, v21, s33, v13
	v_fma_f32 v22, -v7, v21, v130
	v_mul_f32_e32 v22, v22, v12
	v_rndne_f32_e32 v22, v22
	v_med3_f32 v22, v22, s33, v13
	v_cvt_i32_f32_e32 v21, v21
	v_cvt_i32_f32_e32 v22, v22
	v_and_b32_e32 v21, 15, v21
	v_and_b32_e32 v22, 15, v22
	v_lshl_or_b32 v208, v21, 8, v208
	v_lshl_or_b32 v212, v22, 8, v212
	v_mul_f32_e32 v23, v131, v11
	v_rndne_f32_e32 v23, v23
	v_med3_f32 v23, v23, s33, v13
	v_fma_f32 v30, -v7, v23, v131
	v_mul_f32_e32 v30, v30, v12
	v_rndne_f32_e32 v30, v30
	v_med3_f32 v30, v30, s33, v13
	v_cvt_i32_f32_e32 v23, v23
	v_cvt_i32_f32_e32 v30, v30
	v_and_b32_e32 v23, 15, v23
	v_and_b32_e32 v30, 15, v30
	v_lshl_or_b32 v208, v23, 12, v208
	v_lshl_or_b32 v212, v30, 12, v212
	v_mul_f32_e32 v21, v132, v11
	v_rndne_f32_e32 v21, v21
	v_med3_f32 v21, v21, s33, v13
	v_fma_f32 v22, -v7, v21, v132
	v_mul_f32_e32 v22, v22, v12
	v_rndne_f32_e32 v22, v22
	v_med3_f32 v22, v22, s33, v13
	v_cvt_i32_f32_e32 v21, v21
	v_cvt_i32_f32_e32 v22, v22
	v_and_b32_e32 v21, 15, v21
	v_and_b32_e32 v22, 15, v22
	v_lshl_or_b32 v208, v21, 16, v208
	v_lshl_or_b32 v212, v22, 16, v212
	v_mul_f32_e32 v23, v133, v11
	v_rndne_f32_e32 v23, v23
	v_med3_f32 v23, v23, s33, v13
	v_fma_f32 v30, -v7, v23, v133
	v_mul_f32_e32 v30, v30, v12
	v_rndne_f32_e32 v30, v30
	v_med3_f32 v30, v30, s33, v13
	v_cvt_i32_f32_e32 v23, v23
	v_cvt_i32_f32_e32 v30, v30
	v_and_b32_e32 v23, 15, v23
	v_and_b32_e32 v30, 15, v30
	v_lshl_or_b32 v208, v23, 20, v208
	v_lshl_or_b32 v212, v30, 20, v212
	v_mul_f32_e32 v21, v134, v11
	v_rndne_f32_e32 v21, v21
	v_med3_f32 v21, v21, s33, v13
	v_fma_f32 v22, -v7, v21, v134
	v_mul_f32_e32 v22, v22, v12
	v_rndne_f32_e32 v22, v22
	v_med3_f32 v22, v22, s33, v13
	v_cvt_i32_f32_e32 v21, v21
	v_cvt_i32_f32_e32 v22, v22
	v_and_b32_e32 v21, 15, v21
	v_and_b32_e32 v22, 15, v22
	v_lshl_or_b32 v208, v21, 24, v208
	v_lshl_or_b32 v212, v22, 24, v212
	v_mul_f32_e32 v23, v135, v11
	v_rndne_f32_e32 v23, v23
	v_med3_f32 v23, v23, s33, v13
	v_fma_f32 v30, -v7, v23, v135
	v_mul_f32_e32 v30, v30, v12
	v_rndne_f32_e32 v30, v30
	v_med3_f32 v30, v30, s33, v13
	v_cvt_i32_f32_e32 v23, v23
	v_cvt_i32_f32_e32 v30, v30
	v_lshl_or_b32 v208, v23, 28, v208
	v_lshl_or_b32 v212, v30, 28, v212
	v_mul_f32_e32 v21, v136, v11
	v_rndne_f32_e32 v21, v21
	v_med3_f32 v21, v21, s33, v13
	v_fma_f32 v22, -v7, v21, v136
	v_mul_f32_e32 v22, v22, v12
	v_rndne_f32_e32 v22, v22
	v_med3_f32 v22, v22, s33, v13
	v_cvt_i32_f32_e32 v21, v21
	v_cvt_i32_f32_e32 v22, v22
	v_and_b32_e32 v209, 15, v21
	v_and_b32_e32 v213, 15, v22
	v_mul_f32_e32 v23, v137, v11
	v_rndne_f32_e32 v23, v23
	v_med3_f32 v23, v23, s33, v13
	v_fma_f32 v30, -v7, v23, v137
	v_mul_f32_e32 v30, v30, v12
	v_rndne_f32_e32 v30, v30
	v_med3_f32 v30, v30, s33, v13
	v_cvt_i32_f32_e32 v23, v23
	v_cvt_i32_f32_e32 v30, v30
	v_and_b32_e32 v23, 15, v23
	v_and_b32_e32 v30, 15, v30
	v_lshl_or_b32 v209, v23, 4, v209
	v_lshl_or_b32 v213, v30, 4, v213
	v_mul_f32_e32 v21, v138, v11
	v_rndne_f32_e32 v21, v21
	v_med3_f32 v21, v21, s33, v13
	v_fma_f32 v22, -v7, v21, v138
	v_mul_f32_e32 v22, v22, v12
	v_rndne_f32_e32 v22, v22
	v_med3_f32 v22, v22, s33, v13
	v_cvt_i32_f32_e32 v21, v21
	v_cvt_i32_f32_e32 v22, v22
	v_and_b32_e32 v21, 15, v21
	v_and_b32_e32 v22, 15, v22
	v_lshl_or_b32 v209, v21, 8, v209
	v_lshl_or_b32 v213, v22, 8, v213
	v_mul_f32_e32 v23, v139, v11
	v_rndne_f32_e32 v23, v23
	v_med3_f32 v23, v23, s33, v13
	v_fma_f32 v30, -v7, v23, v139
	v_mul_f32_e32 v30, v30, v12
	v_rndne_f32_e32 v30, v30
	v_med3_f32 v30, v30, s33, v13
	v_cvt_i32_f32_e32 v23, v23
	v_cvt_i32_f32_e32 v30, v30
	v_and_b32_e32 v23, 15, v23
	v_and_b32_e32 v30, 15, v30
	v_lshl_or_b32 v209, v23, 12, v209
	v_lshl_or_b32 v213, v30, 12, v213
	v_mul_f32_e32 v21, v140, v11
	v_rndne_f32_e32 v21, v21
	v_med3_f32 v21, v21, s33, v13
	v_fma_f32 v22, -v7, v21, v140
	v_mul_f32_e32 v22, v22, v12
	v_rndne_f32_e32 v22, v22
	v_med3_f32 v22, v22, s33, v13
	v_cvt_i32_f32_e32 v21, v21
	v_cvt_i32_f32_e32 v22, v22
	v_and_b32_e32 v21, 15, v21
	v_and_b32_e32 v22, 15, v22
	v_lshl_or_b32 v209, v21, 16, v209
	v_lshl_or_b32 v213, v22, 16, v213
	v_mul_f32_e32 v23, v141, v11
	v_rndne_f32_e32 v23, v23
	v_med3_f32 v23, v23, s33, v13
	v_fma_f32 v30, -v7, v23, v141
	v_mul_f32_e32 v30, v30, v12
	v_rndne_f32_e32 v30, v30
	v_med3_f32 v30, v30, s33, v13
	v_cvt_i32_f32_e32 v23, v23
	v_cvt_i32_f32_e32 v30, v30
	v_and_b32_e32 v23, 15, v23
	v_and_b32_e32 v30, 15, v30
	v_lshl_or_b32 v209, v23, 20, v209
	v_lshl_or_b32 v213, v30, 20, v213
	v_mul_f32_e32 v21, v142, v11
	v_rndne_f32_e32 v21, v21
	v_med3_f32 v21, v21, s33, v13
	v_fma_f32 v22, -v7, v21, v142
	v_mul_f32_e32 v22, v22, v12
	v_rndne_f32_e32 v22, v22
	v_med3_f32 v22, v22, s33, v13
	v_cvt_i32_f32_e32 v21, v21
	v_cvt_i32_f32_e32 v22, v22
	v_and_b32_e32 v21, 15, v21
	v_and_b32_e32 v22, 15, v22
	v_lshl_or_b32 v209, v21, 24, v209
	v_lshl_or_b32 v213, v22, 24, v213
	v_mul_f32_e32 v23, v143, v11
	v_rndne_f32_e32 v23, v23
	v_med3_f32 v23, v23, s33, v13
	v_fma_f32 v30, -v7, v23, v143
	v_mul_f32_e32 v30, v30, v12
	v_rndne_f32_e32 v30, v30
	v_med3_f32 v30, v30, s33, v13
	v_cvt_i32_f32_e32 v23, v23
	v_cvt_i32_f32_e32 v30, v30
	v_lshl_or_b32 v209, v23, 28, v209
	v_lshl_or_b32 v213, v30, 28, v213
	v_mul_f32_e32 v21, v144, v11
	v_rndne_f32_e32 v21, v21
	v_med3_f32 v21, v21, s33, v13
	v_fma_f32 v22, -v7, v21, v144
	v_mul_f32_e32 v22, v22, v12
	v_rndne_f32_e32 v22, v22
	v_med3_f32 v22, v22, s33, v13
	v_cvt_i32_f32_e32 v21, v21
	v_cvt_i32_f32_e32 v22, v22
	v_and_b32_e32 v210, 15, v21
	v_and_b32_e32 v214, 15, v22
	v_mul_f32_e32 v23, v145, v11
	v_rndne_f32_e32 v23, v23
	v_med3_f32 v23, v23, s33, v13
	v_fma_f32 v30, -v7, v23, v145
	v_mul_f32_e32 v30, v30, v12
	v_rndne_f32_e32 v30, v30
	v_med3_f32 v30, v30, s33, v13
	v_cvt_i32_f32_e32 v23, v23
	v_cvt_i32_f32_e32 v30, v30
	v_and_b32_e32 v23, 15, v23
	v_and_b32_e32 v30, 15, v30
	v_lshl_or_b32 v210, v23, 4, v210
	v_lshl_or_b32 v214, v30, 4, v214
	v_mul_f32_e32 v21, v146, v11
	v_rndne_f32_e32 v21, v21
	v_med3_f32 v21, v21, s33, v13
	v_fma_f32 v22, -v7, v21, v146
	v_mul_f32_e32 v22, v22, v12
	v_rndne_f32_e32 v22, v22
	v_med3_f32 v22, v22, s33, v13
	v_cvt_i32_f32_e32 v21, v21
	v_cvt_i32_f32_e32 v22, v22
	v_and_b32_e32 v21, 15, v21
	v_and_b32_e32 v22, 15, v22
	v_lshl_or_b32 v210, v21, 8, v210
	v_lshl_or_b32 v214, v22, 8, v214
	v_mul_f32_e32 v23, v147, v11
	v_rndne_f32_e32 v23, v23
	v_med3_f32 v23, v23, s33, v13
	v_fma_f32 v30, -v7, v23, v147
	v_mul_f32_e32 v30, v30, v12
	v_rndne_f32_e32 v30, v30
	v_med3_f32 v30, v30, s33, v13
	v_cvt_i32_f32_e32 v23, v23
	v_cvt_i32_f32_e32 v30, v30
	v_and_b32_e32 v23, 15, v23
	v_and_b32_e32 v30, 15, v30
	v_lshl_or_b32 v210, v23, 12, v210
	v_lshl_or_b32 v214, v30, 12, v214
	v_mul_f32_e32 v21, v148, v11
	v_rndne_f32_e32 v21, v21
	v_med3_f32 v21, v21, s33, v13
	v_fma_f32 v22, -v7, v21, v148
	v_mul_f32_e32 v22, v22, v12
	v_rndne_f32_e32 v22, v22
	v_med3_f32 v22, v22, s33, v13
	v_cvt_i32_f32_e32 v21, v21
	v_cvt_i32_f32_e32 v22, v22
	v_and_b32_e32 v21, 15, v21
	v_and_b32_e32 v22, 15, v22
	v_lshl_or_b32 v210, v21, 16, v210
	v_lshl_or_b32 v214, v22, 16, v214
	v_mul_f32_e32 v23, v149, v11
	v_rndne_f32_e32 v23, v23
	v_med3_f32 v23, v23, s33, v13
	v_fma_f32 v30, -v7, v23, v149
	v_mul_f32_e32 v30, v30, v12
	v_rndne_f32_e32 v30, v30
	v_med3_f32 v30, v30, s33, v13
	v_cvt_i32_f32_e32 v23, v23
	v_cvt_i32_f32_e32 v30, v30
	v_and_b32_e32 v23, 15, v23
	v_and_b32_e32 v30, 15, v30
	v_lshl_or_b32 v210, v23, 20, v210
	v_lshl_or_b32 v214, v30, 20, v214
	v_mul_f32_e32 v21, v150, v11
	v_rndne_f32_e32 v21, v21
	v_med3_f32 v21, v21, s33, v13
	v_fma_f32 v22, -v7, v21, v150
	v_mul_f32_e32 v22, v22, v12
	v_rndne_f32_e32 v22, v22
	v_med3_f32 v22, v22, s33, v13
	v_cvt_i32_f32_e32 v21, v21
	v_cvt_i32_f32_e32 v22, v22
	v_and_b32_e32 v21, 15, v21
	v_and_b32_e32 v22, 15, v22
	v_lshl_or_b32 v210, v21, 24, v210
	v_lshl_or_b32 v214, v22, 24, v214
	v_mul_f32_e32 v23, v151, v11
	v_rndne_f32_e32 v23, v23
	v_med3_f32 v23, v23, s33, v13
	v_fma_f32 v30, -v7, v23, v151
	v_mul_f32_e32 v30, v30, v12
	v_rndne_f32_e32 v30, v30
	v_med3_f32 v30, v30, s33, v13
	v_cvt_i32_f32_e32 v23, v23
	v_cvt_i32_f32_e32 v30, v30
	v_lshl_or_b32 v210, v23, 28, v210
	v_lshl_or_b32 v214, v30, 28, v214
	v_mul_f32_e32 v21, v152, v11
	v_rndne_f32_e32 v21, v21
	v_med3_f32 v21, v21, s33, v13
	v_fma_f32 v22, -v7, v21, v152
	v_mul_f32_e32 v22, v22, v12
	v_rndne_f32_e32 v22, v22
	v_med3_f32 v22, v22, s33, v13
	v_cvt_i32_f32_e32 v21, v21
	v_cvt_i32_f32_e32 v22, v22
	v_and_b32_e32 v211, 15, v21
	v_and_b32_e32 v215, 15, v22
	v_mul_f32_e32 v23, v153, v11
	v_rndne_f32_e32 v23, v23
	v_med3_f32 v23, v23, s33, v13
	v_fma_f32 v30, -v7, v23, v153
	v_mul_f32_e32 v30, v30, v12
	v_rndne_f32_e32 v30, v30
	v_med3_f32 v30, v30, s33, v13
	v_cvt_i32_f32_e32 v23, v23
	v_cvt_i32_f32_e32 v30, v30
	v_and_b32_e32 v23, 15, v23
	v_and_b32_e32 v30, 15, v30
	v_lshl_or_b32 v211, v23, 4, v211
	v_lshl_or_b32 v215, v30, 4, v215
	v_mul_f32_e32 v21, v154, v11
	v_rndne_f32_e32 v21, v21
	v_med3_f32 v21, v21, s33, v13
	v_fma_f32 v22, -v7, v21, v154
	v_mul_f32_e32 v22, v22, v12
	v_rndne_f32_e32 v22, v22
	v_med3_f32 v22, v22, s33, v13
	v_cvt_i32_f32_e32 v21, v21
	v_cvt_i32_f32_e32 v22, v22
	v_and_b32_e32 v21, 15, v21
	v_and_b32_e32 v22, 15, v22
	v_lshl_or_b32 v211, v21, 8, v211
	v_lshl_or_b32 v215, v22, 8, v215
	v_mul_f32_e32 v23, v155, v11
	v_rndne_f32_e32 v23, v23
	v_med3_f32 v23, v23, s33, v13
	v_fma_f32 v30, -v7, v23, v155
	v_mul_f32_e32 v30, v30, v12
	v_rndne_f32_e32 v30, v30
	v_med3_f32 v30, v30, s33, v13
	v_cvt_i32_f32_e32 v23, v23
	v_cvt_i32_f32_e32 v30, v30
	v_and_b32_e32 v23, 15, v23
	v_and_b32_e32 v30, 15, v30
	v_lshl_or_b32 v211, v23, 12, v211
	v_lshl_or_b32 v215, v30, 12, v215
	v_mul_f32_e32 v21, v156, v11
	v_rndne_f32_e32 v21, v21
	v_med3_f32 v21, v21, s33, v13
	v_fma_f32 v22, -v7, v21, v156
	v_mul_f32_e32 v22, v22, v12
	v_rndne_f32_e32 v22, v22
	v_med3_f32 v22, v22, s33, v13
	v_cvt_i32_f32_e32 v21, v21
	v_cvt_i32_f32_e32 v22, v22
	v_and_b32_e32 v21, 15, v21
	v_and_b32_e32 v22, 15, v22
	v_lshl_or_b32 v211, v21, 16, v211
	v_lshl_or_b32 v215, v22, 16, v215
	v_mul_f32_e32 v23, v157, v11
	v_rndne_f32_e32 v23, v23
	v_med3_f32 v23, v23, s33, v13
	v_fma_f32 v30, -v7, v23, v157
	v_mul_f32_e32 v30, v30, v12
	v_rndne_f32_e32 v30, v30
	v_med3_f32 v30, v30, s33, v13
	v_cvt_i32_f32_e32 v23, v23
	v_cvt_i32_f32_e32 v30, v30
	v_and_b32_e32 v23, 15, v23
	v_and_b32_e32 v30, 15, v30
	v_lshl_or_b32 v211, v23, 20, v211
	v_lshl_or_b32 v215, v30, 20, v215
	v_mul_f32_e32 v21, v158, v11
	v_rndne_f32_e32 v21, v21
	v_med3_f32 v21, v21, s33, v13
	v_fma_f32 v22, -v7, v21, v158
	v_mul_f32_e32 v22, v22, v12
	v_rndne_f32_e32 v22, v22
	v_med3_f32 v22, v22, s33, v13
	v_cvt_i32_f32_e32 v21, v21
	v_cvt_i32_f32_e32 v22, v22
	v_and_b32_e32 v21, 15, v21
	v_and_b32_e32 v22, 15, v22
	v_lshl_or_b32 v211, v21, 24, v211
	v_lshl_or_b32 v215, v22, 24, v215
	v_mul_f32_e32 v23, v159, v11
	v_rndne_f32_e32 v23, v23
	v_med3_f32 v23, v23, s33, v13
	v_fma_f32 v30, -v7, v23, v159
	v_mul_f32_e32 v30, v30, v12
	v_rndne_f32_e32 v30, v30
	v_med3_f32 v30, v30, s33, v13
	v_cvt_i32_f32_e32 v23, v23
	v_cvt_i32_f32_e32 v30, v30
	v_lshl_or_b32 v211, v23, 28, v211
	v_lshl_or_b32 v215, v30, 28, v215
	s_waitcnt vmcnt(0)
	v_mul_f32_e32 v2, v24, v10
	v_mul_f32_e32 v84, v84, v2
	v_mul_f32_e32 v85, v85, v2
	v_mul_f32_e32 v86, v86, v82
	v_mul_f32_e32 v87, v87, v83
	ds_write_b32 v5, v84
	ds_write_b32 v5, v85 offset:256
	ds_write_b32 v5, v86 offset:512
	ds_write_b32 v5, v87 offset:768
	ds_read_b128 v[10:13], v25
	ds_read_b128 v[18:21], v25 offset:16
	v_add_u32_e32 v25, 32, v25
	s_waitcnt lgkmcnt(0)
	v_readfirstlane_b32 s33, v10
	s_lshl_b32 s33, s33, 10
	s_add_u32 s72, s94, s33
	s_addc_u32 s73, s95, 0
	global_load_dwordx2 v[64:65], v28, s[72:73]
	global_load_dwordx2 v[66:67], v28, s[72:73] offset:512
	global_load_dwordx2 v[96:97], v29, s[72:73]
	global_load_dwordx2 v[98:99], v29, s[72:73] offset:512
	v_readfirstlane_b32 s33, v11
	s_lshl_b32 s33, s33, 10
	s_add_u32 s72, s94, s33
	s_addc_u32 s73, s95, 0
	global_load_dwordx2 v[68:69], v28, s[72:73]
	global_load_dwordx2 v[70:71], v28, s[72:73] offset:512
	global_load_dwordx2 v[100:101], v29, s[72:73]
	global_load_dwordx2 v[102:103], v29, s[72:73] offset:512
	v_readfirstlane_b32 s33, v12
	s_lshl_b32 s33, s33, 10
	s_add_u32 s72, s94, s33
	s_addc_u32 s73, s95, 0
	global_load_dwordx2 v[72:73], v28, s[72:73]
	global_load_dwordx2 v[74:75], v28, s[72:73] offset:512
	global_load_dwordx2 v[104:105], v29, s[72:73]
	global_load_dwordx2 v[106:107], v29, s[72:73] offset:512
	v_readfirstlane_b32 s33, v13
	s_lshl_b32 s33, s33, 10
	s_add_u32 s72, s94, s33
	s_addc_u32 s73, s95, 0
	global_load_dwordx2 v[76:77], v28, s[72:73]
	global_load_dwordx2 v[78:79], v28, s[72:73] offset:512
	global_load_dwordx2 v[108:109], v29, s[72:73]
	global_load_dwordx2 v[110:111], v29, s[72:73] offset:512
	v_readfirstlane_b32 s33, v18
	s_lshl_b32 s33, s33, 10
	s_add_u32 s72, s94, s33
	s_addc_u32 s73, s95, 0
	global_load_dwordx2 v[80:81], v28, s[72:73]
	global_load_dwordx2 v[82:83], v28, s[72:73] offset:512
	global_load_dwordx2 v[112:113], v29, s[72:73]
	global_load_dwordx2 v[114:115], v29, s[72:73] offset:512
	v_readfirstlane_b32 s33, v19
	s_lshl_b32 s33, s33, 10
	s_add_u32 s72, s94, s33
	s_addc_u32 s73, s95, 0
	global_load_dwordx2 v[84:85], v28, s[72:73]
	global_load_dwordx2 v[86:87], v28, s[72:73] offset:512
	global_load_dwordx2 v[116:117], v29, s[72:73]
	global_load_dwordx2 v[118:119], v29, s[72:73] offset:512
	v_readfirstlane_b32 s33, v20
	s_lshl_b32 s33, s33, 10
	s_add_u32 s72, s94, s33
	s_addc_u32 s73, s95, 0
	global_load_dwordx2 v[88:89], v28, s[72:73]
	global_load_dwordx2 v[90:91], v28, s[72:73] offset:512
	global_load_dwordx2 v[120:121], v29, s[72:73]
	global_load_dwordx2 v[122:123], v29, s[72:73] offset:512
	v_readfirstlane_b32 s33, v21
	s_lshl_b32 s33, s33, 10
	s_add_u32 s72, s94, s33
	s_addc_u32 s73, s95, 0
	global_load_dwordx2 v[92:93], v28, s[72:73]
	global_load_dwordx2 v[94:95], v28, s[72:73] offset:512
	global_load_dwordx2 v[124:125], v29, s[72:73]
	global_load_dwordx2 v[126:127], v29, s[72:73] offset:512
	s_mov_b32 s86, 7
.Lp8_eloop:
	ds_read_b128 v[10:13], v25
	ds_read_b128 v[18:21], v25 offset:16
	v_add_u32_e32 v25, 32, v25
	ds_read_b32 v232, v26
	ds_read_b32 v233, v27
	ds_read_b32 v234, v26 offset:512
	ds_read_b32 v235, v27 offset:512
	v_add_u32_e32 v26, 32, v26
	v_add_u32_e32 v27, 32, v27
	s_waitcnt vmcnt(30)
	v_mov_b32_e32 v216, 0
	v_mov_b32_e32 v224, 0
	v_dot8c_i32_i4_e32 v216, v64, v208
	v_dot8c_i32_i4_e32 v224, v64, v212
	v_dot8c_i32_i4_e32 v216, v65, v209
	v_dot8c_i32_i4_e32 v224, v65, v213
	v_dot8c_i32_i4_e32 v216, v66, v210
	v_dot8c_i32_i4_e32 v224, v66, v214
	v_dot8c_i32_i4_e32 v216, v67, v211
	v_dot8c_i32_i4_e32 v224, v67, v215
	s_waitcnt vmcnt(26)
	v_mov_b32_e32 v217, 0
	v_mov_b32_e32 v225, 0
	v_dot8c_i32_i4_e32 v217, v68, v208
	v_dot8c_i32_i4_e32 v225, v68, v212
	v_dot8c_i32_i4_e32 v217, v69, v209
	v_dot8c_i32_i4_e32 v225, v69, v213
	v_dot8c_i32_i4_e32 v217, v70, v210
	v_dot8c_i32_i4_e32 v225, v70, v214
	v_dot8c_i32_i4_e32 v217, v71, v211
	v_dot8c_i32_i4_e32 v225, v71, v215
	s_waitcnt vmcnt(22)
	v_mov_b32_e32 v218, 0
	v_mov_b32_e32 v226, 0
	v_dot8c_i32_i4_e32 v218, v72, v208
	v_dot8c_i32_i4_e32 v226, v72, v212
	v_dot8c_i32_i4_e32 v218, v73, v209
	v_dot8c_i32_i4_e32 v226, v73, v213
	v_dot8c_i32_i4_e32 v218, v74, v210
	v_dot8c_i32_i4_e32 v226, v74, v214
	v_dot8c_i32_i4_e32 v218, v75, v211
	v_dot8c_i32_i4_e32 v226, v75, v215
	s_waitcnt vmcnt(18)
	v_mov_b32_e32 v219, 0
	v_mov_b32_e32 v227, 0
	v_dot8c_i32_i4_e32 v219, v76, v208
	v_dot8c_i32_i4_e32 v227, v76, v212
	v_dot8c_i32_i4_e32 v219, v77, v209
	v_dot8c_i32_i4_e32 v227, v77, v213
	v_dot8c_i32_i4_e32 v219, v78, v210
	v_dot8c_i32_i4_e32 v227, v78, v214
	v_dot8c_i32_i4_e32 v219, v79, v211
	v_dot8c_i32_i4_e32 v227, v79, v215
	s_waitcnt vmcnt(14)
	v_mov_b32_e32 v220, 0
	v_mov_b32_e32 v228, 0
	v_dot8c_i32_i4_e32 v220, v80, v208
	v_dot8c_i32_i4_e32 v228, v80, v212
	v_dot8c_i32_i4_e32 v220, v81, v209
	v_dot8c_i32_i4_e32 v228, v81, v213
	v_dot8c_i32_i4_e32 v220, v82, v210
	v_dot8c_i32_i4_e32 v228, v82, v214
	v_dot8c_i32_i4_e32 v220, v83, v211
	v_dot8c_i32_i4_e32 v228, v83, v215
	s_waitcnt vmcnt(10)
	v_mov_b32_e32 v221, 0
	v_mov_b32_e32 v229, 0
	v_dot8c_i32_i4_e32 v221, v84, v208
	v_dot8c_i32_i4_e32 v229, v84, v212
	v_dot8c_i32_i4_e32 v221, v85, v209
	v_dot8c_i32_i4_e32 v229, v85, v213
	v_dot8c_i32_i4_e32 v221, v86, v210
	v_dot8c_i32_i4_e32 v229, v86, v214
	v_dot8c_i32_i4_e32 v221, v87, v211
	v_dot8c_i32_i4_e32 v229, v87, v215
	s_waitcnt vmcnt(6)
	v_mov_b32_e32 v222, 0
	v_mov_b32_e32 v230, 0
	v_dot8c_i32_i4_e32 v222, v88, v208
	v_dot8c_i32_i4_e32 v230, v88, v212
	v_dot8c_i32_i4_e32 v222, v89, v209
	v_dot8c_i32_i4_e32 v230, v89, v213
	v_dot8c_i32_i4_e32 v222, v90, v210
	v_dot8c_i32_i4_e32 v230, v90, v214
	v_dot8c_i32_i4_e32 v222, v91, v211
	v_dot8c_i32_i4_e32 v230, v91, v215
	s_waitcnt vmcnt(2)
	v_mov_b32_e32 v223, 0
	v_mov_b32_e32 v231, 0
	v_dot8c_i32_i4_e32 v223, v92, v208
	v_dot8c_i32_i4_e32 v231, v92, v212
	v_dot8c_i32_i4_e32 v223, v93, v209
	v_dot8c_i32_i4_e32 v231, v93, v213
	v_dot8c_i32_i4_e32 v223, v94, v210
	v_dot8c_i32_i4_e32 v231, v94, v214
	v_dot8c_i32_i4_e32 v223, v95, v211
	v_dot8c_i32_i4_e32 v231, v95, v215
	s_nop 2
	v_mad_i32_i24 v216, v216, 14, v224
	v_mad_i32_i24 v217, v217, 14, v225
	v_mad_i32_i24 v218, v218, 14, v226
	v_mad_i32_i24 v219, v219, 14, v227
	v_mad_i32_i24 v220, v220, 14, v228
	v_mad_i32_i24 v221, v221, 14, v229
	v_mad_i32_i24 v222, v222, 14, v230
	v_mad_i32_i24 v223, v223, 14, v231
	s_waitcnt lgkmcnt(4)
	v_readfirstlane_b32 s33, v10
	s_lshl_b32 s33, s33, 10
	s_add_u32 s72, s94, s33
	s_addc_u32 s73, s95, 0
	global_load_dwordx2 v[128:129], v28, s[72:73]
	global_load_dwordx2 v[130:131], v28, s[72:73] offset:512
	global_load_dwordx2 v[176:177], v29, s[72:73]
	global_load_dwordx2 v[178:179], v29, s[72:73] offset:512
	v_readfirstlane_b32 s33, v11
	s_lshl_b32 s33, s33, 10
	s_add_u32 s72, s94, s33
	s_addc_u32 s73, s95, 0
	global_load_dwordx2 v[132:133], v28, s[72:73]
	global_load_dwordx2 v[134:135], v28, s[72:73] offset:512
	global_load_dwordx2 v[180:181], v29, s[72:73]
	global_load_dwordx2 v[182:183], v29, s[72:73] offset:512
	v_readfirstlane_b32 s33, v12
	s_lshl_b32 s33, s33, 10
	s_add_u32 s72, s94, s33
	s_addc_u32 s73, s95, 0
	global_load_dwordx2 v[136:137], v28, s[72:73]
	global_load_dwordx2 v[138:139], v28, s[72:73] offset:512
	global_load_dwordx2 v[184:185], v29, s[72:73]
	global_load_dwordx2 v[186:187], v29, s[72:73] offset:512
	v_readfirstlane_b32 s33, v13
	s_lshl_b32 s33, s33, 10
	s_add_u32 s72, s94, s33
	s_addc_u32 s73, s95, 0
	global_load_dwordx2 v[140:141], v28, s[72:73]
	global_load_dwordx2 v[142:143], v28, s[72:73] offset:512
	global_load_dwordx2 v[188:189], v29, s[72:73]
	global_load_dwordx2 v[190:191], v29, s[72:73] offset:512
	v_readfirstlane_b32 s33, v18
	s_lshl_b32 s33, s33, 10
	s_add_u32 s72, s94, s33
	s_addc_u32 s73, s95, 0
	global_load_dwordx2 v[144:145], v28, s[72:73]
	global_load_dwordx2 v[146:147], v28, s[72:73] offset:512
	global_load_dwordx2 v[192:193], v29, s[72:73]
	global_load_dwordx2 v[194:195], v29, s[72:73] offset:512
	v_readfirstlane_b32 s33, v19
	s_lshl_b32 s33, s33, 10
	s_add_u32 s72, s94, s33
	s_addc_u32 s73, s95, 0
	global_load_dwordx2 v[148:149], v28, s[72:73]
	global_load_dwordx2 v[150:151], v28, s[72:73] offset:512
	global_load_dwordx2 v[196:197], v29, s[72:73]
	global_load_dwordx2 v[198:199], v29, s[72:73] offset:512
	v_readfirstlane_b32 s33, v20
	s_lshl_b32 s33, s33, 10
	s_add_u32 s72, s94, s33
	s_addc_u32 s73, s95, 0
	global_load_dwordx2 v[152:153], v28, s[72:73]
	global_load_dwordx2 v[154:155], v28, s[72:73] offset:512
	global_load_dwordx2 v[200:201], v29, s[72:73]
	global_load_dwordx2 v[202:203], v29, s[72:73] offset:512
	v_readfirstlane_b32 s33, v21
	s_lshl_b32 s33, s33, 10
	s_add_u32 s72, s94, s33
	s_addc_u32 s73, s95, 0
	global_load_dwordx2 v[156:157], v28, s[72:73]
	global_load_dwordx2 v[158:159], v28, s[72:73] offset:512
	global_load_dwordx2 v[240:241], v29, s[72:73]
	global_load_dwordx2 v[242:243], v29, s[72:73] offset:512
	s_nop 1
	v_permlane32_swap_b32_e32 v216, v217
	v_permlane32_swap_b32_e32 v218, v219
	v_permlane32_swap_b32_e32 v220, v221
	v_permlane32_swap_b32_e32 v222, v223
	v_add_u32_e32 v216, v216, v217
	v_add_u32_e32 v218, v218, v219
	v_add_u32_e32 v220, v220, v221
	v_add_u32_e32 v222, v222, v223
	s_nop 1
	v_permlane16_swap_b32_e32 v216, v218
	v_permlane16_swap_b32_e32 v220, v222
	v_add_u32_e32 v216, v216, v218
	v_add_u32_e32 v220, v220, v222
	s_nop 1
	v_add_u32_dpp v216, v216, v216 row_ror:8 row_mask:0xf bank_mask:0xf
	v_add_u32_dpp v220, v220, v220 row_ror:8 row_mask:0xf bank_mask:0xf
	s_nop 1
	v_add_u32_dpp v216, v216, v216 row_ror:4 row_mask:0xf bank_mask:0xf
	v_add_u32_dpp v220, v220, v220 row_ror:4 row_mask:0xf bank_mask:0xf
	s_nop 1
	v_add_u32_dpp v216, v216, v216 row_ror:2 row_mask:0xf bank_mask:0xf
	v_add_u32_dpp v220, v220, v220 row_ror:2 row_mask:0xf bank_mask:0xf
	s_nop 1
	v_add_u32_dpp v216, v216, v216 row_ror:1 row_mask:0xf bank_mask:0xf
	v_add_u32_dpp v220, v220, v220 row_ror:1 row_mask:0xf bank_mask:0xf
	s_waitcnt lgkmcnt(0)
	v_cvt_f32_i32_e32 v216, v216
	v_cvt_f32_i32_e32 v220, v220
	v_mul_f32_e32 v216, v216, v232
	v_mul_f32_e32 v220, v220, v233
	v_fma_f32 v2, |v216|, s83, 1.0
	v_fma_f32 v7, |v220|, s83, 1.0
	v_rcp_f32_e32 v2, v2
	v_rcp_f32_e32 v7, v7
	v_mul_f32_e32 v5, v216, v216
	v_mul_f32_e32 v11, v220, v220
	v_mul_f32_e32 v5, 0xbf38aa3b, v5
	v_mul_f32_e32 v11, 0xbf38aa3b, v11
	v_exp_f32_e32 v5, v5
	v_exp_f32_e32 v11, v11
	v_fmamk_f32 v3, v2, 0x3f07dc22, v172
	v_fmamk_f32 v10, v7, 0x3f07dc22, v172
	v_fmaak_f32 v3, v2, v3, 0x3f35f0e3
	v_fmaak_f32 v10, v7, v10, 0x3f35f0e3
	v_fmaak_f32 v3, v2, v3, 0xbe11a98e
	v_fmaak_f32 v10, v7, v10, 0xbe11a98e
	v_fmaak_f32 v3, v2, v3, 0x3e027906
	v_fmaak_f32 v10, v7, v10, 0x3e027906
	v_mul_f32_e32 v3, v2, v3
	v_mul_f32_e32 v10, v7, v10
	v_mul_f32_e32 v3, v5, v3
	v_mul_f32_e32 v10, v11, v10
	v_mul_f32_e32 v6, v216, v3
	v_mul_f32_e32 v12, v220, v10
	v_fma_f32 v3, -v216, v3, v216
	v_fma_f32 v10, -v220, v10, v220
	v_cmp_gt_f32_e32 vcc, 0, v216
	v_cmp_gt_f32_e64 s[96:97], 0, v220
	s_nop 1
	v_cndmask_b32_e32 v216, v3, v6, vcc
	v_cndmask_b32_e64 v220, v10, v12, s[96:97]
	v_mul_f32_e32 v216, v216, v234
	v_mul_f32_e32 v220, v220, v235
	s_nop 0
	v_readlane_b32 s64, v216, 0
	v_readlane_b32 s65, v216, 32
	v_readlane_b32 s66, v216, 16
	v_readlane_b32 s67, v216, 48
	v_readlane_b32 s68, v220, 0
	v_readlane_b32 s69, v220, 32
	v_readlane_b32 s70, v220, 16
	v_readlane_b32 s71, v220, 48
	s_waitcnt vmcnt(60)
	v_cvt_scalef32_pk_f32_fp4 v[160:161], v96, 1.0
	v_cvt_scalef32_pk_f32_fp4 v[162:163], v96, 1.0 op_sel:[1,0,0]
	v_cvt_scalef32_pk_f32_fp4 v[18:19], v96, 1.0 op_sel:[0,1,0]
	v_pk_fma_f32 v[32:33], v[160:161], s[64:65], v[32:33] op_sel_hi:[1,0,1]
	v_cvt_scalef32_pk_f32_fp4 v[20:21], v96, 1.0 op_sel:[1,1,0]
	v_pk_fma_f32 v[34:35], v[162:163], s[64:65], v[34:35] op_sel_hi:[1,0,1]
	v_cvt_scalef32_pk_f32_fp4 v[22:23], v97, 1.0
	v_pk_fma_f32 v[36:37], v[18:19], s[64:65], v[36:37] op_sel_hi:[1,0,1]
	v_cvt_scalef32_pk_f32_fp4 v[30:31], v97, 1.0 op_sel:[1,0,0]
	v_pk_fma_f32 v[38:39], v[20:21], s[64:65], v[38:39] op_sel_hi:[1,0,1]
	v_cvt_scalef32_pk_f32_fp4 v[2:3], v97, 1.0 op_sel:[0,1,0]
	v_pk_fma_f32 v[40:41], v[22:23], s[64:65], v[40:41] op_sel_hi:[1,0,1]
	v_cvt_scalef32_pk_f32_fp4 v[6:7], v97, 1.0 op_sel:[1,1,0]
	v_pk_fma_f32 v[42:43], v[30:31], s[64:65], v[42:43] op_sel_hi:[1,0,1]
	v_cvt_scalef32_pk_f32_fp4 v[160:161], v98, 1.0
	v_pk_fma_f32 v[44:45], v[2:3], s[64:65], v[44:45] op_sel_hi:[1,0,1]
	v_cvt_scalef32_pk_f32_fp4 v[162:163], v98, 1.0 op_sel:[1,0,0]
	v_pk_fma_f32 v[46:47], v[6:7], s[64:65], v[46:47] op_sel_hi:[1,0,1]
	v_cvt_scalef32_pk_f32_fp4 v[18:19], v98, 1.0 op_sel:[0,1,0]
	v_pk_fma_f32 v[48:49], v[160:161], s[64:65], v[48:49] op_sel_hi:[1,0,1]
	v_cvt_scalef32_pk_f32_fp4 v[20:21], v98, 1.0 op_sel:[1,1,0]
	v_pk_fma_f32 v[50:51], v[162:163], s[64:65], v[50:51] op_sel_hi:[1,0,1]
	v_cvt_scalef32_pk_f32_fp4 v[22:23], v99, 1.0
	v_pk_fma_f32 v[52:53], v[18:19], s[64:65], v[52:53] op_sel_hi:[1,0,1]
	v_cvt_scalef32_pk_f32_fp4 v[30:31], v99, 1.0 op_sel:[1,0,0]
	v_pk_fma_f32 v[54:55], v[20:21], s[64:65], v[54:55] op_sel_hi:[1,0,1]
	v_cvt_scalef32_pk_f32_fp4 v[2:3], v99, 1.0 op_sel:[0,1,0]
	v_pk_fma_f32 v[56:57], v[22:23], s[64:65], v[56:57] op_sel_hi:[1,0,1]
	v_cvt_scalef32_pk_f32_fp4 v[6:7], v99, 1.0 op_sel:[1,1,0]
	v_pk_fma_f32 v[58:59], v[30:31], s[64:65], v[58:59] op_sel_hi:[1,0,1]
	v_pk_fma_f32 v[60:61], v[2:3], s[64:65], v[60:61] op_sel_hi:[1,0,1]
	v_pk_fma_f32 v[62:63], v[6:7], s[64:65], v[62:63] op_sel_hi:[1,0,1]
	s_waitcnt vmcnt(56)
	v_cvt_scalef32_pk_f32_fp4 v[160:161], v100, 1.0
	v_cvt_scalef32_pk_f32_fp4 v[162:163], v100, 1.0 op_sel:[1,0,0]
	v_cvt_scalef32_pk_f32_fp4 v[18:19], v100, 1.0 op_sel:[0,1,0]
	v_pk_fma_f32 v[32:33], v[160:161], s[64:65], v[32:33] op_sel:[0,1,0] op_sel_hi:[1,1,1]
	v_cvt_scalef32_pk_f32_fp4 v[20:21], v100, 1.0 op_sel:[1,1,0]
	v_pk_fma_f32 v[34:35], v[162:163], s[64:65], v[34:35] op_sel:[0,1,0] op_sel_hi:[1,1,1]
	v_cvt_scalef32_pk_f32_fp4 v[22:23], v101, 1.0
	v_pk_fma_f32 v[36:37], v[18:19], s[64:65], v[36:37] op_sel:[0,1,0] op_sel_hi:[1,1,1]
	v_cvt_scalef32_pk_f32_fp4 v[30:31], v101, 1.0 op_sel:[1,0,0]
	v_pk_fma_f32 v[38:39], v[20:21], s[64:65], v[38:39] op_sel:[0,1,0] op_sel_hi:[1,1,1]
	v_cvt_scalef32_pk_f32_fp4 v[2:3], v101, 1.0 op_sel:[0,1,0]
	v_pk_fma_f32 v[40:41], v[22:23], s[64:65], v[40:41] op_sel:[0,1,0] op_sel_hi:[1,1,1]
	v_cvt_scalef32_pk_f32_fp4 v[6:7], v101, 1.0 op_sel:[1,1,0]
	v_pk_fma_f32 v[42:43], v[30:31], s[64:65], v[42:43] op_sel:[0,1,0] op_sel_hi:[1,1,1]
	v_cvt_scalef32_pk_f32_fp4 v[160:161], v102, 1.0
	v_pk_fma_f32 v[44:45], v[2:3], s[64:65], v[44:45] op_sel:[0,1,0] op_sel_hi:[1,1,1]
	v_cvt_scalef32_pk_f32_fp4 v[162:163], v102, 1.0 op_sel:[1,0,0]
	v_pk_fma_f32 v[46:47], v[6:7], s[64:65], v[46:47] op_sel:[0,1,0] op_sel_hi:[1,1,1]
	v_cvt_scalef32_pk_f32_fp4 v[18:19], v102, 1.0 op_sel:[0,1,0]
	v_pk_fma_f32 v[48:49], v[160:161], s[64:65], v[48:49] op_sel:[0,1,0] op_sel_hi:[1,1,1]
	v_cvt_scalef32_pk_f32_fp4 v[20:21], v102, 1.0 op_sel:[1,1,0]
	v_pk_fma_f32 v[50:51], v[162:163], s[64:65], v[50:51] op_sel:[0,1,0] op_sel_hi:[1,1,1]
	v_cvt_scalef32_pk_f32_fp4 v[22:23], v103, 1.0
	v_pk_fma_f32 v[52:53], v[18:19], s[64:65], v[52:53] op_sel:[0,1,0] op_sel_hi:[1,1,1]
	v_cvt_scalef32_pk_f32_fp4 v[30:31], v103, 1.0 op_sel:[1,0,0]
	v_pk_fma_f32 v[54:55], v[20:21], s[64:65], v[54:55] op_sel:[0,1,0] op_sel_hi:[1,1,1]
	v_cvt_scalef32_pk_f32_fp4 v[2:3], v103, 1.0 op_sel:[0,1,0]
	v_pk_fma_f32 v[56:57], v[22:23], s[64:65], v[56:57] op_sel:[0,1,0] op_sel_hi:[1,1,1]
	v_cvt_scalef32_pk_f32_fp4 v[6:7], v103, 1.0 op_sel:[1,1,0]
	v_pk_fma_f32 v[58:59], v[30:31], s[64:65], v[58:59] op_sel:[0,1,0] op_sel_hi:[1,1,1]
	v_pk_fma_f32 v[60:61], v[2:3], s[64:65], v[60:61] op_sel:[0,1,0] op_sel_hi:[1,1,1]
	v_pk_fma_f32 v[62:63], v[6:7], s[64:65], v[62:63] op_sel:[0,1,0] op_sel_hi:[1,1,1]
	s_waitcnt vmcnt(52)
	v_cvt_scalef32_pk_f32_fp4 v[160:161], v104, 1.0
	v_cvt_scalef32_pk_f32_fp4 v[162:163], v104, 1.0 op_sel:[1,0,0]
	v_cvt_scalef32_pk_f32_fp4 v[18:19], v104, 1.0 op_sel:[0,1,0]
	v_pk_fma_f32 v[32:33], v[160:161], s[66:67], v[32:33] op_sel_hi:[1,0,1]
	v_cvt_scalef32_pk_f32_fp4 v[20:21], v104, 1.0 op_sel:[1,1,0]
	v_pk_fma_f32 v[34:35], v[162:163], s[66:67], v[34:35] op_sel_hi:[1,0,1]
	v_cvt_scalef32_pk_f32_fp4 v[22:23], v105, 1.0
	v_pk_fma_f32 v[36:37], v[18:19], s[66:67], v[36:37] op_sel_hi:[1,0,1]
	v_cvt_scalef32_pk_f32_fp4 v[30:31], v105, 1.0 op_sel:[1,0,0]
	v_pk_fma_f32 v[38:39], v[20:21], s[66:67], v[38:39] op_sel_hi:[1,0,1]
	v_cvt_scalef32_pk_f32_fp4 v[2:3], v105, 1.0 op_sel:[0,1,0]
	v_pk_fma_f32 v[40:41], v[22:23], s[66:67], v[40:41] op_sel_hi:[1,0,1]
	v_cvt_scalef32_pk_f32_fp4 v[6:7], v105, 1.0 op_sel:[1,1,0]
	v_pk_fma_f32 v[42:43], v[30:31], s[66:67], v[42:43] op_sel_hi:[1,0,1]
	v_cvt_scalef32_pk_f32_fp4 v[160:161], v106, 1.0
	v_pk_fma_f32 v[44:45], v[2:3], s[66:67], v[44:45] op_sel_hi:[1,0,1]
	v_cvt_scalef32_pk_f32_fp4 v[162:163], v106, 1.0 op_sel:[1,0,0]
	v_pk_fma_f32 v[46:47], v[6:7], s[66:67], v[46:47] op_sel_hi:[1,0,1]
	v_cvt_scalef32_pk_f32_fp4 v[18:19], v106, 1.0 op_sel:[0,1,0]
	v_pk_fma_f32 v[48:49], v[160:161], s[66:67], v[48:49] op_sel_hi:[1,0,1]
	v_cvt_scalef32_pk_f32_fp4 v[20:21], v106, 1.0 op_sel:[1,1,0]
	v_pk_fma_f32 v[50:51], v[162:163], s[66:67], v[50:51] op_sel_hi:[1,0,1]
	v_cvt_scalef32_pk_f32_fp4 v[22:23], v107, 1.0
	v_pk_fma_f32 v[52:53], v[18:19], s[66:67], v[52:53] op_sel_hi:[1,0,1]
	v_cvt_scalef32_pk_f32_fp4 v[30:31], v107, 1.0 op_sel:[1,0,0]
	v_pk_fma_f32 v[54:55], v[20:21], s[66:67], v[54:55] op_sel_hi:[1,0,1]
	v_cvt_scalef32_pk_f32_fp4 v[2:3], v107, 1.0 op_sel:[0,1,0]
	v_pk_fma_f32 v[56:57], v[22:23], s[66:67], v[56:57] op_sel_hi:[1,0,1]
	v_cvt_scalef32_pk_f32_fp4 v[6:7], v107, 1.0 op_sel:[1,1,0]
	v_pk_fma_f32 v[58:59], v[30:31], s[66:67], v[58:59] op_sel_hi:[1,0,1]
	v_pk_fma_f32 v[60:61], v[2:3], s[66:67], v[60:61] op_sel_hi:[1,0,1]
	v_pk_fma_f32 v[62:63], v[6:7], s[66:67], v[62:63] op_sel_hi:[1,0,1]
	s_waitcnt vmcnt(48)
	v_cvt_scalef32_pk_f32_fp4 v[160:161], v108, 1.0
	v_cvt_scalef32_pk_f32_fp4 v[162:163], v108, 1.0 op_sel:[1,0,0]
	v_cvt_scalef32_pk_f32_fp4 v[18:19], v108, 1.0 op_sel:[0,1,0]
	v_pk_fma_f32 v[32:33], v[160:161], s[66:67], v[32:33] op_sel:[0,1,0] op_sel_hi:[1,1,1]
	v_cvt_scalef32_pk_f32_fp4 v[20:21], v108, 1.0 op_sel:[1,1,0]
	v_pk_fma_f32 v[34:35], v[162:163], s[66:67], v[34:35] op_sel:[0,1,0] op_sel_hi:[1,1,1]
	v_cvt_scalef32_pk_f32_fp4 v[22:23], v109, 1.0
	v_pk_fma_f32 v[36:37], v[18:19], s[66:67], v[36:37] op_sel:[0,1,0] op_sel_hi:[1,1,1]
	v_cvt_scalef32_pk_f32_fp4 v[30:31], v109, 1.0 op_sel:[1,0,0]
	v_pk_fma_f32 v[38:39], v[20:21], s[66:67], v[38:39] op_sel:[0,1,0] op_sel_hi:[1,1,1]
	v_cvt_scalef32_pk_f32_fp4 v[2:3], v109, 1.0 op_sel:[0,1,0]
	v_pk_fma_f32 v[40:41], v[22:23], s[66:67], v[40:41] op_sel:[0,1,0] op_sel_hi:[1,1,1]
	v_cvt_scalef32_pk_f32_fp4 v[6:7], v109, 1.0 op_sel:[1,1,0]
	v_pk_fma_f32 v[42:43], v[30:31], s[66:67], v[42:43] op_sel:[0,1,0] op_sel_hi:[1,1,1]
	v_cvt_scalef32_pk_f32_fp4 v[160:161], v110, 1.0
	v_pk_fma_f32 v[44:45], v[2:3], s[66:67], v[44:45] op_sel:[0,1,0] op_sel_hi:[1,1,1]
	v_cvt_scalef32_pk_f32_fp4 v[162:163], v110, 1.0 op_sel:[1,0,0]
	v_pk_fma_f32 v[46:47], v[6:7], s[66:67], v[46:47] op_sel:[0,1,0] op_sel_hi:[1,1,1]
	v_cvt_scalef32_pk_f32_fp4 v[18:19], v110, 1.0 op_sel:[0,1,0]
	v_pk_fma_f32 v[48:49], v[160:161], s[66:67], v[48:49] op_sel:[0,1,0] op_sel_hi:[1,1,1]
	v_cvt_scalef32_pk_f32_fp4 v[20:21], v110, 1.0 op_sel:[1,1,0]
	v_pk_fma_f32 v[50:51], v[162:163], s[66:67], v[50:51] op_sel:[0,1,0] op_sel_hi:[1,1,1]
	v_cvt_scalef32_pk_f32_fp4 v[22:23], v111, 1.0
	v_pk_fma_f32 v[52:53], v[18:19], s[66:67], v[52:53] op_sel:[0,1,0] op_sel_hi:[1,1,1]
	v_cvt_scalef32_pk_f32_fp4 v[30:31], v111, 1.0 op_sel:[1,0,0]
	v_pk_fma_f32 v[54:55], v[20:21], s[66:67], v[54:55] op_sel:[0,1,0] op_sel_hi:[1,1,1]
	v_cvt_scalef32_pk_f32_fp4 v[2:3], v111, 1.0 op_sel:[0,1,0]
	v_pk_fma_f32 v[56:57], v[22:23], s[66:67], v[56:57] op_sel:[0,1,0] op_sel_hi:[1,1,1]
	v_cvt_scalef32_pk_f32_fp4 v[6:7], v111, 1.0 op_sel:[1,1,0]
	v_pk_fma_f32 v[58:59], v[30:31], s[66:67], v[58:59] op_sel:[0,1,0] op_sel_hi:[1,1,1]
	v_pk_fma_f32 v[60:61], v[2:3], s[66:67], v[60:61] op_sel:[0,1,0] op_sel_hi:[1,1,1]
	v_pk_fma_f32 v[62:63], v[6:7], s[66:67], v[62:63] op_sel:[0,1,0] op_sel_hi:[1,1,1]
	s_waitcnt vmcnt(44)
	v_cvt_scalef32_pk_f32_fp4 v[160:161], v112, 1.0
	v_cvt_scalef32_pk_f32_fp4 v[162:163], v112, 1.0 op_sel:[1,0,0]
	v_cvt_scalef32_pk_f32_fp4 v[18:19], v112, 1.0 op_sel:[0,1,0]
	v_pk_fma_f32 v[32:33], v[160:161], s[68:69], v[32:33] op_sel_hi:[1,0,1]
	v_cvt_scalef32_pk_f32_fp4 v[20:21], v112, 1.0 op_sel:[1,1,0]
	v_pk_fma_f32 v[34:35], v[162:163], s[68:69], v[34:35] op_sel_hi:[1,0,1]
	v_cvt_scalef32_pk_f32_fp4 v[22:23], v113, 1.0
	v_pk_fma_f32 v[36:37], v[18:19], s[68:69], v[36:37] op_sel_hi:[1,0,1]
	v_cvt_scalef32_pk_f32_fp4 v[30:31], v113, 1.0 op_sel:[1,0,0]
	v_pk_fma_f32 v[38:39], v[20:21], s[68:69], v[38:39] op_sel_hi:[1,0,1]
	v_cvt_scalef32_pk_f32_fp4 v[2:3], v113, 1.0 op_sel:[0,1,0]
	v_pk_fma_f32 v[40:41], v[22:23], s[68:69], v[40:41] op_sel_hi:[1,0,1]
	v_cvt_scalef32_pk_f32_fp4 v[6:7], v113, 1.0 op_sel:[1,1,0]
	v_pk_fma_f32 v[42:43], v[30:31], s[68:69], v[42:43] op_sel_hi:[1,0,1]
	v_cvt_scalef32_pk_f32_fp4 v[160:161], v114, 1.0
	v_pk_fma_f32 v[44:45], v[2:3], s[68:69], v[44:45] op_sel_hi:[1,0,1]
	v_cvt_scalef32_pk_f32_fp4 v[162:163], v114, 1.0 op_sel:[1,0,0]
	v_pk_fma_f32 v[46:47], v[6:7], s[68:69], v[46:47] op_sel_hi:[1,0,1]
	v_cvt_scalef32_pk_f32_fp4 v[18:19], v114, 1.0 op_sel:[0,1,0]
	v_pk_fma_f32 v[48:49], v[160:161], s[68:69], v[48:49] op_sel_hi:[1,0,1]
	v_cvt_scalef32_pk_f32_fp4 v[20:21], v114, 1.0 op_sel:[1,1,0]
	v_pk_fma_f32 v[50:51], v[162:163], s[68:69], v[50:51] op_sel_hi:[1,0,1]
	v_cvt_scalef32_pk_f32_fp4 v[22:23], v115, 1.0
	v_pk_fma_f32 v[52:53], v[18:19], s[68:69], v[52:53] op_sel_hi:[1,0,1]
	v_cvt_scalef32_pk_f32_fp4 v[30:31], v115, 1.0 op_sel:[1,0,0]
	v_pk_fma_f32 v[54:55], v[20:21], s[68:69], v[54:55] op_sel_hi:[1,0,1]
	v_cvt_scalef32_pk_f32_fp4 v[2:3], v115, 1.0 op_sel:[0,1,0]
	v_pk_fma_f32 v[56:57], v[22:23], s[68:69], v[56:57] op_sel_hi:[1,0,1]
	v_cvt_scalef32_pk_f32_fp4 v[6:7], v115, 1.0 op_sel:[1,1,0]
	v_pk_fma_f32 v[58:59], v[30:31], s[68:69], v[58:59] op_sel_hi:[1,0,1]
	v_pk_fma_f32 v[60:61], v[2:3], s[68:69], v[60:61] op_sel_hi:[1,0,1]
	v_pk_fma_f32 v[62:63], v[6:7], s[68:69], v[62:63] op_sel_hi:[1,0,1]
	s_waitcnt vmcnt(40)
	v_cvt_scalef32_pk_f32_fp4 v[160:161], v116, 1.0
	v_cvt_scalef32_pk_f32_fp4 v[162:163], v116, 1.0 op_sel:[1,0,0]
	v_cvt_scalef32_pk_f32_fp4 v[18:19], v116, 1.0 op_sel:[0,1,0]
	v_pk_fma_f32 v[32:33], v[160:161], s[68:69], v[32:33] op_sel:[0,1,0] op_sel_hi:[1,1,1]
	v_cvt_scalef32_pk_f32_fp4 v[20:21], v116, 1.0 op_sel:[1,1,0]
	v_pk_fma_f32 v[34:35], v[162:163], s[68:69], v[34:35] op_sel:[0,1,0] op_sel_hi:[1,1,1]
	v_cvt_scalef32_pk_f32_fp4 v[22:23], v117, 1.0
	v_pk_fma_f32 v[36:37], v[18:19], s[68:69], v[36:37] op_sel:[0,1,0] op_sel_hi:[1,1,1]
	v_cvt_scalef32_pk_f32_fp4 v[30:31], v117, 1.0 op_sel:[1,0,0]
	v_pk_fma_f32 v[38:39], v[20:21], s[68:69], v[38:39] op_sel:[0,1,0] op_sel_hi:[1,1,1]
	v_cvt_scalef32_pk_f32_fp4 v[2:3], v117, 1.0 op_sel:[0,1,0]
	v_pk_fma_f32 v[40:41], v[22:23], s[68:69], v[40:41] op_sel:[0,1,0] op_sel_hi:[1,1,1]
	v_cvt_scalef32_pk_f32_fp4 v[6:7], v117, 1.0 op_sel:[1,1,0]
	v_pk_fma_f32 v[42:43], v[30:31], s[68:69], v[42:43] op_sel:[0,1,0] op_sel_hi:[1,1,1]
	v_cvt_scalef32_pk_f32_fp4 v[160:161], v118, 1.0
	v_pk_fma_f32 v[44:45], v[2:3], s[68:69], v[44:45] op_sel:[0,1,0] op_sel_hi:[1,1,1]
	v_cvt_scalef32_pk_f32_fp4 v[162:163], v118, 1.0 op_sel:[1,0,0]
	v_pk_fma_f32 v[46:47], v[6:7], s[68:69], v[46:47] op_sel:[0,1,0] op_sel_hi:[1,1,1]
	v_cvt_scalef32_pk_f32_fp4 v[18:19], v118, 1.0 op_sel:[0,1,0]
	v_pk_fma_f32 v[48:49], v[160:161], s[68:69], v[48:49] op_sel:[0,1,0] op_sel_hi:[1,1,1]
	v_cvt_scalef32_pk_f32_fp4 v[20:21], v118, 1.0 op_sel:[1,1,0]
	v_pk_fma_f32 v[50:51], v[162:163], s[68:69], v[50:51] op_sel:[0,1,0] op_sel_hi:[1,1,1]
	v_cvt_scalef32_pk_f32_fp4 v[22:23], v119, 1.0
	v_pk_fma_f32 v[52:53], v[18:19], s[68:69], v[52:53] op_sel:[0,1,0] op_sel_hi:[1,1,1]
	v_cvt_scalef32_pk_f32_fp4 v[30:31], v119, 1.0 op_sel:[1,0,0]
	v_pk_fma_f32 v[54:55], v[20:21], s[68:69], v[54:55] op_sel:[0,1,0] op_sel_hi:[1,1,1]
	v_cvt_scalef32_pk_f32_fp4 v[2:3], v119, 1.0 op_sel:[0,1,0]
	v_pk_fma_f32 v[56:57], v[22:23], s[68:69], v[56:57] op_sel:[0,1,0] op_sel_hi:[1,1,1]
	v_cvt_scalef32_pk_f32_fp4 v[6:7], v119, 1.0 op_sel:[1,1,0]
	v_pk_fma_f32 v[58:59], v[30:31], s[68:69], v[58:59] op_sel:[0,1,0] op_sel_hi:[1,1,1]
	v_pk_fma_f32 v[60:61], v[2:3], s[68:69], v[60:61] op_sel:[0,1,0] op_sel_hi:[1,1,1]
	v_pk_fma_f32 v[62:63], v[6:7], s[68:69], v[62:63] op_sel:[0,1,0] op_sel_hi:[1,1,1]
	s_waitcnt vmcnt(36)
	v_cvt_scalef32_pk_f32_fp4 v[160:161], v120, 1.0
	v_cvt_scalef32_pk_f32_fp4 v[162:163], v120, 1.0 op_sel:[1,0,0]
	v_cvt_scalef32_pk_f32_fp4 v[18:19], v120, 1.0 op_sel:[0,1,0]
	v_pk_fma_f32 v[32:33], v[160:161], s[70:71], v[32:33] op_sel_hi:[1,0,1]
	v_cvt_scalef32_pk_f32_fp4 v[20:21], v120, 1.0 op_sel:[1,1,0]
	v_pk_fma_f32 v[34:35], v[162:163], s[70:71], v[34:35] op_sel_hi:[1,0,1]
	v_cvt_scalef32_pk_f32_fp4 v[22:23], v121, 1.0
	v_pk_fma_f32 v[36:37], v[18:19], s[70:71], v[36:37] op_sel_hi:[1,0,1]
	v_cvt_scalef32_pk_f32_fp4 v[30:31], v121, 1.0 op_sel:[1,0,0]
	v_pk_fma_f32 v[38:39], v[20:21], s[70:71], v[38:39] op_sel_hi:[1,0,1]
	v_cvt_scalef32_pk_f32_fp4 v[2:3], v121, 1.0 op_sel:[0,1,0]
	v_pk_fma_f32 v[40:41], v[22:23], s[70:71], v[40:41] op_sel_hi:[1,0,1]
	v_cvt_scalef32_pk_f32_fp4 v[6:7], v121, 1.0 op_sel:[1,1,0]
	v_pk_fma_f32 v[42:43], v[30:31], s[70:71], v[42:43] op_sel_hi:[1,0,1]
	v_cvt_scalef32_pk_f32_fp4 v[160:161], v122, 1.0
	v_pk_fma_f32 v[44:45], v[2:3], s[70:71], v[44:45] op_sel_hi:[1,0,1]
	v_cvt_scalef32_pk_f32_fp4 v[162:163], v122, 1.0 op_sel:[1,0,0]
	v_pk_fma_f32 v[46:47], v[6:7], s[70:71], v[46:47] op_sel_hi:[1,0,1]
	v_cvt_scalef32_pk_f32_fp4 v[18:19], v122, 1.0 op_sel:[0,1,0]
	v_pk_fma_f32 v[48:49], v[160:161], s[70:71], v[48:49] op_sel_hi:[1,0,1]
	v_cvt_scalef32_pk_f32_fp4 v[20:21], v122, 1.0 op_sel:[1,1,0]
	v_pk_fma_f32 v[50:51], v[162:163], s[70:71], v[50:51] op_sel_hi:[1,0,1]
	v_cvt_scalef32_pk_f32_fp4 v[22:23], v123, 1.0
	v_pk_fma_f32 v[52:53], v[18:19], s[70:71], v[52:53] op_sel_hi:[1,0,1]
	v_cvt_scalef32_pk_f32_fp4 v[30:31], v123, 1.0 op_sel:[1,0,0]
	v_pk_fma_f32 v[54:55], v[20:21], s[70:71], v[54:55] op_sel_hi:[1,0,1]
	v_cvt_scalef32_pk_f32_fp4 v[2:3], v123, 1.0 op_sel:[0,1,0]
	v_pk_fma_f32 v[56:57], v[22:23], s[70:71], v[56:57] op_sel_hi:[1,0,1]
	v_cvt_scalef32_pk_f32_fp4 v[6:7], v123, 1.0 op_sel:[1,1,0]
	v_pk_fma_f32 v[58:59], v[30:31], s[70:71], v[58:59] op_sel_hi:[1,0,1]
	v_pk_fma_f32 v[60:61], v[2:3], s[70:71], v[60:61] op_sel_hi:[1,0,1]
	v_pk_fma_f32 v[62:63], v[6:7], s[70:71], v[62:63] op_sel_hi:[1,0,1]
	s_waitcnt vmcnt(32)
	v_cvt_scalef32_pk_f32_fp4 v[160:161], v124, 1.0
	v_cvt_scalef32_pk_f32_fp4 v[162:163], v124, 1.0 op_sel:[1,0,0]
	v_cvt_scalef32_pk_f32_fp4 v[18:19], v124, 1.0 op_sel:[0,1,0]
	v_pk_fma_f32 v[32:33], v[160:161], s[70:71], v[32:33] op_sel:[0,1,0] op_sel_hi:[1,1,1]
	v_cvt_scalef32_pk_f32_fp4 v[20:21], v124, 1.0 op_sel:[1,1,0]
	v_pk_fma_f32 v[34:35], v[162:163], s[70:71], v[34:35] op_sel:[0,1,0] op_sel_hi:[1,1,1]
	v_cvt_scalef32_pk_f32_fp4 v[22:23], v125, 1.0
	v_pk_fma_f32 v[36:37], v[18:19], s[70:71], v[36:37] op_sel:[0,1,0] op_sel_hi:[1,1,1]
	v_cvt_scalef32_pk_f32_fp4 v[30:31], v125, 1.0 op_sel:[1,0,0]
	v_pk_fma_f32 v[38:39], v[20:21], s[70:71], v[38:39] op_sel:[0,1,0] op_sel_hi:[1,1,1]
	v_cvt_scalef32_pk_f32_fp4 v[2:3], v125, 1.0 op_sel:[0,1,0]
	v_pk_fma_f32 v[40:41], v[22:23], s[70:71], v[40:41] op_sel:[0,1,0] op_sel_hi:[1,1,1]
	v_cvt_scalef32_pk_f32_fp4 v[6:7], v125, 1.0 op_sel:[1,1,0]
	v_pk_fma_f32 v[42:43], v[30:31], s[70:71], v[42:43] op_sel:[0,1,0] op_sel_hi:[1,1,1]
	v_cvt_scalef32_pk_f32_fp4 v[160:161], v126, 1.0
	v_pk_fma_f32 v[44:45], v[2:3], s[70:71], v[44:45] op_sel:[0,1,0] op_sel_hi:[1,1,1]
	v_cvt_scalef32_pk_f32_fp4 v[162:163], v126, 1.0 op_sel:[1,0,0]
	v_pk_fma_f32 v[46:47], v[6:7], s[70:71], v[46:47] op_sel:[0,1,0] op_sel_hi:[1,1,1]
	v_cvt_scalef32_pk_f32_fp4 v[18:19], v126, 1.0 op_sel:[0,1,0]
	v_pk_fma_f32 v[48:49], v[160:161], s[70:71], v[48:49] op_sel:[0,1,0] op_sel_hi:[1,1,1]
	v_cvt_scalef32_pk_f32_fp4 v[20:21], v126, 1.0 op_sel:[1,1,0]
	v_pk_fma_f32 v[50:51], v[162:163], s[70:71], v[50:51] op_sel:[0,1,0] op_sel_hi:[1,1,1]
	v_cvt_scalef32_pk_f32_fp4 v[22:23], v127, 1.0
	v_pk_fma_f32 v[52:53], v[18:19], s[70:71], v[52:53] op_sel:[0,1,0] op_sel_hi:[1,1,1]
	v_cvt_scalef32_pk_f32_fp4 v[30:31], v127, 1.0 op_sel:[1,0,0]
	v_pk_fma_f32 v[54:55], v[20:21], s[70:71], v[54:55] op_sel:[0,1,0] op_sel_hi:[1,1,1]
	v_cvt_scalef32_pk_f32_fp4 v[2:3], v127, 1.0 op_sel:[0,1,0]
	v_pk_fma_f32 v[56:57], v[22:23], s[70:71], v[56:57] op_sel:[0,1,0] op_sel_hi:[1,1,1]
	v_cvt_scalef32_pk_f32_fp4 v[6:7], v127, 1.0 op_sel:[1,1,0]
	v_pk_fma_f32 v[58:59], v[30:31], s[70:71], v[58:59] op_sel:[0,1,0] op_sel_hi:[1,1,1]
	v_pk_fma_f32 v[60:61], v[2:3], s[70:71], v[60:61] op_sel:[0,1,0] op_sel_hi:[1,1,1]
	v_pk_fma_f32 v[62:63], v[6:7], s[70:71], v[62:63] op_sel:[0,1,0] op_sel_hi:[1,1,1]
	ds_read_b128 v[10:13], v25
	ds_read_b128 v[18:21], v25 offset:16
	v_add_u32_e32 v25, 32, v25
	ds_read_b32 v232, v26
	ds_read_b32 v233, v27
	ds_read_b32 v234, v26 offset:512
	ds_read_b32 v235, v27 offset:512
	v_add_u32_e32 v26, 32, v26
	v_add_u32_e32 v27, 32, v27
	s_waitcnt vmcnt(30)
	v_mov_b32_e32 v216, 0
	v_mov_b32_e32 v224, 0
	v_dot8c_i32_i4_e32 v216, v128, v208
	v_dot8c_i32_i4_e32 v224, v128, v212
	v_dot8c_i32_i4_e32 v216, v129, v209
	v_dot8c_i32_i4_e32 v224, v129, v213
	v_dot8c_i32_i4_e32 v216, v130, v210
	v_dot8c_i32_i4_e32 v224, v130, v214
	v_dot8c_i32_i4_e32 v216, v131, v211
	v_dot8c_i32_i4_e32 v224, v131, v215
	s_waitcnt vmcnt(26)
	v_mov_b32_e32 v217, 0
	v_mov_b32_e32 v225, 0
	v_dot8c_i32_i4_e32 v217, v132, v208
	v_dot8c_i32_i4_e32 v225, v132, v212
	v_dot8c_i32_i4_e32 v217, v133, v209
	v_dot8c_i32_i4_e32 v225, v133, v213
	v_dot8c_i32_i4_e32 v217, v134, v210
	v_dot8c_i32_i4_e32 v225, v134, v214
	v_dot8c_i32_i4_e32 v217, v135, v211
	v_dot8c_i32_i4_e32 v225, v135, v215
	s_waitcnt vmcnt(22)
	v_mov_b32_e32 v218, 0
	v_mov_b32_e32 v226, 0
	v_dot8c_i32_i4_e32 v218, v136, v208
	v_dot8c_i32_i4_e32 v226, v136, v212
	v_dot8c_i32_i4_e32 v218, v137, v209
	v_dot8c_i32_i4_e32 v226, v137, v213
	v_dot8c_i32_i4_e32 v218, v138, v210
	v_dot8c_i32_i4_e32 v226, v138, v214
	v_dot8c_i32_i4_e32 v218, v139, v211
	v_dot8c_i32_i4_e32 v226, v139, v215
	s_waitcnt vmcnt(18)
	v_mov_b32_e32 v219, 0
	v_mov_b32_e32 v227, 0
	v_dot8c_i32_i4_e32 v219, v140, v208
	v_dot8c_i32_i4_e32 v227, v140, v212
	v_dot8c_i32_i4_e32 v219, v141, v209
	v_dot8c_i32_i4_e32 v227, v141, v213
	v_dot8c_i32_i4_e32 v219, v142, v210
	v_dot8c_i32_i4_e32 v227, v142, v214
	v_dot8c_i32_i4_e32 v219, v143, v211
	v_dot8c_i32_i4_e32 v227, v143, v215
	s_waitcnt vmcnt(14)
	v_mov_b32_e32 v220, 0
	v_mov_b32_e32 v228, 0
	v_dot8c_i32_i4_e32 v220, v144, v208
	v_dot8c_i32_i4_e32 v228, v144, v212
	v_dot8c_i32_i4_e32 v220, v145, v209
	v_dot8c_i32_i4_e32 v228, v145, v213
	v_dot8c_i32_i4_e32 v220, v146, v210
	v_dot8c_i32_i4_e32 v228, v146, v214
	v_dot8c_i32_i4_e32 v220, v147, v211
	v_dot8c_i32_i4_e32 v228, v147, v215
	s_waitcnt vmcnt(10)
	v_mov_b32_e32 v221, 0
	v_mov_b32_e32 v229, 0
	v_dot8c_i32_i4_e32 v221, v148, v208
	v_dot8c_i32_i4_e32 v229, v148, v212
	v_dot8c_i32_i4_e32 v221, v149, v209
	v_dot8c_i32_i4_e32 v229, v149, v213
	v_dot8c_i32_i4_e32 v221, v150, v210
	v_dot8c_i32_i4_e32 v229, v150, v214
	v_dot8c_i32_i4_e32 v221, v151, v211
	v_dot8c_i32_i4_e32 v229, v151, v215
	s_waitcnt vmcnt(6)
	v_mov_b32_e32 v222, 0
	v_mov_b32_e32 v230, 0
	v_dot8c_i32_i4_e32 v222, v152, v208
	v_dot8c_i32_i4_e32 v230, v152, v212
	v_dot8c_i32_i4_e32 v222, v153, v209
	v_dot8c_i32_i4_e32 v230, v153, v213
	v_dot8c_i32_i4_e32 v222, v154, v210
	v_dot8c_i32_i4_e32 v230, v154, v214
	v_dot8c_i32_i4_e32 v222, v155, v211
	v_dot8c_i32_i4_e32 v230, v155, v215
	s_waitcnt vmcnt(2)
	v_mov_b32_e32 v223, 0
	v_mov_b32_e32 v231, 0
	v_dot8c_i32_i4_e32 v223, v156, v208
	v_dot8c_i32_i4_e32 v231, v156, v212
	v_dot8c_i32_i4_e32 v223, v157, v209
	v_dot8c_i32_i4_e32 v231, v157, v213
	v_dot8c_i32_i4_e32 v223, v158, v210
	v_dot8c_i32_i4_e32 v231, v158, v214
	v_dot8c_i32_i4_e32 v223, v159, v211
	v_dot8c_i32_i4_e32 v231, v159, v215
	s_nop 2
	v_mad_i32_i24 v216, v216, 14, v224
	v_mad_i32_i24 v217, v217, 14, v225
	v_mad_i32_i24 v218, v218, 14, v226
	v_mad_i32_i24 v219, v219, 14, v227
	v_mad_i32_i24 v220, v220, 14, v228
	v_mad_i32_i24 v221, v221, 14, v229
	v_mad_i32_i24 v222, v222, 14, v230
	v_mad_i32_i24 v223, v223, 14, v231
	s_waitcnt lgkmcnt(4)
	v_readfirstlane_b32 s33, v10
	s_lshl_b32 s33, s33, 10
	s_add_u32 s72, s94, s33
	s_addc_u32 s73, s95, 0
	global_load_dwordx2 v[64:65], v28, s[72:73]
	global_load_dwordx2 v[66:67], v28, s[72:73] offset:512
	global_load_dwordx2 v[96:97], v29, s[72:73]
	global_load_dwordx2 v[98:99], v29, s[72:73] offset:512
	v_readfirstlane_b32 s33, v11
	s_lshl_b32 s33, s33, 10
	s_add_u32 s72, s94, s33
	s_addc_u32 s73, s95, 0
	global_load_dwordx2 v[68:69], v28, s[72:73]
	global_load_dwordx2 v[70:71], v28, s[72:73] offset:512
	global_load_dwordx2 v[100:101], v29, s[72:73]
	global_load_dwordx2 v[102:103], v29, s[72:73] offset:512
	v_readfirstlane_b32 s33, v12
	s_lshl_b32 s33, s33, 10
	s_add_u32 s72, s94, s33
	s_addc_u32 s73, s95, 0
	global_load_dwordx2 v[72:73], v28, s[72:73]
	global_load_dwordx2 v[74:75], v28, s[72:73] offset:512
	global_load_dwordx2 v[104:105], v29, s[72:73]
	global_load_dwordx2 v[106:107], v29, s[72:73] offset:512
	v_readfirstlane_b32 s33, v13
	s_lshl_b32 s33, s33, 10
	s_add_u32 s72, s94, s33
	s_addc_u32 s73, s95, 0
	global_load_dwordx2 v[76:77], v28, s[72:73]
	global_load_dwordx2 v[78:79], v28, s[72:73] offset:512
	global_load_dwordx2 v[108:109], v29, s[72:73]
	global_load_dwordx2 v[110:111], v29, s[72:73] offset:512
	v_readfirstlane_b32 s33, v18
	s_lshl_b32 s33, s33, 10
	s_add_u32 s72, s94, s33
	s_addc_u32 s73, s95, 0
	global_load_dwordx2 v[80:81], v28, s[72:73]
	global_load_dwordx2 v[82:83], v28, s[72:73] offset:512
	global_load_dwordx2 v[112:113], v29, s[72:73]
	global_load_dwordx2 v[114:115], v29, s[72:73] offset:512
	v_readfirstlane_b32 s33, v19
	s_lshl_b32 s33, s33, 10
	s_add_u32 s72, s94, s33
	s_addc_u32 s73, s95, 0
	global_load_dwordx2 v[84:85], v28, s[72:73]
	global_load_dwordx2 v[86:87], v28, s[72:73] offset:512
	global_load_dwordx2 v[116:117], v29, s[72:73]
	global_load_dwordx2 v[118:119], v29, s[72:73] offset:512
	v_readfirstlane_b32 s33, v20
	s_lshl_b32 s33, s33, 10
	s_add_u32 s72, s94, s33
	s_addc_u32 s73, s95, 0
	global_load_dwordx2 v[88:89], v28, s[72:73]
	global_load_dwordx2 v[90:91], v28, s[72:73] offset:512
	global_load_dwordx2 v[120:121], v29, s[72:73]
	global_load_dwordx2 v[122:123], v29, s[72:73] offset:512
	v_readfirstlane_b32 s33, v21
	s_lshl_b32 s33, s33, 10
	s_add_u32 s72, s94, s33
	s_addc_u32 s73, s95, 0
	global_load_dwordx2 v[92:93], v28, s[72:73]
	global_load_dwordx2 v[94:95], v28, s[72:73] offset:512
	global_load_dwordx2 v[124:125], v29, s[72:73]
	global_load_dwordx2 v[126:127], v29, s[72:73] offset:512
	s_nop 1
	v_permlane32_swap_b32_e32 v216, v217
	v_permlane32_swap_b32_e32 v218, v219
	v_permlane32_swap_b32_e32 v220, v221
	v_permlane32_swap_b32_e32 v222, v223
	v_add_u32_e32 v216, v216, v217
	v_add_u32_e32 v218, v218, v219
	v_add_u32_e32 v220, v220, v221
	v_add_u32_e32 v222, v222, v223
	s_nop 1
	v_permlane16_swap_b32_e32 v216, v218
	v_permlane16_swap_b32_e32 v220, v222
	v_add_u32_e32 v216, v216, v218
	v_add_u32_e32 v220, v220, v222
	s_nop 1
	v_add_u32_dpp v216, v216, v216 row_ror:8 row_mask:0xf bank_mask:0xf
	v_add_u32_dpp v220, v220, v220 row_ror:8 row_mask:0xf bank_mask:0xf
	s_nop 1
	v_add_u32_dpp v216, v216, v216 row_ror:4 row_mask:0xf bank_mask:0xf
	v_add_u32_dpp v220, v220, v220 row_ror:4 row_mask:0xf bank_mask:0xf
	s_nop 1
	v_add_u32_dpp v216, v216, v216 row_ror:2 row_mask:0xf bank_mask:0xf
	v_add_u32_dpp v220, v220, v220 row_ror:2 row_mask:0xf bank_mask:0xf
	s_nop 1
	v_add_u32_dpp v216, v216, v216 row_ror:1 row_mask:0xf bank_mask:0xf
	v_add_u32_dpp v220, v220, v220 row_ror:1 row_mask:0xf bank_mask:0xf
	s_waitcnt lgkmcnt(0)
	v_cvt_f32_i32_e32 v216, v216
	v_cvt_f32_i32_e32 v220, v220
	v_mul_f32_e32 v216, v216, v232
	v_mul_f32_e32 v220, v220, v233
	v_fma_f32 v2, |v216|, s83, 1.0
	v_fma_f32 v7, |v220|, s83, 1.0
	v_rcp_f32_e32 v2, v2
	v_rcp_f32_e32 v7, v7
	v_mul_f32_e32 v5, v216, v216
	v_mul_f32_e32 v11, v220, v220
	v_mul_f32_e32 v5, 0xbf38aa3b, v5
	v_mul_f32_e32 v11, 0xbf38aa3b, v11
	v_exp_f32_e32 v5, v5
	v_exp_f32_e32 v11, v11
	v_fmamk_f32 v3, v2, 0x3f07dc22, v172
	v_fmamk_f32 v10, v7, 0x3f07dc22, v172
	v_fmaak_f32 v3, v2, v3, 0x3f35f0e3
	v_fmaak_f32 v10, v7, v10, 0x3f35f0e3
	v_fmaak_f32 v3, v2, v3, 0xbe11a98e
	v_fmaak_f32 v10, v7, v10, 0xbe11a98e
	v_fmaak_f32 v3, v2, v3, 0x3e027906
	v_fmaak_f32 v10, v7, v10, 0x3e027906
	v_mul_f32_e32 v3, v2, v3
	v_mul_f32_e32 v10, v7, v10
	v_mul_f32_e32 v3, v5, v3
	v_mul_f32_e32 v10, v11, v10
	v_mul_f32_e32 v6, v216, v3
	v_mul_f32_e32 v12, v220, v10
	v_fma_f32 v3, -v216, v3, v216
	v_fma_f32 v10, -v220, v10, v220
	v_cmp_gt_f32_e32 vcc, 0, v216
	v_cmp_gt_f32_e64 s[96:97], 0, v220
	s_nop 1
	v_cndmask_b32_e32 v216, v3, v6, vcc
	v_cndmask_b32_e64 v220, v10, v12, s[96:97]
	v_mul_f32_e32 v216, v216, v234
	v_mul_f32_e32 v220, v220, v235
	s_nop 0
	v_readlane_b32 s64, v216, 0
	v_readlane_b32 s65, v216, 32
	v_readlane_b32 s66, v216, 16
	v_readlane_b32 s67, v216, 48
	v_readlane_b32 s68, v220, 0
	v_readlane_b32 s69, v220, 32
	v_readlane_b32 s70, v220, 16
	v_readlane_b32 s71, v220, 48
	s_waitcnt vmcnt(60)
	v_cvt_scalef32_pk_f32_fp4 v[160:161], v176, 1.0
	v_cvt_scalef32_pk_f32_fp4 v[162:163], v176, 1.0 op_sel:[1,0,0]
	v_cvt_scalef32_pk_f32_fp4 v[18:19], v176, 1.0 op_sel:[0,1,0]
	v_pk_fma_f32 v[32:33], v[160:161], s[64:65], v[32:33] op_sel_hi:[1,0,1]
	v_cvt_scalef32_pk_f32_fp4 v[20:21], v176, 1.0 op_sel:[1,1,0]
	v_pk_fma_f32 v[34:35], v[162:163], s[64:65], v[34:35] op_sel_hi:[1,0,1]
	v_cvt_scalef32_pk_f32_fp4 v[22:23], v177, 1.0
	v_pk_fma_f32 v[36:37], v[18:19], s[64:65], v[36:37] op_sel_hi:[1,0,1]
	v_cvt_scalef32_pk_f32_fp4 v[30:31], v177, 1.0 op_sel:[1,0,0]
	v_pk_fma_f32 v[38:39], v[20:21], s[64:65], v[38:39] op_sel_hi:[1,0,1]
	v_cvt_scalef32_pk_f32_fp4 v[2:3], v177, 1.0 op_sel:[0,1,0]
	v_pk_fma_f32 v[40:41], v[22:23], s[64:65], v[40:41] op_sel_hi:[1,0,1]
	v_cvt_scalef32_pk_f32_fp4 v[6:7], v177, 1.0 op_sel:[1,1,0]
	v_pk_fma_f32 v[42:43], v[30:31], s[64:65], v[42:43] op_sel_hi:[1,0,1]
	v_cvt_scalef32_pk_f32_fp4 v[160:161], v178, 1.0
	v_pk_fma_f32 v[44:45], v[2:3], s[64:65], v[44:45] op_sel_hi:[1,0,1]
	v_cvt_scalef32_pk_f32_fp4 v[162:163], v178, 1.0 op_sel:[1,0,0]
	v_pk_fma_f32 v[46:47], v[6:7], s[64:65], v[46:47] op_sel_hi:[1,0,1]
	v_cvt_scalef32_pk_f32_fp4 v[18:19], v178, 1.0 op_sel:[0,1,0]
	v_pk_fma_f32 v[48:49], v[160:161], s[64:65], v[48:49] op_sel_hi:[1,0,1]
	v_cvt_scalef32_pk_f32_fp4 v[20:21], v178, 1.0 op_sel:[1,1,0]
	v_pk_fma_f32 v[50:51], v[162:163], s[64:65], v[50:51] op_sel_hi:[1,0,1]
	v_cvt_scalef32_pk_f32_fp4 v[22:23], v179, 1.0
	v_pk_fma_f32 v[52:53], v[18:19], s[64:65], v[52:53] op_sel_hi:[1,0,1]
	v_cvt_scalef32_pk_f32_fp4 v[30:31], v179, 1.0 op_sel:[1,0,0]
	v_pk_fma_f32 v[54:55], v[20:21], s[64:65], v[54:55] op_sel_hi:[1,0,1]
	v_cvt_scalef32_pk_f32_fp4 v[2:3], v179, 1.0 op_sel:[0,1,0]
	v_pk_fma_f32 v[56:57], v[22:23], s[64:65], v[56:57] op_sel_hi:[1,0,1]
	v_cvt_scalef32_pk_f32_fp4 v[6:7], v179, 1.0 op_sel:[1,1,0]
	v_pk_fma_f32 v[58:59], v[30:31], s[64:65], v[58:59] op_sel_hi:[1,0,1]
	v_pk_fma_f32 v[60:61], v[2:3], s[64:65], v[60:61] op_sel_hi:[1,0,1]
	v_pk_fma_f32 v[62:63], v[6:7], s[64:65], v[62:63] op_sel_hi:[1,0,1]
	s_waitcnt vmcnt(56)
	v_cvt_scalef32_pk_f32_fp4 v[160:161], v180, 1.0
	v_cvt_scalef32_pk_f32_fp4 v[162:163], v180, 1.0 op_sel:[1,0,0]
	v_cvt_scalef32_pk_f32_fp4 v[18:19], v180, 1.0 op_sel:[0,1,0]
	v_pk_fma_f32 v[32:33], v[160:161], s[64:65], v[32:33] op_sel:[0,1,0] op_sel_hi:[1,1,1]
	v_cvt_scalef32_pk_f32_fp4 v[20:21], v180, 1.0 op_sel:[1,1,0]
	v_pk_fma_f32 v[34:35], v[162:163], s[64:65], v[34:35] op_sel:[0,1,0] op_sel_hi:[1,1,1]
	v_cvt_scalef32_pk_f32_fp4 v[22:23], v181, 1.0
	v_pk_fma_f32 v[36:37], v[18:19], s[64:65], v[36:37] op_sel:[0,1,0] op_sel_hi:[1,1,1]
	v_cvt_scalef32_pk_f32_fp4 v[30:31], v181, 1.0 op_sel:[1,0,0]
	v_pk_fma_f32 v[38:39], v[20:21], s[64:65], v[38:39] op_sel:[0,1,0] op_sel_hi:[1,1,1]
	v_cvt_scalef32_pk_f32_fp4 v[2:3], v181, 1.0 op_sel:[0,1,0]
	v_pk_fma_f32 v[40:41], v[22:23], s[64:65], v[40:41] op_sel:[0,1,0] op_sel_hi:[1,1,1]
	v_cvt_scalef32_pk_f32_fp4 v[6:7], v181, 1.0 op_sel:[1,1,0]
	v_pk_fma_f32 v[42:43], v[30:31], s[64:65], v[42:43] op_sel:[0,1,0] op_sel_hi:[1,1,1]
	v_cvt_scalef32_pk_f32_fp4 v[160:161], v182, 1.0
	v_pk_fma_f32 v[44:45], v[2:3], s[64:65], v[44:45] op_sel:[0,1,0] op_sel_hi:[1,1,1]
	v_cvt_scalef32_pk_f32_fp4 v[162:163], v182, 1.0 op_sel:[1,0,0]
	v_pk_fma_f32 v[46:47], v[6:7], s[64:65], v[46:47] op_sel:[0,1,0] op_sel_hi:[1,1,1]
	v_cvt_scalef32_pk_f32_fp4 v[18:19], v182, 1.0 op_sel:[0,1,0]
	v_pk_fma_f32 v[48:49], v[160:161], s[64:65], v[48:49] op_sel:[0,1,0] op_sel_hi:[1,1,1]
	v_cvt_scalef32_pk_f32_fp4 v[20:21], v182, 1.0 op_sel:[1,1,0]
	v_pk_fma_f32 v[50:51], v[162:163], s[64:65], v[50:51] op_sel:[0,1,0] op_sel_hi:[1,1,1]
	v_cvt_scalef32_pk_f32_fp4 v[22:23], v183, 1.0
	v_pk_fma_f32 v[52:53], v[18:19], s[64:65], v[52:53] op_sel:[0,1,0] op_sel_hi:[1,1,1]
	v_cvt_scalef32_pk_f32_fp4 v[30:31], v183, 1.0 op_sel:[1,0,0]
	v_pk_fma_f32 v[54:55], v[20:21], s[64:65], v[54:55] op_sel:[0,1,0] op_sel_hi:[1,1,1]
	v_cvt_scalef32_pk_f32_fp4 v[2:3], v183, 1.0 op_sel:[0,1,0]
	v_pk_fma_f32 v[56:57], v[22:23], s[64:65], v[56:57] op_sel:[0,1,0] op_sel_hi:[1,1,1]
	v_cvt_scalef32_pk_f32_fp4 v[6:7], v183, 1.0 op_sel:[1,1,0]
	v_pk_fma_f32 v[58:59], v[30:31], s[64:65], v[58:59] op_sel:[0,1,0] op_sel_hi:[1,1,1]
	v_pk_fma_f32 v[60:61], v[2:3], s[64:65], v[60:61] op_sel:[0,1,0] op_sel_hi:[1,1,1]
	v_pk_fma_f32 v[62:63], v[6:7], s[64:65], v[62:63] op_sel:[0,1,0] op_sel_hi:[1,1,1]
	s_waitcnt vmcnt(52)
	v_cvt_scalef32_pk_f32_fp4 v[160:161], v184, 1.0
	v_cvt_scalef32_pk_f32_fp4 v[162:163], v184, 1.0 op_sel:[1,0,0]
	v_cvt_scalef32_pk_f32_fp4 v[18:19], v184, 1.0 op_sel:[0,1,0]
	v_pk_fma_f32 v[32:33], v[160:161], s[66:67], v[32:33] op_sel_hi:[1,0,1]
	v_cvt_scalef32_pk_f32_fp4 v[20:21], v184, 1.0 op_sel:[1,1,0]
	v_pk_fma_f32 v[34:35], v[162:163], s[66:67], v[34:35] op_sel_hi:[1,0,1]
	v_cvt_scalef32_pk_f32_fp4 v[22:23], v185, 1.0
	v_pk_fma_f32 v[36:37], v[18:19], s[66:67], v[36:37] op_sel_hi:[1,0,1]
	v_cvt_scalef32_pk_f32_fp4 v[30:31], v185, 1.0 op_sel:[1,0,0]
	v_pk_fma_f32 v[38:39], v[20:21], s[66:67], v[38:39] op_sel_hi:[1,0,1]
	v_cvt_scalef32_pk_f32_fp4 v[2:3], v185, 1.0 op_sel:[0,1,0]
	v_pk_fma_f32 v[40:41], v[22:23], s[66:67], v[40:41] op_sel_hi:[1,0,1]
	v_cvt_scalef32_pk_f32_fp4 v[6:7], v185, 1.0 op_sel:[1,1,0]
	v_pk_fma_f32 v[42:43], v[30:31], s[66:67], v[42:43] op_sel_hi:[1,0,1]
	v_cvt_scalef32_pk_f32_fp4 v[160:161], v186, 1.0
	v_pk_fma_f32 v[44:45], v[2:3], s[66:67], v[44:45] op_sel_hi:[1,0,1]
	v_cvt_scalef32_pk_f32_fp4 v[162:163], v186, 1.0 op_sel:[1,0,0]
	v_pk_fma_f32 v[46:47], v[6:7], s[66:67], v[46:47] op_sel_hi:[1,0,1]
	v_cvt_scalef32_pk_f32_fp4 v[18:19], v186, 1.0 op_sel:[0,1,0]
	v_pk_fma_f32 v[48:49], v[160:161], s[66:67], v[48:49] op_sel_hi:[1,0,1]
	v_cvt_scalef32_pk_f32_fp4 v[20:21], v186, 1.0 op_sel:[1,1,0]
	v_pk_fma_f32 v[50:51], v[162:163], s[66:67], v[50:51] op_sel_hi:[1,0,1]
	v_cvt_scalef32_pk_f32_fp4 v[22:23], v187, 1.0
	v_pk_fma_f32 v[52:53], v[18:19], s[66:67], v[52:53] op_sel_hi:[1,0,1]
	v_cvt_scalef32_pk_f32_fp4 v[30:31], v187, 1.0 op_sel:[1,0,0]
	v_pk_fma_f32 v[54:55], v[20:21], s[66:67], v[54:55] op_sel_hi:[1,0,1]
	v_cvt_scalef32_pk_f32_fp4 v[2:3], v187, 1.0 op_sel:[0,1,0]
	v_pk_fma_f32 v[56:57], v[22:23], s[66:67], v[56:57] op_sel_hi:[1,0,1]
	v_cvt_scalef32_pk_f32_fp4 v[6:7], v187, 1.0 op_sel:[1,1,0]
	v_pk_fma_f32 v[58:59], v[30:31], s[66:67], v[58:59] op_sel_hi:[1,0,1]
	v_pk_fma_f32 v[60:61], v[2:3], s[66:67], v[60:61] op_sel_hi:[1,0,1]
	v_pk_fma_f32 v[62:63], v[6:7], s[66:67], v[62:63] op_sel_hi:[1,0,1]
	s_waitcnt vmcnt(48)
	v_cvt_scalef32_pk_f32_fp4 v[160:161], v188, 1.0
	v_cvt_scalef32_pk_f32_fp4 v[162:163], v188, 1.0 op_sel:[1,0,0]
	v_cvt_scalef32_pk_f32_fp4 v[18:19], v188, 1.0 op_sel:[0,1,0]
	v_pk_fma_f32 v[32:33], v[160:161], s[66:67], v[32:33] op_sel:[0,1,0] op_sel_hi:[1,1,1]
	v_cvt_scalef32_pk_f32_fp4 v[20:21], v188, 1.0 op_sel:[1,1,0]
	v_pk_fma_f32 v[34:35], v[162:163], s[66:67], v[34:35] op_sel:[0,1,0] op_sel_hi:[1,1,1]
	v_cvt_scalef32_pk_f32_fp4 v[22:23], v189, 1.0
	v_pk_fma_f32 v[36:37], v[18:19], s[66:67], v[36:37] op_sel:[0,1,0] op_sel_hi:[1,1,1]
	v_cvt_scalef32_pk_f32_fp4 v[30:31], v189, 1.0 op_sel:[1,0,0]
	v_pk_fma_f32 v[38:39], v[20:21], s[66:67], v[38:39] op_sel:[0,1,0] op_sel_hi:[1,1,1]
	v_cvt_scalef32_pk_f32_fp4 v[2:3], v189, 1.0 op_sel:[0,1,0]
	v_pk_fma_f32 v[40:41], v[22:23], s[66:67], v[40:41] op_sel:[0,1,0] op_sel_hi:[1,1,1]
	v_cvt_scalef32_pk_f32_fp4 v[6:7], v189, 1.0 op_sel:[1,1,0]
	v_pk_fma_f32 v[42:43], v[30:31], s[66:67], v[42:43] op_sel:[0,1,0] op_sel_hi:[1,1,1]
	v_cvt_scalef32_pk_f32_fp4 v[160:161], v190, 1.0
	v_pk_fma_f32 v[44:45], v[2:3], s[66:67], v[44:45] op_sel:[0,1,0] op_sel_hi:[1,1,1]
	v_cvt_scalef32_pk_f32_fp4 v[162:163], v190, 1.0 op_sel:[1,0,0]
	v_pk_fma_f32 v[46:47], v[6:7], s[66:67], v[46:47] op_sel:[0,1,0] op_sel_hi:[1,1,1]
	v_cvt_scalef32_pk_f32_fp4 v[18:19], v190, 1.0 op_sel:[0,1,0]
	v_pk_fma_f32 v[48:49], v[160:161], s[66:67], v[48:49] op_sel:[0,1,0] op_sel_hi:[1,1,1]
	v_cvt_scalef32_pk_f32_fp4 v[20:21], v190, 1.0 op_sel:[1,1,0]
	v_pk_fma_f32 v[50:51], v[162:163], s[66:67], v[50:51] op_sel:[0,1,0] op_sel_hi:[1,1,1]
	v_cvt_scalef32_pk_f32_fp4 v[22:23], v191, 1.0
	v_pk_fma_f32 v[52:53], v[18:19], s[66:67], v[52:53] op_sel:[0,1,0] op_sel_hi:[1,1,1]
	v_cvt_scalef32_pk_f32_fp4 v[30:31], v191, 1.0 op_sel:[1,0,0]
	v_pk_fma_f32 v[54:55], v[20:21], s[66:67], v[54:55] op_sel:[0,1,0] op_sel_hi:[1,1,1]
	v_cvt_scalef32_pk_f32_fp4 v[2:3], v191, 1.0 op_sel:[0,1,0]
	v_pk_fma_f32 v[56:57], v[22:23], s[66:67], v[56:57] op_sel:[0,1,0] op_sel_hi:[1,1,1]
	v_cvt_scalef32_pk_f32_fp4 v[6:7], v191, 1.0 op_sel:[1,1,0]
	v_pk_fma_f32 v[58:59], v[30:31], s[66:67], v[58:59] op_sel:[0,1,0] op_sel_hi:[1,1,1]
	v_pk_fma_f32 v[60:61], v[2:3], s[66:67], v[60:61] op_sel:[0,1,0] op_sel_hi:[1,1,1]
	v_pk_fma_f32 v[62:63], v[6:7], s[66:67], v[62:63] op_sel:[0,1,0] op_sel_hi:[1,1,1]
	s_waitcnt vmcnt(44)
	v_cvt_scalef32_pk_f32_fp4 v[160:161], v192, 1.0
	v_cvt_scalef32_pk_f32_fp4 v[162:163], v192, 1.0 op_sel:[1,0,0]
	v_cvt_scalef32_pk_f32_fp4 v[18:19], v192, 1.0 op_sel:[0,1,0]
	v_pk_fma_f32 v[32:33], v[160:161], s[68:69], v[32:33] op_sel_hi:[1,0,1]
	v_cvt_scalef32_pk_f32_fp4 v[20:21], v192, 1.0 op_sel:[1,1,0]
	v_pk_fma_f32 v[34:35], v[162:163], s[68:69], v[34:35] op_sel_hi:[1,0,1]
	v_cvt_scalef32_pk_f32_fp4 v[22:23], v193, 1.0
	v_pk_fma_f32 v[36:37], v[18:19], s[68:69], v[36:37] op_sel_hi:[1,0,1]
	v_cvt_scalef32_pk_f32_fp4 v[30:31], v193, 1.0 op_sel:[1,0,0]
	v_pk_fma_f32 v[38:39], v[20:21], s[68:69], v[38:39] op_sel_hi:[1,0,1]
	v_cvt_scalef32_pk_f32_fp4 v[2:3], v193, 1.0 op_sel:[0,1,0]
	v_pk_fma_f32 v[40:41], v[22:23], s[68:69], v[40:41] op_sel_hi:[1,0,1]
	v_cvt_scalef32_pk_f32_fp4 v[6:7], v193, 1.0 op_sel:[1,1,0]
	v_pk_fma_f32 v[42:43], v[30:31], s[68:69], v[42:43] op_sel_hi:[1,0,1]
	v_cvt_scalef32_pk_f32_fp4 v[160:161], v194, 1.0
	v_pk_fma_f32 v[44:45], v[2:3], s[68:69], v[44:45] op_sel_hi:[1,0,1]
	v_cvt_scalef32_pk_f32_fp4 v[162:163], v194, 1.0 op_sel:[1,0,0]
	v_pk_fma_f32 v[46:47], v[6:7], s[68:69], v[46:47] op_sel_hi:[1,0,1]
	v_cvt_scalef32_pk_f32_fp4 v[18:19], v194, 1.0 op_sel:[0,1,0]
	v_pk_fma_f32 v[48:49], v[160:161], s[68:69], v[48:49] op_sel_hi:[1,0,1]
	v_cvt_scalef32_pk_f32_fp4 v[20:21], v194, 1.0 op_sel:[1,1,0]
	v_pk_fma_f32 v[50:51], v[162:163], s[68:69], v[50:51] op_sel_hi:[1,0,1]
	v_cvt_scalef32_pk_f32_fp4 v[22:23], v195, 1.0
	v_pk_fma_f32 v[52:53], v[18:19], s[68:69], v[52:53] op_sel_hi:[1,0,1]
	v_cvt_scalef32_pk_f32_fp4 v[30:31], v195, 1.0 op_sel:[1,0,0]
	v_pk_fma_f32 v[54:55], v[20:21], s[68:69], v[54:55] op_sel_hi:[1,0,1]
	v_cvt_scalef32_pk_f32_fp4 v[2:3], v195, 1.0 op_sel:[0,1,0]
	v_pk_fma_f32 v[56:57], v[22:23], s[68:69], v[56:57] op_sel_hi:[1,0,1]
	v_cvt_scalef32_pk_f32_fp4 v[6:7], v195, 1.0 op_sel:[1,1,0]
	v_pk_fma_f32 v[58:59], v[30:31], s[68:69], v[58:59] op_sel_hi:[1,0,1]
	v_pk_fma_f32 v[60:61], v[2:3], s[68:69], v[60:61] op_sel_hi:[1,0,1]
	v_pk_fma_f32 v[62:63], v[6:7], s[68:69], v[62:63] op_sel_hi:[1,0,1]
	s_waitcnt vmcnt(40)
	v_cvt_scalef32_pk_f32_fp4 v[160:161], v196, 1.0
	v_cvt_scalef32_pk_f32_fp4 v[162:163], v196, 1.0 op_sel:[1,0,0]
	v_cvt_scalef32_pk_f32_fp4 v[18:19], v196, 1.0 op_sel:[0,1,0]
	v_pk_fma_f32 v[32:33], v[160:161], s[68:69], v[32:33] op_sel:[0,1,0] op_sel_hi:[1,1,1]
	v_cvt_scalef32_pk_f32_fp4 v[20:21], v196, 1.0 op_sel:[1,1,0]
	v_pk_fma_f32 v[34:35], v[162:163], s[68:69], v[34:35] op_sel:[0,1,0] op_sel_hi:[1,1,1]
	v_cvt_scalef32_pk_f32_fp4 v[22:23], v197, 1.0
	v_pk_fma_f32 v[36:37], v[18:19], s[68:69], v[36:37] op_sel:[0,1,0] op_sel_hi:[1,1,1]
	v_cvt_scalef32_pk_f32_fp4 v[30:31], v197, 1.0 op_sel:[1,0,0]
	v_pk_fma_f32 v[38:39], v[20:21], s[68:69], v[38:39] op_sel:[0,1,0] op_sel_hi:[1,1,1]
	v_cvt_scalef32_pk_f32_fp4 v[2:3], v197, 1.0 op_sel:[0,1,0]
	v_pk_fma_f32 v[40:41], v[22:23], s[68:69], v[40:41] op_sel:[0,1,0] op_sel_hi:[1,1,1]
	v_cvt_scalef32_pk_f32_fp4 v[6:7], v197, 1.0 op_sel:[1,1,0]
	v_pk_fma_f32 v[42:43], v[30:31], s[68:69], v[42:43] op_sel:[0,1,0] op_sel_hi:[1,1,1]
	v_cvt_scalef32_pk_f32_fp4 v[160:161], v198, 1.0
	v_pk_fma_f32 v[44:45], v[2:3], s[68:69], v[44:45] op_sel:[0,1,0] op_sel_hi:[1,1,1]
	v_cvt_scalef32_pk_f32_fp4 v[162:163], v198, 1.0 op_sel:[1,0,0]
	v_pk_fma_f32 v[46:47], v[6:7], s[68:69], v[46:47] op_sel:[0,1,0] op_sel_hi:[1,1,1]
	v_cvt_scalef32_pk_f32_fp4 v[18:19], v198, 1.0 op_sel:[0,1,0]
	v_pk_fma_f32 v[48:49], v[160:161], s[68:69], v[48:49] op_sel:[0,1,0] op_sel_hi:[1,1,1]
	v_cvt_scalef32_pk_f32_fp4 v[20:21], v198, 1.0 op_sel:[1,1,0]
	v_pk_fma_f32 v[50:51], v[162:163], s[68:69], v[50:51] op_sel:[0,1,0] op_sel_hi:[1,1,1]
	v_cvt_scalef32_pk_f32_fp4 v[22:23], v199, 1.0
	v_pk_fma_f32 v[52:53], v[18:19], s[68:69], v[52:53] op_sel:[0,1,0] op_sel_hi:[1,1,1]
	v_cvt_scalef32_pk_f32_fp4 v[30:31], v199, 1.0 op_sel:[1,0,0]
	v_pk_fma_f32 v[54:55], v[20:21], s[68:69], v[54:55] op_sel:[0,1,0] op_sel_hi:[1,1,1]
	v_cvt_scalef32_pk_f32_fp4 v[2:3], v199, 1.0 op_sel:[0,1,0]
	v_pk_fma_f32 v[56:57], v[22:23], s[68:69], v[56:57] op_sel:[0,1,0] op_sel_hi:[1,1,1]
	v_cvt_scalef32_pk_f32_fp4 v[6:7], v199, 1.0 op_sel:[1,1,0]
	v_pk_fma_f32 v[58:59], v[30:31], s[68:69], v[58:59] op_sel:[0,1,0] op_sel_hi:[1,1,1]
	v_pk_fma_f32 v[60:61], v[2:3], s[68:69], v[60:61] op_sel:[0,1,0] op_sel_hi:[1,1,1]
	v_pk_fma_f32 v[62:63], v[6:7], s[68:69], v[62:63] op_sel:[0,1,0] op_sel_hi:[1,1,1]
	s_waitcnt vmcnt(36)
	v_cvt_scalef32_pk_f32_fp4 v[160:161], v200, 1.0
	v_cvt_scalef32_pk_f32_fp4 v[162:163], v200, 1.0 op_sel:[1,0,0]
	v_cvt_scalef32_pk_f32_fp4 v[18:19], v200, 1.0 op_sel:[0,1,0]
	v_pk_fma_f32 v[32:33], v[160:161], s[70:71], v[32:33] op_sel_hi:[1,0,1]
	v_cvt_scalef32_pk_f32_fp4 v[20:21], v200, 1.0 op_sel:[1,1,0]
	v_pk_fma_f32 v[34:35], v[162:163], s[70:71], v[34:35] op_sel_hi:[1,0,1]
	v_cvt_scalef32_pk_f32_fp4 v[22:23], v201, 1.0
	v_pk_fma_f32 v[36:37], v[18:19], s[70:71], v[36:37] op_sel_hi:[1,0,1]
	v_cvt_scalef32_pk_f32_fp4 v[30:31], v201, 1.0 op_sel:[1,0,0]
	v_pk_fma_f32 v[38:39], v[20:21], s[70:71], v[38:39] op_sel_hi:[1,0,1]
	v_cvt_scalef32_pk_f32_fp4 v[2:3], v201, 1.0 op_sel:[0,1,0]
	v_pk_fma_f32 v[40:41], v[22:23], s[70:71], v[40:41] op_sel_hi:[1,0,1]
	v_cvt_scalef32_pk_f32_fp4 v[6:7], v201, 1.0 op_sel:[1,1,0]
	v_pk_fma_f32 v[42:43], v[30:31], s[70:71], v[42:43] op_sel_hi:[1,0,1]
	v_cvt_scalef32_pk_f32_fp4 v[160:161], v202, 1.0
	v_pk_fma_f32 v[44:45], v[2:3], s[70:71], v[44:45] op_sel_hi:[1,0,1]
	v_cvt_scalef32_pk_f32_fp4 v[162:163], v202, 1.0 op_sel:[1,0,0]
	v_pk_fma_f32 v[46:47], v[6:7], s[70:71], v[46:47] op_sel_hi:[1,0,1]
	v_cvt_scalef32_pk_f32_fp4 v[18:19], v202, 1.0 op_sel:[0,1,0]
	v_pk_fma_f32 v[48:49], v[160:161], s[70:71], v[48:49] op_sel_hi:[1,0,1]
	v_cvt_scalef32_pk_f32_fp4 v[20:21], v202, 1.0 op_sel:[1,1,0]
	v_pk_fma_f32 v[50:51], v[162:163], s[70:71], v[50:51] op_sel_hi:[1,0,1]
	v_cvt_scalef32_pk_f32_fp4 v[22:23], v203, 1.0
	v_pk_fma_f32 v[52:53], v[18:19], s[70:71], v[52:53] op_sel_hi:[1,0,1]
	v_cvt_scalef32_pk_f32_fp4 v[30:31], v203, 1.0 op_sel:[1,0,0]
	v_pk_fma_f32 v[54:55], v[20:21], s[70:71], v[54:55] op_sel_hi:[1,0,1]
	v_cvt_scalef32_pk_f32_fp4 v[2:3], v203, 1.0 op_sel:[0,1,0]
	v_pk_fma_f32 v[56:57], v[22:23], s[70:71], v[56:57] op_sel_hi:[1,0,1]
	v_cvt_scalef32_pk_f32_fp4 v[6:7], v203, 1.0 op_sel:[1,1,0]
	v_pk_fma_f32 v[58:59], v[30:31], s[70:71], v[58:59] op_sel_hi:[1,0,1]
	v_pk_fma_f32 v[60:61], v[2:3], s[70:71], v[60:61] op_sel_hi:[1,0,1]
	v_pk_fma_f32 v[62:63], v[6:7], s[70:71], v[62:63] op_sel_hi:[1,0,1]
	s_waitcnt vmcnt(32)
	v_cvt_scalef32_pk_f32_fp4 v[160:161], v240, 1.0
	v_cvt_scalef32_pk_f32_fp4 v[162:163], v240, 1.0 op_sel:[1,0,0]
	v_cvt_scalef32_pk_f32_fp4 v[18:19], v240, 1.0 op_sel:[0,1,0]
	v_pk_fma_f32 v[32:33], v[160:161], s[70:71], v[32:33] op_sel:[0,1,0] op_sel_hi:[1,1,1]
	v_cvt_scalef32_pk_f32_fp4 v[20:21], v240, 1.0 op_sel:[1,1,0]
	v_pk_fma_f32 v[34:35], v[162:163], s[70:71], v[34:35] op_sel:[0,1,0] op_sel_hi:[1,1,1]
	v_cvt_scalef32_pk_f32_fp4 v[22:23], v241, 1.0
	v_pk_fma_f32 v[36:37], v[18:19], s[70:71], v[36:37] op_sel:[0,1,0] op_sel_hi:[1,1,1]
	v_cvt_scalef32_pk_f32_fp4 v[30:31], v241, 1.0 op_sel:[1,0,0]
	v_pk_fma_f32 v[38:39], v[20:21], s[70:71], v[38:39] op_sel:[0,1,0] op_sel_hi:[1,1,1]
	v_cvt_scalef32_pk_f32_fp4 v[2:3], v241, 1.0 op_sel:[0,1,0]
	v_pk_fma_f32 v[40:41], v[22:23], s[70:71], v[40:41] op_sel:[0,1,0] op_sel_hi:[1,1,1]
	v_cvt_scalef32_pk_f32_fp4 v[6:7], v241, 1.0 op_sel:[1,1,0]
	v_pk_fma_f32 v[42:43], v[30:31], s[70:71], v[42:43] op_sel:[0,1,0] op_sel_hi:[1,1,1]
	v_cvt_scalef32_pk_f32_fp4 v[160:161], v242, 1.0
	v_pk_fma_f32 v[44:45], v[2:3], s[70:71], v[44:45] op_sel:[0,1,0] op_sel_hi:[1,1,1]
	v_cvt_scalef32_pk_f32_fp4 v[162:163], v242, 1.0 op_sel:[1,0,0]
	v_pk_fma_f32 v[46:47], v[6:7], s[70:71], v[46:47] op_sel:[0,1,0] op_sel_hi:[1,1,1]
	v_cvt_scalef32_pk_f32_fp4 v[18:19], v242, 1.0 op_sel:[0,1,0]
	v_pk_fma_f32 v[48:49], v[160:161], s[70:71], v[48:49] op_sel:[0,1,0] op_sel_hi:[1,1,1]
	v_cvt_scalef32_pk_f32_fp4 v[20:21], v242, 1.0 op_sel:[1,1,0]
	v_pk_fma_f32 v[50:51], v[162:163], s[70:71], v[50:51] op_sel:[0,1,0] op_sel_hi:[1,1,1]
	v_cvt_scalef32_pk_f32_fp4 v[22:23], v243, 1.0
	v_pk_fma_f32 v[52:53], v[18:19], s[70:71], v[52:53] op_sel:[0,1,0] op_sel_hi:[1,1,1]
	v_cvt_scalef32_pk_f32_fp4 v[30:31], v243, 1.0 op_sel:[1,0,0]
	v_pk_fma_f32 v[54:55], v[20:21], s[70:71], v[54:55] op_sel:[0,1,0] op_sel_hi:[1,1,1]
	v_cvt_scalef32_pk_f32_fp4 v[2:3], v243, 1.0 op_sel:[0,1,0]
	v_pk_fma_f32 v[56:57], v[22:23], s[70:71], v[56:57] op_sel:[0,1,0] op_sel_hi:[1,1,1]
	v_cvt_scalef32_pk_f32_fp4 v[6:7], v243, 1.0 op_sel:[1,1,0]
	v_pk_fma_f32 v[58:59], v[30:31], s[70:71], v[58:59] op_sel:[0,1,0] op_sel_hi:[1,1,1]
	v_pk_fma_f32 v[60:61], v[2:3], s[70:71], v[60:61] op_sel:[0,1,0] op_sel_hi:[1,1,1]
	v_pk_fma_f32 v[62:63], v[6:7], s[70:71], v[62:63] op_sel:[0,1,0] op_sel_hi:[1,1,1]
	s_sub_u32 s86, s86, 1
	s_cmp_lg_u32 s86, 0
	s_cbranch_scc1 .Lp8_eloop
	ds_read_b128 v[10:13], v25
	ds_read_b128 v[18:21], v25 offset:16
	v_add_u32_e32 v25, 32, v25
	ds_read_b32 v232, v26
	ds_read_b32 v233, v27
	ds_read_b32 v234, v26 offset:512
	ds_read_b32 v235, v27 offset:512
	v_add_u32_e32 v26, 32, v26
	v_add_u32_e32 v27, 32, v27
	s_waitcnt vmcnt(30)
	v_mov_b32_e32 v216, 0
	v_mov_b32_e32 v224, 0
	v_dot8c_i32_i4_e32 v216, v64, v208
	v_dot8c_i32_i4_e32 v224, v64, v212
	v_dot8c_i32_i4_e32 v216, v65, v209
	v_dot8c_i32_i4_e32 v224, v65, v213
	v_dot8c_i32_i4_e32 v216, v66, v210
	v_dot8c_i32_i4_e32 v224, v66, v214
	v_dot8c_i32_i4_e32 v216, v67, v211
	v_dot8c_i32_i4_e32 v224, v67, v215
	s_waitcnt vmcnt(26)
	v_mov_b32_e32 v217, 0
	v_mov_b32_e32 v225, 0
	v_dot8c_i32_i4_e32 v217, v68, v208
	v_dot8c_i32_i4_e32 v225, v68, v212
	v_dot8c_i32_i4_e32 v217, v69, v209
	v_dot8c_i32_i4_e32 v225, v69, v213
	v_dot8c_i32_i4_e32 v217, v70, v210
	v_dot8c_i32_i4_e32 v225, v70, v214
	v_dot8c_i32_i4_e32 v217, v71, v211
	v_dot8c_i32_i4_e32 v225, v71, v215
	s_waitcnt vmcnt(22)
	v_mov_b32_e32 v218, 0
	v_mov_b32_e32 v226, 0
	v_dot8c_i32_i4_e32 v218, v72, v208
	v_dot8c_i32_i4_e32 v226, v72, v212
	v_dot8c_i32_i4_e32 v218, v73, v209
	v_dot8c_i32_i4_e32 v226, v73, v213
	v_dot8c_i32_i4_e32 v218, v74, v210
	v_dot8c_i32_i4_e32 v226, v74, v214
	v_dot8c_i32_i4_e32 v218, v75, v211
	v_dot8c_i32_i4_e32 v226, v75, v215
	s_waitcnt vmcnt(18)
	v_mov_b32_e32 v219, 0
	v_mov_b32_e32 v227, 0
	v_dot8c_i32_i4_e32 v219, v76, v208
	v_dot8c_i32_i4_e32 v227, v76, v212
	v_dot8c_i32_i4_e32 v219, v77, v209
	v_dot8c_i32_i4_e32 v227, v77, v213
	v_dot8c_i32_i4_e32 v219, v78, v210
	v_dot8c_i32_i4_e32 v227, v78, v214
	v_dot8c_i32_i4_e32 v219, v79, v211
	v_dot8c_i32_i4_e32 v227, v79, v215
	s_waitcnt vmcnt(14)
	v_mov_b32_e32 v220, 0
	v_mov_b32_e32 v228, 0
	v_dot8c_i32_i4_e32 v220, v80, v208
	v_dot8c_i32_i4_e32 v228, v80, v212
	v_dot8c_i32_i4_e32 v220, v81, v209
	v_dot8c_i32_i4_e32 v228, v81, v213
	v_dot8c_i32_i4_e32 v220, v82, v210
	v_dot8c_i32_i4_e32 v228, v82, v214
	v_dot8c_i32_i4_e32 v220, v83, v211
	v_dot8c_i32_i4_e32 v228, v83, v215
	s_waitcnt vmcnt(10)
	v_mov_b32_e32 v221, 0
	v_mov_b32_e32 v229, 0
	v_dot8c_i32_i4_e32 v221, v84, v208
	v_dot8c_i32_i4_e32 v229, v84, v212
	v_dot8c_i32_i4_e32 v221, v85, v209
	v_dot8c_i32_i4_e32 v229, v85, v213
	v_dot8c_i32_i4_e32 v221, v86, v210
	v_dot8c_i32_i4_e32 v229, v86, v214
	v_dot8c_i32_i4_e32 v221, v87, v211
	v_dot8c_i32_i4_e32 v229, v87, v215
	s_waitcnt vmcnt(6)
	v_mov_b32_e32 v222, 0
	v_mov_b32_e32 v230, 0
	v_dot8c_i32_i4_e32 v222, v88, v208
	v_dot8c_i32_i4_e32 v230, v88, v212
	v_dot8c_i32_i4_e32 v222, v89, v209
	v_dot8c_i32_i4_e32 v230, v89, v213
	v_dot8c_i32_i4_e32 v222, v90, v210
	v_dot8c_i32_i4_e32 v230, v90, v214
	v_dot8c_i32_i4_e32 v222, v91, v211
	v_dot8c_i32_i4_e32 v230, v91, v215
	s_waitcnt vmcnt(2)
	v_mov_b32_e32 v223, 0
	v_mov_b32_e32 v231, 0
	v_dot8c_i32_i4_e32 v223, v92, v208
	v_dot8c_i32_i4_e32 v231, v92, v212
	v_dot8c_i32_i4_e32 v223, v93, v209
	v_dot8c_i32_i4_e32 v231, v93, v213
	v_dot8c_i32_i4_e32 v223, v94, v210
	v_dot8c_i32_i4_e32 v231, v94, v214
	v_dot8c_i32_i4_e32 v223, v95, v211
	v_dot8c_i32_i4_e32 v231, v95, v215
	s_nop 2
	v_mad_i32_i24 v216, v216, 14, v224
	v_mad_i32_i24 v217, v217, 14, v225
	v_mad_i32_i24 v218, v218, 14, v226
	v_mad_i32_i24 v219, v219, 14, v227
	v_mad_i32_i24 v220, v220, 14, v228
	v_mad_i32_i24 v221, v221, 14, v229
	v_mad_i32_i24 v222, v222, 14, v230
	v_mad_i32_i24 v223, v223, 14, v231
	s_waitcnt lgkmcnt(4)
	v_readfirstlane_b32 s33, v10
	s_lshl_b32 s33, s33, 10
	s_add_u32 s72, s94, s33
	s_addc_u32 s73, s95, 0
	global_load_dwordx2 v[128:129], v28, s[72:73]
	global_load_dwordx2 v[130:131], v28, s[72:73] offset:512
	global_load_dwordx2 v[176:177], v29, s[72:73]
	global_load_dwordx2 v[178:179], v29, s[72:73] offset:512
	v_readfirstlane_b32 s33, v11
	s_lshl_b32 s33, s33, 10
	s_add_u32 s72, s94, s33
	s_addc_u32 s73, s95, 0
	global_load_dwordx2 v[132:133], v28, s[72:73]
	global_load_dwordx2 v[134:135], v28, s[72:73] offset:512
	global_load_dwordx2 v[180:181], v29, s[72:73]
	global_load_dwordx2 v[182:183], v29, s[72:73] offset:512
	v_readfirstlane_b32 s33, v12
	s_lshl_b32 s33, s33, 10
	s_add_u32 s72, s94, s33
	s_addc_u32 s73, s95, 0
	global_load_dwordx2 v[136:137], v28, s[72:73]
	global_load_dwordx2 v[138:139], v28, s[72:73] offset:512
	global_load_dwordx2 v[184:185], v29, s[72:73]
	global_load_dwordx2 v[186:187], v29, s[72:73] offset:512
	v_readfirstlane_b32 s33, v13
	s_lshl_b32 s33, s33, 10
	s_add_u32 s72, s94, s33
	s_addc_u32 s73, s95, 0
	global_load_dwordx2 v[140:141], v28, s[72:73]
	global_load_dwordx2 v[142:143], v28, s[72:73] offset:512
	global_load_dwordx2 v[188:189], v29, s[72:73]
	global_load_dwordx2 v[190:191], v29, s[72:73] offset:512
	v_readfirstlane_b32 s33, v18
	s_lshl_b32 s33, s33, 10
	s_add_u32 s72, s94, s33
	s_addc_u32 s73, s95, 0
	global_load_dwordx2 v[144:145], v28, s[72:73]
	global_load_dwordx2 v[146:147], v28, s[72:73] offset:512
	global_load_dwordx2 v[192:193], v29, s[72:73]
	global_load_dwordx2 v[194:195], v29, s[72:73] offset:512
	v_readfirstlane_b32 s33, v19
	s_lshl_b32 s33, s33, 10
	s_add_u32 s72, s94, s33
	s_addc_u32 s73, s95, 0
	global_load_dwordx2 v[148:149], v28, s[72:73]
	global_load_dwordx2 v[150:151], v28, s[72:73] offset:512
	global_load_dwordx2 v[196:197], v29, s[72:73]
	global_load_dwordx2 v[198:199], v29, s[72:73] offset:512
	v_readfirstlane_b32 s33, v20
	s_lshl_b32 s33, s33, 10
	s_add_u32 s72, s94, s33
	s_addc_u32 s73, s95, 0
	global_load_dwordx2 v[152:153], v28, s[72:73]
	global_load_dwordx2 v[154:155], v28, s[72:73] offset:512
	global_load_dwordx2 v[200:201], v29, s[72:73]
	global_load_dwordx2 v[202:203], v29, s[72:73] offset:512
	v_readfirstlane_b32 s33, v21
	s_lshl_b32 s33, s33, 10
	s_add_u32 s72, s94, s33
	s_addc_u32 s73, s95, 0
	global_load_dwordx2 v[156:157], v28, s[72:73]
	global_load_dwordx2 v[158:159], v28, s[72:73] offset:512
	global_load_dwordx2 v[240:241], v29, s[72:73]
	global_load_dwordx2 v[242:243], v29, s[72:73] offset:512
	s_nop 1
	v_permlane32_swap_b32_e32 v216, v217
	v_permlane32_swap_b32_e32 v218, v219
	v_permlane32_swap_b32_e32 v220, v221
	v_permlane32_swap_b32_e32 v222, v223
	v_add_u32_e32 v216, v216, v217
	v_add_u32_e32 v218, v218, v219
	v_add_u32_e32 v220, v220, v221
	v_add_u32_e32 v222, v222, v223
	s_nop 1
	v_permlane16_swap_b32_e32 v216, v218
	v_permlane16_swap_b32_e32 v220, v222
	v_add_u32_e32 v216, v216, v218
	v_add_u32_e32 v220, v220, v222
	s_nop 1
	v_add_u32_dpp v216, v216, v216 row_ror:8 row_mask:0xf bank_mask:0xf
	v_add_u32_dpp v220, v220, v220 row_ror:8 row_mask:0xf bank_mask:0xf
	s_nop 1
	v_add_u32_dpp v216, v216, v216 row_ror:4 row_mask:0xf bank_mask:0xf
	v_add_u32_dpp v220, v220, v220 row_ror:4 row_mask:0xf bank_mask:0xf
	s_nop 1
	v_add_u32_dpp v216, v216, v216 row_ror:2 row_mask:0xf bank_mask:0xf
	v_add_u32_dpp v220, v220, v220 row_ror:2 row_mask:0xf bank_mask:0xf
	s_nop 1
	v_add_u32_dpp v216, v216, v216 row_ror:1 row_mask:0xf bank_mask:0xf
	v_add_u32_dpp v220, v220, v220 row_ror:1 row_mask:0xf bank_mask:0xf
	s_waitcnt lgkmcnt(0)
	v_cvt_f32_i32_e32 v216, v216
	v_cvt_f32_i32_e32 v220, v220
	v_mul_f32_e32 v216, v216, v232
	v_mul_f32_e32 v220, v220, v233
	v_fma_f32 v2, |v216|, s83, 1.0
	v_fma_f32 v7, |v220|, s83, 1.0
	v_rcp_f32_e32 v2, v2
	v_rcp_f32_e32 v7, v7
	v_mul_f32_e32 v5, v216, v216
	v_mul_f32_e32 v11, v220, v220
	v_mul_f32_e32 v5, 0xbf38aa3b, v5
	v_mul_f32_e32 v11, 0xbf38aa3b, v11
	v_exp_f32_e32 v5, v5
	v_exp_f32_e32 v11, v11
	v_fmamk_f32 v3, v2, 0x3f07dc22, v172
	v_fmamk_f32 v10, v7, 0x3f07dc22, v172
	v_fmaak_f32 v3, v2, v3, 0x3f35f0e3
	v_fmaak_f32 v10, v7, v10, 0x3f35f0e3
	v_fmaak_f32 v3, v2, v3, 0xbe11a98e
	v_fmaak_f32 v10, v7, v10, 0xbe11a98e
	v_fmaak_f32 v3, v2, v3, 0x3e027906
	v_fmaak_f32 v10, v7, v10, 0x3e027906
	v_mul_f32_e32 v3, v2, v3
	v_mul_f32_e32 v10, v7, v10
	v_mul_f32_e32 v3, v5, v3
	v_mul_f32_e32 v10, v11, v10
	v_mul_f32_e32 v6, v216, v3
	v_mul_f32_e32 v12, v220, v10
	v_fma_f32 v3, -v216, v3, v216
	v_fma_f32 v10, -v220, v10, v220
	v_cmp_gt_f32_e32 vcc, 0, v216
	v_cmp_gt_f32_e64 s[96:97], 0, v220
	s_nop 1
	v_cndmask_b32_e32 v216, v3, v6, vcc
	v_cndmask_b32_e64 v220, v10, v12, s[96:97]
	v_mul_f32_e32 v216, v216, v234
	v_mul_f32_e32 v220, v220, v235
	s_nop 0
	v_readlane_b32 s64, v216, 0
	v_readlane_b32 s65, v216, 32
	v_readlane_b32 s66, v216, 16
	v_readlane_b32 s67, v216, 48
	v_readlane_b32 s68, v220, 0
	v_readlane_b32 s69, v220, 32
	v_readlane_b32 s70, v220, 16
	v_readlane_b32 s71, v220, 48
	s_waitcnt vmcnt(60)
	v_cvt_scalef32_pk_f32_fp4 v[160:161], v96, 1.0
	v_cvt_scalef32_pk_f32_fp4 v[162:163], v96, 1.0 op_sel:[1,0,0]
	v_cvt_scalef32_pk_f32_fp4 v[18:19], v96, 1.0 op_sel:[0,1,0]
	v_pk_fma_f32 v[32:33], v[160:161], s[64:65], v[32:33] op_sel_hi:[1,0,1]
	v_cvt_scalef32_pk_f32_fp4 v[20:21], v96, 1.0 op_sel:[1,1,0]
	v_pk_fma_f32 v[34:35], v[162:163], s[64:65], v[34:35] op_sel_hi:[1,0,1]
	v_cvt_scalef32_pk_f32_fp4 v[22:23], v97, 1.0
	v_pk_fma_f32 v[36:37], v[18:19], s[64:65], v[36:37] op_sel_hi:[1,0,1]
	v_cvt_scalef32_pk_f32_fp4 v[30:31], v97, 1.0 op_sel:[1,0,0]
	v_pk_fma_f32 v[38:39], v[20:21], s[64:65], v[38:39] op_sel_hi:[1,0,1]
	v_cvt_scalef32_pk_f32_fp4 v[2:3], v97, 1.0 op_sel:[0,1,0]
	v_pk_fma_f32 v[40:41], v[22:23], s[64:65], v[40:41] op_sel_hi:[1,0,1]
	v_cvt_scalef32_pk_f32_fp4 v[6:7], v97, 1.0 op_sel:[1,1,0]
	v_pk_fma_f32 v[42:43], v[30:31], s[64:65], v[42:43] op_sel_hi:[1,0,1]
	v_cvt_scalef32_pk_f32_fp4 v[160:161], v98, 1.0
	v_pk_fma_f32 v[44:45], v[2:3], s[64:65], v[44:45] op_sel_hi:[1,0,1]
	v_cvt_scalef32_pk_f32_fp4 v[162:163], v98, 1.0 op_sel:[1,0,0]
	v_pk_fma_f32 v[46:47], v[6:7], s[64:65], v[46:47] op_sel_hi:[1,0,1]
	v_cvt_scalef32_pk_f32_fp4 v[18:19], v98, 1.0 op_sel:[0,1,0]
	v_pk_fma_f32 v[48:49], v[160:161], s[64:65], v[48:49] op_sel_hi:[1,0,1]
	v_cvt_scalef32_pk_f32_fp4 v[20:21], v98, 1.0 op_sel:[1,1,0]
	v_pk_fma_f32 v[50:51], v[162:163], s[64:65], v[50:51] op_sel_hi:[1,0,1]
	v_cvt_scalef32_pk_f32_fp4 v[22:23], v99, 1.0
	v_pk_fma_f32 v[52:53], v[18:19], s[64:65], v[52:53] op_sel_hi:[1,0,1]
	v_cvt_scalef32_pk_f32_fp4 v[30:31], v99, 1.0 op_sel:[1,0,0]
	v_pk_fma_f32 v[54:55], v[20:21], s[64:65], v[54:55] op_sel_hi:[1,0,1]
	v_cvt_scalef32_pk_f32_fp4 v[2:3], v99, 1.0 op_sel:[0,1,0]
	v_pk_fma_f32 v[56:57], v[22:23], s[64:65], v[56:57] op_sel_hi:[1,0,1]
	v_cvt_scalef32_pk_f32_fp4 v[6:7], v99, 1.0 op_sel:[1,1,0]
	v_pk_fma_f32 v[58:59], v[30:31], s[64:65], v[58:59] op_sel_hi:[1,0,1]
	v_pk_fma_f32 v[60:61], v[2:3], s[64:65], v[60:61] op_sel_hi:[1,0,1]
	v_pk_fma_f32 v[62:63], v[6:7], s[64:65], v[62:63] op_sel_hi:[1,0,1]
	s_waitcnt vmcnt(56)
	v_cvt_scalef32_pk_f32_fp4 v[160:161], v100, 1.0
	v_cvt_scalef32_pk_f32_fp4 v[162:163], v100, 1.0 op_sel:[1,0,0]
	v_cvt_scalef32_pk_f32_fp4 v[18:19], v100, 1.0 op_sel:[0,1,0]
	v_pk_fma_f32 v[32:33], v[160:161], s[64:65], v[32:33] op_sel:[0,1,0] op_sel_hi:[1,1,1]
	v_cvt_scalef32_pk_f32_fp4 v[20:21], v100, 1.0 op_sel:[1,1,0]
	v_pk_fma_f32 v[34:35], v[162:163], s[64:65], v[34:35] op_sel:[0,1,0] op_sel_hi:[1,1,1]
	v_cvt_scalef32_pk_f32_fp4 v[22:23], v101, 1.0
	v_pk_fma_f32 v[36:37], v[18:19], s[64:65], v[36:37] op_sel:[0,1,0] op_sel_hi:[1,1,1]
	v_cvt_scalef32_pk_f32_fp4 v[30:31], v101, 1.0 op_sel:[1,0,0]
	v_pk_fma_f32 v[38:39], v[20:21], s[64:65], v[38:39] op_sel:[0,1,0] op_sel_hi:[1,1,1]
	v_cvt_scalef32_pk_f32_fp4 v[2:3], v101, 1.0 op_sel:[0,1,0]
	v_pk_fma_f32 v[40:41], v[22:23], s[64:65], v[40:41] op_sel:[0,1,0] op_sel_hi:[1,1,1]
	v_cvt_scalef32_pk_f32_fp4 v[6:7], v101, 1.0 op_sel:[1,1,0]
	v_pk_fma_f32 v[42:43], v[30:31], s[64:65], v[42:43] op_sel:[0,1,0] op_sel_hi:[1,1,1]
	v_cvt_scalef32_pk_f32_fp4 v[160:161], v102, 1.0
	v_pk_fma_f32 v[44:45], v[2:3], s[64:65], v[44:45] op_sel:[0,1,0] op_sel_hi:[1,1,1]
	v_cvt_scalef32_pk_f32_fp4 v[162:163], v102, 1.0 op_sel:[1,0,0]
	v_pk_fma_f32 v[46:47], v[6:7], s[64:65], v[46:47] op_sel:[0,1,0] op_sel_hi:[1,1,1]
	v_cvt_scalef32_pk_f32_fp4 v[18:19], v102, 1.0 op_sel:[0,1,0]
	v_pk_fma_f32 v[48:49], v[160:161], s[64:65], v[48:49] op_sel:[0,1,0] op_sel_hi:[1,1,1]
	v_cvt_scalef32_pk_f32_fp4 v[20:21], v102, 1.0 op_sel:[1,1,0]
	v_pk_fma_f32 v[50:51], v[162:163], s[64:65], v[50:51] op_sel:[0,1,0] op_sel_hi:[1,1,1]
	v_cvt_scalef32_pk_f32_fp4 v[22:23], v103, 1.0
	v_pk_fma_f32 v[52:53], v[18:19], s[64:65], v[52:53] op_sel:[0,1,0] op_sel_hi:[1,1,1]
	v_cvt_scalef32_pk_f32_fp4 v[30:31], v103, 1.0 op_sel:[1,0,0]
	v_pk_fma_f32 v[54:55], v[20:21], s[64:65], v[54:55] op_sel:[0,1,0] op_sel_hi:[1,1,1]
	v_cvt_scalef32_pk_f32_fp4 v[2:3], v103, 1.0 op_sel:[0,1,0]
	v_pk_fma_f32 v[56:57], v[22:23], s[64:65], v[56:57] op_sel:[0,1,0] op_sel_hi:[1,1,1]
	v_cvt_scalef32_pk_f32_fp4 v[6:7], v103, 1.0 op_sel:[1,1,0]
	v_pk_fma_f32 v[58:59], v[30:31], s[64:65], v[58:59] op_sel:[0,1,0] op_sel_hi:[1,1,1]
	v_pk_fma_f32 v[60:61], v[2:3], s[64:65], v[60:61] op_sel:[0,1,0] op_sel_hi:[1,1,1]
	v_pk_fma_f32 v[62:63], v[6:7], s[64:65], v[62:63] op_sel:[0,1,0] op_sel_hi:[1,1,1]
	s_waitcnt vmcnt(52)
	v_cvt_scalef32_pk_f32_fp4 v[160:161], v104, 1.0
	v_cvt_scalef32_pk_f32_fp4 v[162:163], v104, 1.0 op_sel:[1,0,0]
	v_cvt_scalef32_pk_f32_fp4 v[18:19], v104, 1.0 op_sel:[0,1,0]
	v_pk_fma_f32 v[32:33], v[160:161], s[66:67], v[32:33] op_sel_hi:[1,0,1]
	v_cvt_scalef32_pk_f32_fp4 v[20:21], v104, 1.0 op_sel:[1,1,0]
	v_pk_fma_f32 v[34:35], v[162:163], s[66:67], v[34:35] op_sel_hi:[1,0,1]
	v_cvt_scalef32_pk_f32_fp4 v[22:23], v105, 1.0
	v_pk_fma_f32 v[36:37], v[18:19], s[66:67], v[36:37] op_sel_hi:[1,0,1]
	v_cvt_scalef32_pk_f32_fp4 v[30:31], v105, 1.0 op_sel:[1,0,0]
	v_pk_fma_f32 v[38:39], v[20:21], s[66:67], v[38:39] op_sel_hi:[1,0,1]
	v_cvt_scalef32_pk_f32_fp4 v[2:3], v105, 1.0 op_sel:[0,1,0]
	v_pk_fma_f32 v[40:41], v[22:23], s[66:67], v[40:41] op_sel_hi:[1,0,1]
	v_cvt_scalef32_pk_f32_fp4 v[6:7], v105, 1.0 op_sel:[1,1,0]
	v_pk_fma_f32 v[42:43], v[30:31], s[66:67], v[42:43] op_sel_hi:[1,0,1]
	v_cvt_scalef32_pk_f32_fp4 v[160:161], v106, 1.0
	v_pk_fma_f32 v[44:45], v[2:3], s[66:67], v[44:45] op_sel_hi:[1,0,1]
	v_cvt_scalef32_pk_f32_fp4 v[162:163], v106, 1.0 op_sel:[1,0,0]
	v_pk_fma_f32 v[46:47], v[6:7], s[66:67], v[46:47] op_sel_hi:[1,0,1]
	v_cvt_scalef32_pk_f32_fp4 v[18:19], v106, 1.0 op_sel:[0,1,0]
	v_pk_fma_f32 v[48:49], v[160:161], s[66:67], v[48:49] op_sel_hi:[1,0,1]
	v_cvt_scalef32_pk_f32_fp4 v[20:21], v106, 1.0 op_sel:[1,1,0]
	v_pk_fma_f32 v[50:51], v[162:163], s[66:67], v[50:51] op_sel_hi:[1,0,1]
	v_cvt_scalef32_pk_f32_fp4 v[22:23], v107, 1.0
	v_pk_fma_f32 v[52:53], v[18:19], s[66:67], v[52:53] op_sel_hi:[1,0,1]
	v_cvt_scalef32_pk_f32_fp4 v[30:31], v107, 1.0 op_sel:[1,0,0]
	v_pk_fma_f32 v[54:55], v[20:21], s[66:67], v[54:55] op_sel_hi:[1,0,1]
	v_cvt_scalef32_pk_f32_fp4 v[2:3], v107, 1.0 op_sel:[0,1,0]
	v_pk_fma_f32 v[56:57], v[22:23], s[66:67], v[56:57] op_sel_hi:[1,0,1]
	v_cvt_scalef32_pk_f32_fp4 v[6:7], v107, 1.0 op_sel:[1,1,0]
	v_pk_fma_f32 v[58:59], v[30:31], s[66:67], v[58:59] op_sel_hi:[1,0,1]
	v_pk_fma_f32 v[60:61], v[2:3], s[66:67], v[60:61] op_sel_hi:[1,0,1]
	v_pk_fma_f32 v[62:63], v[6:7], s[66:67], v[62:63] op_sel_hi:[1,0,1]
	s_waitcnt vmcnt(48)
	v_cvt_scalef32_pk_f32_fp4 v[160:161], v108, 1.0
	v_cvt_scalef32_pk_f32_fp4 v[162:163], v108, 1.0 op_sel:[1,0,0]
	v_cvt_scalef32_pk_f32_fp4 v[18:19], v108, 1.0 op_sel:[0,1,0]
	v_pk_fma_f32 v[32:33], v[160:161], s[66:67], v[32:33] op_sel:[0,1,0] op_sel_hi:[1,1,1]
	v_cvt_scalef32_pk_f32_fp4 v[20:21], v108, 1.0 op_sel:[1,1,0]
	v_pk_fma_f32 v[34:35], v[162:163], s[66:67], v[34:35] op_sel:[0,1,0] op_sel_hi:[1,1,1]
	v_cvt_scalef32_pk_f32_fp4 v[22:23], v109, 1.0
	v_pk_fma_f32 v[36:37], v[18:19], s[66:67], v[36:37] op_sel:[0,1,0] op_sel_hi:[1,1,1]
	v_cvt_scalef32_pk_f32_fp4 v[30:31], v109, 1.0 op_sel:[1,0,0]
	v_pk_fma_f32 v[38:39], v[20:21], s[66:67], v[38:39] op_sel:[0,1,0] op_sel_hi:[1,1,1]
	v_cvt_scalef32_pk_f32_fp4 v[2:3], v109, 1.0 op_sel:[0,1,0]
	v_pk_fma_f32 v[40:41], v[22:23], s[66:67], v[40:41] op_sel:[0,1,0] op_sel_hi:[1,1,1]
	v_cvt_scalef32_pk_f32_fp4 v[6:7], v109, 1.0 op_sel:[1,1,0]
	v_pk_fma_f32 v[42:43], v[30:31], s[66:67], v[42:43] op_sel:[0,1,0] op_sel_hi:[1,1,1]
	v_cvt_scalef32_pk_f32_fp4 v[160:161], v110, 1.0
	v_pk_fma_f32 v[44:45], v[2:3], s[66:67], v[44:45] op_sel:[0,1,0] op_sel_hi:[1,1,1]
	v_cvt_scalef32_pk_f32_fp4 v[162:163], v110, 1.0 op_sel:[1,0,0]
	v_pk_fma_f32 v[46:47], v[6:7], s[66:67], v[46:47] op_sel:[0,1,0] op_sel_hi:[1,1,1]
	v_cvt_scalef32_pk_f32_fp4 v[18:19], v110, 1.0 op_sel:[0,1,0]
	v_pk_fma_f32 v[48:49], v[160:161], s[66:67], v[48:49] op_sel:[0,1,0] op_sel_hi:[1,1,1]
	v_cvt_scalef32_pk_f32_fp4 v[20:21], v110, 1.0 op_sel:[1,1,0]
	v_pk_fma_f32 v[50:51], v[162:163], s[66:67], v[50:51] op_sel:[0,1,0] op_sel_hi:[1,1,1]
	v_cvt_scalef32_pk_f32_fp4 v[22:23], v111, 1.0
	v_pk_fma_f32 v[52:53], v[18:19], s[66:67], v[52:53] op_sel:[0,1,0] op_sel_hi:[1,1,1]
	v_cvt_scalef32_pk_f32_fp4 v[30:31], v111, 1.0 op_sel:[1,0,0]
	v_pk_fma_f32 v[54:55], v[20:21], s[66:67], v[54:55] op_sel:[0,1,0] op_sel_hi:[1,1,1]
	v_cvt_scalef32_pk_f32_fp4 v[2:3], v111, 1.0 op_sel:[0,1,0]
	v_pk_fma_f32 v[56:57], v[22:23], s[66:67], v[56:57] op_sel:[0,1,0] op_sel_hi:[1,1,1]
	v_cvt_scalef32_pk_f32_fp4 v[6:7], v111, 1.0 op_sel:[1,1,0]
	v_pk_fma_f32 v[58:59], v[30:31], s[66:67], v[58:59] op_sel:[0,1,0] op_sel_hi:[1,1,1]
	v_pk_fma_f32 v[60:61], v[2:3], s[66:67], v[60:61] op_sel:[0,1,0] op_sel_hi:[1,1,1]
	v_pk_fma_f32 v[62:63], v[6:7], s[66:67], v[62:63] op_sel:[0,1,0] op_sel_hi:[1,1,1]
	s_waitcnt vmcnt(44)
	v_cvt_scalef32_pk_f32_fp4 v[160:161], v112, 1.0
	v_cvt_scalef32_pk_f32_fp4 v[162:163], v112, 1.0 op_sel:[1,0,0]
	v_cvt_scalef32_pk_f32_fp4 v[18:19], v112, 1.0 op_sel:[0,1,0]
	v_pk_fma_f32 v[32:33], v[160:161], s[68:69], v[32:33] op_sel_hi:[1,0,1]
	v_cvt_scalef32_pk_f32_fp4 v[20:21], v112, 1.0 op_sel:[1,1,0]
	v_pk_fma_f32 v[34:35], v[162:163], s[68:69], v[34:35] op_sel_hi:[1,0,1]
	v_cvt_scalef32_pk_f32_fp4 v[22:23], v113, 1.0
	v_pk_fma_f32 v[36:37], v[18:19], s[68:69], v[36:37] op_sel_hi:[1,0,1]
	v_cvt_scalef32_pk_f32_fp4 v[30:31], v113, 1.0 op_sel:[1,0,0]
	v_pk_fma_f32 v[38:39], v[20:21], s[68:69], v[38:39] op_sel_hi:[1,0,1]
	v_cvt_scalef32_pk_f32_fp4 v[2:3], v113, 1.0 op_sel:[0,1,0]
	v_pk_fma_f32 v[40:41], v[22:23], s[68:69], v[40:41] op_sel_hi:[1,0,1]
	v_cvt_scalef32_pk_f32_fp4 v[6:7], v113, 1.0 op_sel:[1,1,0]
	v_pk_fma_f32 v[42:43], v[30:31], s[68:69], v[42:43] op_sel_hi:[1,0,1]
	v_cvt_scalef32_pk_f32_fp4 v[160:161], v114, 1.0
	v_pk_fma_f32 v[44:45], v[2:3], s[68:69], v[44:45] op_sel_hi:[1,0,1]
	v_cvt_scalef32_pk_f32_fp4 v[162:163], v114, 1.0 op_sel:[1,0,0]
	v_pk_fma_f32 v[46:47], v[6:7], s[68:69], v[46:47] op_sel_hi:[1,0,1]
	v_cvt_scalef32_pk_f32_fp4 v[18:19], v114, 1.0 op_sel:[0,1,0]
	v_pk_fma_f32 v[48:49], v[160:161], s[68:69], v[48:49] op_sel_hi:[1,0,1]
	v_cvt_scalef32_pk_f32_fp4 v[20:21], v114, 1.0 op_sel:[1,1,0]
	v_pk_fma_f32 v[50:51], v[162:163], s[68:69], v[50:51] op_sel_hi:[1,0,1]
	v_cvt_scalef32_pk_f32_fp4 v[22:23], v115, 1.0
	v_pk_fma_f32 v[52:53], v[18:19], s[68:69], v[52:53] op_sel_hi:[1,0,1]
	v_cvt_scalef32_pk_f32_fp4 v[30:31], v115, 1.0 op_sel:[1,0,0]
	v_pk_fma_f32 v[54:55], v[20:21], s[68:69], v[54:55] op_sel_hi:[1,0,1]
	v_cvt_scalef32_pk_f32_fp4 v[2:3], v115, 1.0 op_sel:[0,1,0]
	v_pk_fma_f32 v[56:57], v[22:23], s[68:69], v[56:57] op_sel_hi:[1,0,1]
	v_cvt_scalef32_pk_f32_fp4 v[6:7], v115, 1.0 op_sel:[1,1,0]
	v_pk_fma_f32 v[58:59], v[30:31], s[68:69], v[58:59] op_sel_hi:[1,0,1]
	v_pk_fma_f32 v[60:61], v[2:3], s[68:69], v[60:61] op_sel_hi:[1,0,1]
	v_pk_fma_f32 v[62:63], v[6:7], s[68:69], v[62:63] op_sel_hi:[1,0,1]
	s_waitcnt vmcnt(40)
	v_cvt_scalef32_pk_f32_fp4 v[160:161], v116, 1.0
	v_cvt_scalef32_pk_f32_fp4 v[162:163], v116, 1.0 op_sel:[1,0,0]
	v_cvt_scalef32_pk_f32_fp4 v[18:19], v116, 1.0 op_sel:[0,1,0]
	v_pk_fma_f32 v[32:33], v[160:161], s[68:69], v[32:33] op_sel:[0,1,0] op_sel_hi:[1,1,1]
	v_cvt_scalef32_pk_f32_fp4 v[20:21], v116, 1.0 op_sel:[1,1,0]
	v_pk_fma_f32 v[34:35], v[162:163], s[68:69], v[34:35] op_sel:[0,1,0] op_sel_hi:[1,1,1]
	v_cvt_scalef32_pk_f32_fp4 v[22:23], v117, 1.0
	v_pk_fma_f32 v[36:37], v[18:19], s[68:69], v[36:37] op_sel:[0,1,0] op_sel_hi:[1,1,1]
	v_cvt_scalef32_pk_f32_fp4 v[30:31], v117, 1.0 op_sel:[1,0,0]
	v_pk_fma_f32 v[38:39], v[20:21], s[68:69], v[38:39] op_sel:[0,1,0] op_sel_hi:[1,1,1]
	v_cvt_scalef32_pk_f32_fp4 v[2:3], v117, 1.0 op_sel:[0,1,0]
	v_pk_fma_f32 v[40:41], v[22:23], s[68:69], v[40:41] op_sel:[0,1,0] op_sel_hi:[1,1,1]
	v_cvt_scalef32_pk_f32_fp4 v[6:7], v117, 1.0 op_sel:[1,1,0]
	v_pk_fma_f32 v[42:43], v[30:31], s[68:69], v[42:43] op_sel:[0,1,0] op_sel_hi:[1,1,1]
	v_cvt_scalef32_pk_f32_fp4 v[160:161], v118, 1.0
	v_pk_fma_f32 v[44:45], v[2:3], s[68:69], v[44:45] op_sel:[0,1,0] op_sel_hi:[1,1,1]
	v_cvt_scalef32_pk_f32_fp4 v[162:163], v118, 1.0 op_sel:[1,0,0]
	v_pk_fma_f32 v[46:47], v[6:7], s[68:69], v[46:47] op_sel:[0,1,0] op_sel_hi:[1,1,1]
	v_cvt_scalef32_pk_f32_fp4 v[18:19], v118, 1.0 op_sel:[0,1,0]
	v_pk_fma_f32 v[48:49], v[160:161], s[68:69], v[48:49] op_sel:[0,1,0] op_sel_hi:[1,1,1]
	v_cvt_scalef32_pk_f32_fp4 v[20:21], v118, 1.0 op_sel:[1,1,0]
	v_pk_fma_f32 v[50:51], v[162:163], s[68:69], v[50:51] op_sel:[0,1,0] op_sel_hi:[1,1,1]
	v_cvt_scalef32_pk_f32_fp4 v[22:23], v119, 1.0
	v_pk_fma_f32 v[52:53], v[18:19], s[68:69], v[52:53] op_sel:[0,1,0] op_sel_hi:[1,1,1]
	v_cvt_scalef32_pk_f32_fp4 v[30:31], v119, 1.0 op_sel:[1,0,0]
	v_pk_fma_f32 v[54:55], v[20:21], s[68:69], v[54:55] op_sel:[0,1,0] op_sel_hi:[1,1,1]
	v_cvt_scalef32_pk_f32_fp4 v[2:3], v119, 1.0 op_sel:[0,1,0]
	v_pk_fma_f32 v[56:57], v[22:23], s[68:69], v[56:57] op_sel:[0,1,0] op_sel_hi:[1,1,1]
	v_cvt_scalef32_pk_f32_fp4 v[6:7], v119, 1.0 op_sel:[1,1,0]
	v_pk_fma_f32 v[58:59], v[30:31], s[68:69], v[58:59] op_sel:[0,1,0] op_sel_hi:[1,1,1]
	v_pk_fma_f32 v[60:61], v[2:3], s[68:69], v[60:61] op_sel:[0,1,0] op_sel_hi:[1,1,1]
	v_pk_fma_f32 v[62:63], v[6:7], s[68:69], v[62:63] op_sel:[0,1,0] op_sel_hi:[1,1,1]
	s_waitcnt vmcnt(36)
	v_cvt_scalef32_pk_f32_fp4 v[160:161], v120, 1.0
	v_cvt_scalef32_pk_f32_fp4 v[162:163], v120, 1.0 op_sel:[1,0,0]
	v_cvt_scalef32_pk_f32_fp4 v[18:19], v120, 1.0 op_sel:[0,1,0]
	v_pk_fma_f32 v[32:33], v[160:161], s[70:71], v[32:33] op_sel_hi:[1,0,1]
	v_cvt_scalef32_pk_f32_fp4 v[20:21], v120, 1.0 op_sel:[1,1,0]
	v_pk_fma_f32 v[34:35], v[162:163], s[70:71], v[34:35] op_sel_hi:[1,0,1]
	v_cvt_scalef32_pk_f32_fp4 v[22:23], v121, 1.0
	v_pk_fma_f32 v[36:37], v[18:19], s[70:71], v[36:37] op_sel_hi:[1,0,1]
	v_cvt_scalef32_pk_f32_fp4 v[30:31], v121, 1.0 op_sel:[1,0,0]
	v_pk_fma_f32 v[38:39], v[20:21], s[70:71], v[38:39] op_sel_hi:[1,0,1]
	v_cvt_scalef32_pk_f32_fp4 v[2:3], v121, 1.0 op_sel:[0,1,0]
	v_pk_fma_f32 v[40:41], v[22:23], s[70:71], v[40:41] op_sel_hi:[1,0,1]
	v_cvt_scalef32_pk_f32_fp4 v[6:7], v121, 1.0 op_sel:[1,1,0]
	v_pk_fma_f32 v[42:43], v[30:31], s[70:71], v[42:43] op_sel_hi:[1,0,1]
	v_cvt_scalef32_pk_f32_fp4 v[160:161], v122, 1.0
	v_pk_fma_f32 v[44:45], v[2:3], s[70:71], v[44:45] op_sel_hi:[1,0,1]
	v_cvt_scalef32_pk_f32_fp4 v[162:163], v122, 1.0 op_sel:[1,0,0]
	v_pk_fma_f32 v[46:47], v[6:7], s[70:71], v[46:47] op_sel_hi:[1,0,1]
	v_cvt_scalef32_pk_f32_fp4 v[18:19], v122, 1.0 op_sel:[0,1,0]
	v_pk_fma_f32 v[48:49], v[160:161], s[70:71], v[48:49] op_sel_hi:[1,0,1]
	v_cvt_scalef32_pk_f32_fp4 v[20:21], v122, 1.0 op_sel:[1,1,0]
	v_pk_fma_f32 v[50:51], v[162:163], s[70:71], v[50:51] op_sel_hi:[1,0,1]
	v_cvt_scalef32_pk_f32_fp4 v[22:23], v123, 1.0
	v_pk_fma_f32 v[52:53], v[18:19], s[70:71], v[52:53] op_sel_hi:[1,0,1]
	v_cvt_scalef32_pk_f32_fp4 v[30:31], v123, 1.0 op_sel:[1,0,0]
	v_pk_fma_f32 v[54:55], v[20:21], s[70:71], v[54:55] op_sel_hi:[1,0,1]
	v_cvt_scalef32_pk_f32_fp4 v[2:3], v123, 1.0 op_sel:[0,1,0]
	v_pk_fma_f32 v[56:57], v[22:23], s[70:71], v[56:57] op_sel_hi:[1,0,1]
	v_cvt_scalef32_pk_f32_fp4 v[6:7], v123, 1.0 op_sel:[1,1,0]
	v_pk_fma_f32 v[58:59], v[30:31], s[70:71], v[58:59] op_sel_hi:[1,0,1]
	v_pk_fma_f32 v[60:61], v[2:3], s[70:71], v[60:61] op_sel_hi:[1,0,1]
	v_pk_fma_f32 v[62:63], v[6:7], s[70:71], v[62:63] op_sel_hi:[1,0,1]
	s_waitcnt vmcnt(32)
	v_cvt_scalef32_pk_f32_fp4 v[160:161], v124, 1.0
	v_cvt_scalef32_pk_f32_fp4 v[162:163], v124, 1.0 op_sel:[1,0,0]
	v_cvt_scalef32_pk_f32_fp4 v[18:19], v124, 1.0 op_sel:[0,1,0]
	v_pk_fma_f32 v[32:33], v[160:161], s[70:71], v[32:33] op_sel:[0,1,0] op_sel_hi:[1,1,1]
	v_cvt_scalef32_pk_f32_fp4 v[20:21], v124, 1.0 op_sel:[1,1,0]
	v_pk_fma_f32 v[34:35], v[162:163], s[70:71], v[34:35] op_sel:[0,1,0] op_sel_hi:[1,1,1]
	v_cvt_scalef32_pk_f32_fp4 v[22:23], v125, 1.0
	v_pk_fma_f32 v[36:37], v[18:19], s[70:71], v[36:37] op_sel:[0,1,0] op_sel_hi:[1,1,1]
	v_cvt_scalef32_pk_f32_fp4 v[30:31], v125, 1.0 op_sel:[1,0,0]
	v_pk_fma_f32 v[38:39], v[20:21], s[70:71], v[38:39] op_sel:[0,1,0] op_sel_hi:[1,1,1]
	v_cvt_scalef32_pk_f32_fp4 v[2:3], v125, 1.0 op_sel:[0,1,0]
	v_pk_fma_f32 v[40:41], v[22:23], s[70:71], v[40:41] op_sel:[0,1,0] op_sel_hi:[1,1,1]
	v_cvt_scalef32_pk_f32_fp4 v[6:7], v125, 1.0 op_sel:[1,1,0]
	v_pk_fma_f32 v[42:43], v[30:31], s[70:71], v[42:43] op_sel:[0,1,0] op_sel_hi:[1,1,1]
	v_cvt_scalef32_pk_f32_fp4 v[160:161], v126, 1.0
	v_pk_fma_f32 v[44:45], v[2:3], s[70:71], v[44:45] op_sel:[0,1,0] op_sel_hi:[1,1,1]
	v_cvt_scalef32_pk_f32_fp4 v[162:163], v126, 1.0 op_sel:[1,0,0]
	v_pk_fma_f32 v[46:47], v[6:7], s[70:71], v[46:47] op_sel:[0,1,0] op_sel_hi:[1,1,1]
	v_cvt_scalef32_pk_f32_fp4 v[18:19], v126, 1.0 op_sel:[0,1,0]
	v_pk_fma_f32 v[48:49], v[160:161], s[70:71], v[48:49] op_sel:[0,1,0] op_sel_hi:[1,1,1]
	v_cvt_scalef32_pk_f32_fp4 v[20:21], v126, 1.0 op_sel:[1,1,0]
	v_pk_fma_f32 v[50:51], v[162:163], s[70:71], v[50:51] op_sel:[0,1,0] op_sel_hi:[1,1,1]
	v_cvt_scalef32_pk_f32_fp4 v[22:23], v127, 1.0
	v_pk_fma_f32 v[52:53], v[18:19], s[70:71], v[52:53] op_sel:[0,1,0] op_sel_hi:[1,1,1]
	v_cvt_scalef32_pk_f32_fp4 v[30:31], v127, 1.0 op_sel:[1,0,0]
	v_pk_fma_f32 v[54:55], v[20:21], s[70:71], v[54:55] op_sel:[0,1,0] op_sel_hi:[1,1,1]
	v_cvt_scalef32_pk_f32_fp4 v[2:3], v127, 1.0 op_sel:[0,1,0]
	v_pk_fma_f32 v[56:57], v[22:23], s[70:71], v[56:57] op_sel:[0,1,0] op_sel_hi:[1,1,1]
	v_cvt_scalef32_pk_f32_fp4 v[6:7], v127, 1.0 op_sel:[1,1,0]
	v_pk_fma_f32 v[58:59], v[30:31], s[70:71], v[58:59] op_sel:[0,1,0] op_sel_hi:[1,1,1]
	v_pk_fma_f32 v[60:61], v[2:3], s[70:71], v[60:61] op_sel:[0,1,0] op_sel_hi:[1,1,1]
	v_pk_fma_f32 v[62:63], v[6:7], s[70:71], v[62:63] op_sel:[0,1,0] op_sel_hi:[1,1,1]
	ds_read_b32 v232, v26
	ds_read_b32 v233, v27
	ds_read_b32 v234, v26 offset:512
	ds_read_b32 v235, v27 offset:512
	v_add_u32_e32 v26, 32, v26
	v_add_u32_e32 v27, 32, v27
	s_waitcnt vmcnt(30)
	v_mov_b32_e32 v216, 0
	v_mov_b32_e32 v224, 0
	v_dot8c_i32_i4_e32 v216, v128, v208
	v_dot8c_i32_i4_e32 v224, v128, v212
	v_dot8c_i32_i4_e32 v216, v129, v209
	v_dot8c_i32_i4_e32 v224, v129, v213
	v_dot8c_i32_i4_e32 v216, v130, v210
	v_dot8c_i32_i4_e32 v224, v130, v214
	v_dot8c_i32_i4_e32 v216, v131, v211
	v_dot8c_i32_i4_e32 v224, v131, v215
	s_waitcnt vmcnt(26)
	v_mov_b32_e32 v217, 0
	v_mov_b32_e32 v225, 0
	v_dot8c_i32_i4_e32 v217, v132, v208
	v_dot8c_i32_i4_e32 v225, v132, v212
	v_dot8c_i32_i4_e32 v217, v133, v209
	v_dot8c_i32_i4_e32 v225, v133, v213
	v_dot8c_i32_i4_e32 v217, v134, v210
	v_dot8c_i32_i4_e32 v225, v134, v214
	v_dot8c_i32_i4_e32 v217, v135, v211
	v_dot8c_i32_i4_e32 v225, v135, v215
	s_waitcnt vmcnt(22)
	v_mov_b32_e32 v218, 0
	v_mov_b32_e32 v226, 0
	v_dot8c_i32_i4_e32 v218, v136, v208
	v_dot8c_i32_i4_e32 v226, v136, v212
	v_dot8c_i32_i4_e32 v218, v137, v209
	v_dot8c_i32_i4_e32 v226, v137, v213
	v_dot8c_i32_i4_e32 v218, v138, v210
	v_dot8c_i32_i4_e32 v226, v138, v214
	v_dot8c_i32_i4_e32 v218, v139, v211
	v_dot8c_i32_i4_e32 v226, v139, v215
	s_waitcnt vmcnt(18)
	v_mov_b32_e32 v219, 0
	v_mov_b32_e32 v227, 0
	v_dot8c_i32_i4_e32 v219, v140, v208
	v_dot8c_i32_i4_e32 v227, v140, v212
	v_dot8c_i32_i4_e32 v219, v141, v209
	v_dot8c_i32_i4_e32 v227, v141, v213
	v_dot8c_i32_i4_e32 v219, v142, v210
	v_dot8c_i32_i4_e32 v227, v142, v214
	v_dot8c_i32_i4_e32 v219, v143, v211
	v_dot8c_i32_i4_e32 v227, v143, v215
	s_waitcnt vmcnt(14)
	v_mov_b32_e32 v220, 0
	v_mov_b32_e32 v228, 0
	v_dot8c_i32_i4_e32 v220, v144, v208
	v_dot8c_i32_i4_e32 v228, v144, v212
	v_dot8c_i32_i4_e32 v220, v145, v209
	v_dot8c_i32_i4_e32 v228, v145, v213
	v_dot8c_i32_i4_e32 v220, v146, v210
	v_dot8c_i32_i4_e32 v228, v146, v214
	v_dot8c_i32_i4_e32 v220, v147, v211
	v_dot8c_i32_i4_e32 v228, v147, v215
	s_waitcnt vmcnt(10)
	v_mov_b32_e32 v221, 0
	v_mov_b32_e32 v229, 0
	v_dot8c_i32_i4_e32 v221, v148, v208
	v_dot8c_i32_i4_e32 v229, v148, v212
	v_dot8c_i32_i4_e32 v221, v149, v209
	v_dot8c_i32_i4_e32 v229, v149, v213
	v_dot8c_i32_i4_e32 v221, v150, v210
	v_dot8c_i32_i4_e32 v229, v150, v214
	v_dot8c_i32_i4_e32 v221, v151, v211
	v_dot8c_i32_i4_e32 v229, v151, v215
	s_waitcnt vmcnt(6)
	v_mov_b32_e32 v222, 0
	v_mov_b32_e32 v230, 0
	v_dot8c_i32_i4_e32 v222, v152, v208
	v_dot8c_i32_i4_e32 v230, v152, v212
	v_dot8c_i32_i4_e32 v222, v153, v209
	v_dot8c_i32_i4_e32 v230, v153, v213
	v_dot8c_i32_i4_e32 v222, v154, v210
	v_dot8c_i32_i4_e32 v230, v154, v214
	v_dot8c_i32_i4_e32 v222, v155, v211
	v_dot8c_i32_i4_e32 v230, v155, v215
	s_waitcnt vmcnt(2)
	v_mov_b32_e32 v223, 0
	v_mov_b32_e32 v231, 0
	v_dot8c_i32_i4_e32 v223, v156, v208
	v_dot8c_i32_i4_e32 v231, v156, v212
	v_dot8c_i32_i4_e32 v223, v157, v209
	v_dot8c_i32_i4_e32 v231, v157, v213
	v_dot8c_i32_i4_e32 v223, v158, v210
	v_dot8c_i32_i4_e32 v231, v158, v214
	v_dot8c_i32_i4_e32 v223, v159, v211
	v_dot8c_i32_i4_e32 v231, v159, v215
	s_nop 2
	v_mad_i32_i24 v216, v216, 14, v224
	v_mad_i32_i24 v217, v217, 14, v225
	v_mad_i32_i24 v218, v218, 14, v226
	v_mad_i32_i24 v219, v219, 14, v227
	v_mad_i32_i24 v220, v220, 14, v228
	v_mad_i32_i24 v221, v221, 14, v229
	v_mad_i32_i24 v222, v222, 14, v230
	v_mad_i32_i24 v223, v223, 14, v231
	s_nop 1
	v_permlane32_swap_b32_e32 v216, v217
	v_permlane32_swap_b32_e32 v218, v219
	v_permlane32_swap_b32_e32 v220, v221
	v_permlane32_swap_b32_e32 v222, v223
	v_add_u32_e32 v216, v216, v217
	v_add_u32_e32 v218, v218, v219
	v_add_u32_e32 v220, v220, v221
	v_add_u32_e32 v222, v222, v223
	s_nop 1
	v_permlane16_swap_b32_e32 v216, v218
	v_permlane16_swap_b32_e32 v220, v222
	v_add_u32_e32 v216, v216, v218
	v_add_u32_e32 v220, v220, v222
	s_nop 1
	v_add_u32_dpp v216, v216, v216 row_ror:8 row_mask:0xf bank_mask:0xf
	v_add_u32_dpp v220, v220, v220 row_ror:8 row_mask:0xf bank_mask:0xf
	s_nop 1
	v_add_u32_dpp v216, v216, v216 row_ror:4 row_mask:0xf bank_mask:0xf
	v_add_u32_dpp v220, v220, v220 row_ror:4 row_mask:0xf bank_mask:0xf
	s_nop 1
	v_add_u32_dpp v216, v216, v216 row_ror:2 row_mask:0xf bank_mask:0xf
	v_add_u32_dpp v220, v220, v220 row_ror:2 row_mask:0xf bank_mask:0xf
	s_nop 1
	v_add_u32_dpp v216, v216, v216 row_ror:1 row_mask:0xf bank_mask:0xf
	v_add_u32_dpp v220, v220, v220 row_ror:1 row_mask:0xf bank_mask:0xf
	s_waitcnt lgkmcnt(0)
	v_cvt_f32_i32_e32 v216, v216
	v_cvt_f32_i32_e32 v220, v220
	v_mul_f32_e32 v216, v216, v232
	v_mul_f32_e32 v220, v220, v233
	v_fma_f32 v2, |v216|, s83, 1.0
	v_fma_f32 v7, |v220|, s83, 1.0
	v_rcp_f32_e32 v2, v2
	v_rcp_f32_e32 v7, v7
	v_mul_f32_e32 v5, v216, v216
	v_mul_f32_e32 v11, v220, v220
	v_mul_f32_e32 v5, 0xbf38aa3b, v5
	v_mul_f32_e32 v11, 0xbf38aa3b, v11
	v_exp_f32_e32 v5, v5
	v_exp_f32_e32 v11, v11
	v_fmamk_f32 v3, v2, 0x3f07dc22, v172
	v_fmamk_f32 v10, v7, 0x3f07dc22, v172
	v_fmaak_f32 v3, v2, v3, 0x3f35f0e3
	v_fmaak_f32 v10, v7, v10, 0x3f35f0e3
	v_fmaak_f32 v3, v2, v3, 0xbe11a98e
	v_fmaak_f32 v10, v7, v10, 0xbe11a98e
	v_fmaak_f32 v3, v2, v3, 0x3e027906
	v_fmaak_f32 v10, v7, v10, 0x3e027906
	v_mul_f32_e32 v3, v2, v3
	v_mul_f32_e32 v10, v7, v10
	v_mul_f32_e32 v3, v5, v3
	v_mul_f32_e32 v10, v11, v10
	v_mul_f32_e32 v6, v216, v3
	v_mul_f32_e32 v12, v220, v10
	v_fma_f32 v3, -v216, v3, v216
	v_fma_f32 v10, -v220, v10, v220
	v_cmp_gt_f32_e32 vcc, 0, v216
	v_cmp_gt_f32_e64 s[96:97], 0, v220
	s_nop 1
	v_cndmask_b32_e32 v216, v3, v6, vcc
	v_cndmask_b32_e64 v220, v10, v12, s[96:97]
	v_mul_f32_e32 v216, v216, v234
	v_mul_f32_e32 v220, v220, v235
	s_nop 0
	v_readlane_b32 s64, v216, 0
	v_readlane_b32 s65, v216, 32
	v_readlane_b32 s66, v216, 16
	v_readlane_b32 s67, v216, 48
	v_readlane_b32 s68, v220, 0
	v_readlane_b32 s69, v220, 32
	v_readlane_b32 s70, v220, 16
	v_readlane_b32 s71, v220, 48
	s_waitcnt vmcnt(28)
	v_cvt_scalef32_pk_f32_fp4 v[160:161], v176, 1.0
	v_cvt_scalef32_pk_f32_fp4 v[162:163], v176, 1.0 op_sel:[1,0,0]
	v_cvt_scalef32_pk_f32_fp4 v[18:19], v176, 1.0 op_sel:[0,1,0]
	v_pk_fma_f32 v[32:33], v[160:161], s[64:65], v[32:33] op_sel_hi:[1,0,1]
	v_cvt_scalef32_pk_f32_fp4 v[20:21], v176, 1.0 op_sel:[1,1,0]
	v_pk_fma_f32 v[34:35], v[162:163], s[64:65], v[34:35] op_sel_hi:[1,0,1]
	v_cvt_scalef32_pk_f32_fp4 v[22:23], v177, 1.0
	v_pk_fma_f32 v[36:37], v[18:19], s[64:65], v[36:37] op_sel_hi:[1,0,1]
	v_cvt_scalef32_pk_f32_fp4 v[30:31], v177, 1.0 op_sel:[1,0,0]
	v_pk_fma_f32 v[38:39], v[20:21], s[64:65], v[38:39] op_sel_hi:[1,0,1]
	v_cvt_scalef32_pk_f32_fp4 v[2:3], v177, 1.0 op_sel:[0,1,0]
	v_pk_fma_f32 v[40:41], v[22:23], s[64:65], v[40:41] op_sel_hi:[1,0,1]
	v_cvt_scalef32_pk_f32_fp4 v[6:7], v177, 1.0 op_sel:[1,1,0]
	v_pk_fma_f32 v[42:43], v[30:31], s[64:65], v[42:43] op_sel_hi:[1,0,1]
	v_cvt_scalef32_pk_f32_fp4 v[160:161], v178, 1.0
	v_pk_fma_f32 v[44:45], v[2:3], s[64:65], v[44:45] op_sel_hi:[1,0,1]
	v_cvt_scalef32_pk_f32_fp4 v[162:163], v178, 1.0 op_sel:[1,0,0]
	v_pk_fma_f32 v[46:47], v[6:7], s[64:65], v[46:47] op_sel_hi:[1,0,1]
	v_cvt_scalef32_pk_f32_fp4 v[18:19], v178, 1.0 op_sel:[0,1,0]
	v_pk_fma_f32 v[48:49], v[160:161], s[64:65], v[48:49] op_sel_hi:[1,0,1]
	v_cvt_scalef32_pk_f32_fp4 v[20:21], v178, 1.0 op_sel:[1,1,0]
	v_pk_fma_f32 v[50:51], v[162:163], s[64:65], v[50:51] op_sel_hi:[1,0,1]
	v_cvt_scalef32_pk_f32_fp4 v[22:23], v179, 1.0
	v_pk_fma_f32 v[52:53], v[18:19], s[64:65], v[52:53] op_sel_hi:[1,0,1]
	v_cvt_scalef32_pk_f32_fp4 v[30:31], v179, 1.0 op_sel:[1,0,0]
	v_pk_fma_f32 v[54:55], v[20:21], s[64:65], v[54:55] op_sel_hi:[1,0,1]
	v_cvt_scalef32_pk_f32_fp4 v[2:3], v179, 1.0 op_sel:[0,1,0]
	v_pk_fma_f32 v[56:57], v[22:23], s[64:65], v[56:57] op_sel_hi:[1,0,1]
	v_cvt_scalef32_pk_f32_fp4 v[6:7], v179, 1.0 op_sel:[1,1,0]
	v_pk_fma_f32 v[58:59], v[30:31], s[64:65], v[58:59] op_sel_hi:[1,0,1]
	v_pk_fma_f32 v[60:61], v[2:3], s[64:65], v[60:61] op_sel_hi:[1,0,1]
	v_pk_fma_f32 v[62:63], v[6:7], s[64:65], v[62:63] op_sel_hi:[1,0,1]
	s_waitcnt vmcnt(24)
	v_cvt_scalef32_pk_f32_fp4 v[160:161], v180, 1.0
	v_cvt_scalef32_pk_f32_fp4 v[162:163], v180, 1.0 op_sel:[1,0,0]
	v_cvt_scalef32_pk_f32_fp4 v[18:19], v180, 1.0 op_sel:[0,1,0]
	v_pk_fma_f32 v[32:33], v[160:161], s[64:65], v[32:33] op_sel:[0,1,0] op_sel_hi:[1,1,1]
	v_cvt_scalef32_pk_f32_fp4 v[20:21], v180, 1.0 op_sel:[1,1,0]
	v_pk_fma_f32 v[34:35], v[162:163], s[64:65], v[34:35] op_sel:[0,1,0] op_sel_hi:[1,1,1]
	v_cvt_scalef32_pk_f32_fp4 v[22:23], v181, 1.0
	v_pk_fma_f32 v[36:37], v[18:19], s[64:65], v[36:37] op_sel:[0,1,0] op_sel_hi:[1,1,1]
	v_cvt_scalef32_pk_f32_fp4 v[30:31], v181, 1.0 op_sel:[1,0,0]
	v_pk_fma_f32 v[38:39], v[20:21], s[64:65], v[38:39] op_sel:[0,1,0] op_sel_hi:[1,1,1]
	v_cvt_scalef32_pk_f32_fp4 v[2:3], v181, 1.0 op_sel:[0,1,0]
	v_pk_fma_f32 v[40:41], v[22:23], s[64:65], v[40:41] op_sel:[0,1,0] op_sel_hi:[1,1,1]
	v_cvt_scalef32_pk_f32_fp4 v[6:7], v181, 1.0 op_sel:[1,1,0]
	v_pk_fma_f32 v[42:43], v[30:31], s[64:65], v[42:43] op_sel:[0,1,0] op_sel_hi:[1,1,1]
	v_cvt_scalef32_pk_f32_fp4 v[160:161], v182, 1.0
	v_pk_fma_f32 v[44:45], v[2:3], s[64:65], v[44:45] op_sel:[0,1,0] op_sel_hi:[1,1,1]
	v_cvt_scalef32_pk_f32_fp4 v[162:163], v182, 1.0 op_sel:[1,0,0]
	v_pk_fma_f32 v[46:47], v[6:7], s[64:65], v[46:47] op_sel:[0,1,0] op_sel_hi:[1,1,1]
	v_cvt_scalef32_pk_f32_fp4 v[18:19], v182, 1.0 op_sel:[0,1,0]
	v_pk_fma_f32 v[48:49], v[160:161], s[64:65], v[48:49] op_sel:[0,1,0] op_sel_hi:[1,1,1]
	v_cvt_scalef32_pk_f32_fp4 v[20:21], v182, 1.0 op_sel:[1,1,0]
	v_pk_fma_f32 v[50:51], v[162:163], s[64:65], v[50:51] op_sel:[0,1,0] op_sel_hi:[1,1,1]
	v_cvt_scalef32_pk_f32_fp4 v[22:23], v183, 1.0
	v_pk_fma_f32 v[52:53], v[18:19], s[64:65], v[52:53] op_sel:[0,1,0] op_sel_hi:[1,1,1]
	v_cvt_scalef32_pk_f32_fp4 v[30:31], v183, 1.0 op_sel:[1,0,0]
	v_pk_fma_f32 v[54:55], v[20:21], s[64:65], v[54:55] op_sel:[0,1,0] op_sel_hi:[1,1,1]
	v_cvt_scalef32_pk_f32_fp4 v[2:3], v183, 1.0 op_sel:[0,1,0]
	v_pk_fma_f32 v[56:57], v[22:23], s[64:65], v[56:57] op_sel:[0,1,0] op_sel_hi:[1,1,1]
	v_cvt_scalef32_pk_f32_fp4 v[6:7], v183, 1.0 op_sel:[1,1,0]
	v_pk_fma_f32 v[58:59], v[30:31], s[64:65], v[58:59] op_sel:[0,1,0] op_sel_hi:[1,1,1]
	v_pk_fma_f32 v[60:61], v[2:3], s[64:65], v[60:61] op_sel:[0,1,0] op_sel_hi:[1,1,1]
	v_pk_fma_f32 v[62:63], v[6:7], s[64:65], v[62:63] op_sel:[0,1,0] op_sel_hi:[1,1,1]
	s_waitcnt vmcnt(20)
	v_cvt_scalef32_pk_f32_fp4 v[160:161], v184, 1.0
	v_cvt_scalef32_pk_f32_fp4 v[162:163], v184, 1.0 op_sel:[1,0,0]
	v_cvt_scalef32_pk_f32_fp4 v[18:19], v184, 1.0 op_sel:[0,1,0]
	v_pk_fma_f32 v[32:33], v[160:161], s[66:67], v[32:33] op_sel_hi:[1,0,1]
	v_cvt_scalef32_pk_f32_fp4 v[20:21], v184, 1.0 op_sel:[1,1,0]
	v_pk_fma_f32 v[34:35], v[162:163], s[66:67], v[34:35] op_sel_hi:[1,0,1]
	v_cvt_scalef32_pk_f32_fp4 v[22:23], v185, 1.0
	v_pk_fma_f32 v[36:37], v[18:19], s[66:67], v[36:37] op_sel_hi:[1,0,1]
	v_cvt_scalef32_pk_f32_fp4 v[30:31], v185, 1.0 op_sel:[1,0,0]
	v_pk_fma_f32 v[38:39], v[20:21], s[66:67], v[38:39] op_sel_hi:[1,0,1]
	v_cvt_scalef32_pk_f32_fp4 v[2:3], v185, 1.0 op_sel:[0,1,0]
	v_pk_fma_f32 v[40:41], v[22:23], s[66:67], v[40:41] op_sel_hi:[1,0,1]
	v_cvt_scalef32_pk_f32_fp4 v[6:7], v185, 1.0 op_sel:[1,1,0]
	v_pk_fma_f32 v[42:43], v[30:31], s[66:67], v[42:43] op_sel_hi:[1,0,1]
	v_cvt_scalef32_pk_f32_fp4 v[160:161], v186, 1.0
	v_pk_fma_f32 v[44:45], v[2:3], s[66:67], v[44:45] op_sel_hi:[1,0,1]
	v_cvt_scalef32_pk_f32_fp4 v[162:163], v186, 1.0 op_sel:[1,0,0]
	v_pk_fma_f32 v[46:47], v[6:7], s[66:67], v[46:47] op_sel_hi:[1,0,1]
	v_cvt_scalef32_pk_f32_fp4 v[18:19], v186, 1.0 op_sel:[0,1,0]
	v_pk_fma_f32 v[48:49], v[160:161], s[66:67], v[48:49] op_sel_hi:[1,0,1]
	v_cvt_scalef32_pk_f32_fp4 v[20:21], v186, 1.0 op_sel:[1,1,0]
	v_pk_fma_f32 v[50:51], v[162:163], s[66:67], v[50:51] op_sel_hi:[1,0,1]
	v_cvt_scalef32_pk_f32_fp4 v[22:23], v187, 1.0
	v_pk_fma_f32 v[52:53], v[18:19], s[66:67], v[52:53] op_sel_hi:[1,0,1]
	v_cvt_scalef32_pk_f32_fp4 v[30:31], v187, 1.0 op_sel:[1,0,0]
	v_pk_fma_f32 v[54:55], v[20:21], s[66:67], v[54:55] op_sel_hi:[1,0,1]
	v_cvt_scalef32_pk_f32_fp4 v[2:3], v187, 1.0 op_sel:[0,1,0]
	v_pk_fma_f32 v[56:57], v[22:23], s[66:67], v[56:57] op_sel_hi:[1,0,1]
	v_cvt_scalef32_pk_f32_fp4 v[6:7], v187, 1.0 op_sel:[1,1,0]
	v_pk_fma_f32 v[58:59], v[30:31], s[66:67], v[58:59] op_sel_hi:[1,0,1]
	v_pk_fma_f32 v[60:61], v[2:3], s[66:67], v[60:61] op_sel_hi:[1,0,1]
	v_pk_fma_f32 v[62:63], v[6:7], s[66:67], v[62:63] op_sel_hi:[1,0,1]
	s_waitcnt vmcnt(16)
	v_cvt_scalef32_pk_f32_fp4 v[160:161], v188, 1.0
	v_cvt_scalef32_pk_f32_fp4 v[162:163], v188, 1.0 op_sel:[1,0,0]
	v_cvt_scalef32_pk_f32_fp4 v[18:19], v188, 1.0 op_sel:[0,1,0]
	v_pk_fma_f32 v[32:33], v[160:161], s[66:67], v[32:33] op_sel:[0,1,0] op_sel_hi:[1,1,1]
	v_cvt_scalef32_pk_f32_fp4 v[20:21], v188, 1.0 op_sel:[1,1,0]
	v_pk_fma_f32 v[34:35], v[162:163], s[66:67], v[34:35] op_sel:[0,1,0] op_sel_hi:[1,1,1]
	v_cvt_scalef32_pk_f32_fp4 v[22:23], v189, 1.0
	v_pk_fma_f32 v[36:37], v[18:19], s[66:67], v[36:37] op_sel:[0,1,0] op_sel_hi:[1,1,1]
	v_cvt_scalef32_pk_f32_fp4 v[30:31], v189, 1.0 op_sel:[1,0,0]
	v_pk_fma_f32 v[38:39], v[20:21], s[66:67], v[38:39] op_sel:[0,1,0] op_sel_hi:[1,1,1]
	v_cvt_scalef32_pk_f32_fp4 v[2:3], v189, 1.0 op_sel:[0,1,0]
	v_pk_fma_f32 v[40:41], v[22:23], s[66:67], v[40:41] op_sel:[0,1,0] op_sel_hi:[1,1,1]
	v_cvt_scalef32_pk_f32_fp4 v[6:7], v189, 1.0 op_sel:[1,1,0]
	v_pk_fma_f32 v[42:43], v[30:31], s[66:67], v[42:43] op_sel:[0,1,0] op_sel_hi:[1,1,1]
	v_cvt_scalef32_pk_f32_fp4 v[160:161], v190, 1.0
	v_pk_fma_f32 v[44:45], v[2:3], s[66:67], v[44:45] op_sel:[0,1,0] op_sel_hi:[1,1,1]
	v_cvt_scalef32_pk_f32_fp4 v[162:163], v190, 1.0 op_sel:[1,0,0]
	v_pk_fma_f32 v[46:47], v[6:7], s[66:67], v[46:47] op_sel:[0,1,0] op_sel_hi:[1,1,1]
	v_cvt_scalef32_pk_f32_fp4 v[18:19], v190, 1.0 op_sel:[0,1,0]
	v_pk_fma_f32 v[48:49], v[160:161], s[66:67], v[48:49] op_sel:[0,1,0] op_sel_hi:[1,1,1]
	v_cvt_scalef32_pk_f32_fp4 v[20:21], v190, 1.0 op_sel:[1,1,0]
	v_pk_fma_f32 v[50:51], v[162:163], s[66:67], v[50:51] op_sel:[0,1,0] op_sel_hi:[1,1,1]
	v_cvt_scalef32_pk_f32_fp4 v[22:23], v191, 1.0
	v_pk_fma_f32 v[52:53], v[18:19], s[66:67], v[52:53] op_sel:[0,1,0] op_sel_hi:[1,1,1]
	v_cvt_scalef32_pk_f32_fp4 v[30:31], v191, 1.0 op_sel:[1,0,0]
	v_pk_fma_f32 v[54:55], v[20:21], s[66:67], v[54:55] op_sel:[0,1,0] op_sel_hi:[1,1,1]
	v_cvt_scalef32_pk_f32_fp4 v[2:3], v191, 1.0 op_sel:[0,1,0]
	v_pk_fma_f32 v[56:57], v[22:23], s[66:67], v[56:57] op_sel:[0,1,0] op_sel_hi:[1,1,1]
	v_cvt_scalef32_pk_f32_fp4 v[6:7], v191, 1.0 op_sel:[1,1,0]
	v_pk_fma_f32 v[58:59], v[30:31], s[66:67], v[58:59] op_sel:[0,1,0] op_sel_hi:[1,1,1]
	v_pk_fma_f32 v[60:61], v[2:3], s[66:67], v[60:61] op_sel:[0,1,0] op_sel_hi:[1,1,1]
	v_pk_fma_f32 v[62:63], v[6:7], s[66:67], v[62:63] op_sel:[0,1,0] op_sel_hi:[1,1,1]
	s_waitcnt vmcnt(12)
	v_cvt_scalef32_pk_f32_fp4 v[160:161], v192, 1.0
	v_cvt_scalef32_pk_f32_fp4 v[162:163], v192, 1.0 op_sel:[1,0,0]
	v_cvt_scalef32_pk_f32_fp4 v[18:19], v192, 1.0 op_sel:[0,1,0]
	v_pk_fma_f32 v[32:33], v[160:161], s[68:69], v[32:33] op_sel_hi:[1,0,1]
	v_cvt_scalef32_pk_f32_fp4 v[20:21], v192, 1.0 op_sel:[1,1,0]
	v_pk_fma_f32 v[34:35], v[162:163], s[68:69], v[34:35] op_sel_hi:[1,0,1]
	v_cvt_scalef32_pk_f32_fp4 v[22:23], v193, 1.0
	v_pk_fma_f32 v[36:37], v[18:19], s[68:69], v[36:37] op_sel_hi:[1,0,1]
	v_cvt_scalef32_pk_f32_fp4 v[30:31], v193, 1.0 op_sel:[1,0,0]
	v_pk_fma_f32 v[38:39], v[20:21], s[68:69], v[38:39] op_sel_hi:[1,0,1]
	v_cvt_scalef32_pk_f32_fp4 v[2:3], v193, 1.0 op_sel:[0,1,0]
	v_pk_fma_f32 v[40:41], v[22:23], s[68:69], v[40:41] op_sel_hi:[1,0,1]
	v_cvt_scalef32_pk_f32_fp4 v[6:7], v193, 1.0 op_sel:[1,1,0]
	v_pk_fma_f32 v[42:43], v[30:31], s[68:69], v[42:43] op_sel_hi:[1,0,1]
	v_cvt_scalef32_pk_f32_fp4 v[160:161], v194, 1.0
	v_pk_fma_f32 v[44:45], v[2:3], s[68:69], v[44:45] op_sel_hi:[1,0,1]
	v_cvt_scalef32_pk_f32_fp4 v[162:163], v194, 1.0 op_sel:[1,0,0]
	v_pk_fma_f32 v[46:47], v[6:7], s[68:69], v[46:47] op_sel_hi:[1,0,1]
	v_cvt_scalef32_pk_f32_fp4 v[18:19], v194, 1.0 op_sel:[0,1,0]
	v_pk_fma_f32 v[48:49], v[160:161], s[68:69], v[48:49] op_sel_hi:[1,0,1]
	v_cvt_scalef32_pk_f32_fp4 v[20:21], v194, 1.0 op_sel:[1,1,0]
	v_pk_fma_f32 v[50:51], v[162:163], s[68:69], v[50:51] op_sel_hi:[1,0,1]
	v_cvt_scalef32_pk_f32_fp4 v[22:23], v195, 1.0
	v_pk_fma_f32 v[52:53], v[18:19], s[68:69], v[52:53] op_sel_hi:[1,0,1]
	v_cvt_scalef32_pk_f32_fp4 v[30:31], v195, 1.0 op_sel:[1,0,0]
	v_pk_fma_f32 v[54:55], v[20:21], s[68:69], v[54:55] op_sel_hi:[1,0,1]
	v_cvt_scalef32_pk_f32_fp4 v[2:3], v195, 1.0 op_sel:[0,1,0]
	v_pk_fma_f32 v[56:57], v[22:23], s[68:69], v[56:57] op_sel_hi:[1,0,1]
	v_cvt_scalef32_pk_f32_fp4 v[6:7], v195, 1.0 op_sel:[1,1,0]
	v_pk_fma_f32 v[58:59], v[30:31], s[68:69], v[58:59] op_sel_hi:[1,0,1]
	v_pk_fma_f32 v[60:61], v[2:3], s[68:69], v[60:61] op_sel_hi:[1,0,1]
	v_pk_fma_f32 v[62:63], v[6:7], s[68:69], v[62:63] op_sel_hi:[1,0,1]
	s_waitcnt vmcnt(8)
	v_cvt_scalef32_pk_f32_fp4 v[160:161], v196, 1.0
	v_cvt_scalef32_pk_f32_fp4 v[162:163], v196, 1.0 op_sel:[1,0,0]
	v_cvt_scalef32_pk_f32_fp4 v[18:19], v196, 1.0 op_sel:[0,1,0]
	v_pk_fma_f32 v[32:33], v[160:161], s[68:69], v[32:33] op_sel:[0,1,0] op_sel_hi:[1,1,1]
	v_cvt_scalef32_pk_f32_fp4 v[20:21], v196, 1.0 op_sel:[1,1,0]
	v_pk_fma_f32 v[34:35], v[162:163], s[68:69], v[34:35] op_sel:[0,1,0] op_sel_hi:[1,1,1]
	v_cvt_scalef32_pk_f32_fp4 v[22:23], v197, 1.0
	v_pk_fma_f32 v[36:37], v[18:19], s[68:69], v[36:37] op_sel:[0,1,0] op_sel_hi:[1,1,1]
	v_cvt_scalef32_pk_f32_fp4 v[30:31], v197, 1.0 op_sel:[1,0,0]
	v_pk_fma_f32 v[38:39], v[20:21], s[68:69], v[38:39] op_sel:[0,1,0] op_sel_hi:[1,1,1]
	v_cvt_scalef32_pk_f32_fp4 v[2:3], v197, 1.0 op_sel:[0,1,0]
	v_pk_fma_f32 v[40:41], v[22:23], s[68:69], v[40:41] op_sel:[0,1,0] op_sel_hi:[1,1,1]
	v_cvt_scalef32_pk_f32_fp4 v[6:7], v197, 1.0 op_sel:[1,1,0]
	v_pk_fma_f32 v[42:43], v[30:31], s[68:69], v[42:43] op_sel:[0,1,0] op_sel_hi:[1,1,1]
	v_cvt_scalef32_pk_f32_fp4 v[160:161], v198, 1.0
	v_pk_fma_f32 v[44:45], v[2:3], s[68:69], v[44:45] op_sel:[0,1,0] op_sel_hi:[1,1,1]
	v_cvt_scalef32_pk_f32_fp4 v[162:163], v198, 1.0 op_sel:[1,0,0]
	v_pk_fma_f32 v[46:47], v[6:7], s[68:69], v[46:47] op_sel:[0,1,0] op_sel_hi:[1,1,1]
	v_cvt_scalef32_pk_f32_fp4 v[18:19], v198, 1.0 op_sel:[0,1,0]
	v_pk_fma_f32 v[48:49], v[160:161], s[68:69], v[48:49] op_sel:[0,1,0] op_sel_hi:[1,1,1]
	v_cvt_scalef32_pk_f32_fp4 v[20:21], v198, 1.0 op_sel:[1,1,0]
	v_pk_fma_f32 v[50:51], v[162:163], s[68:69], v[50:51] op_sel:[0,1,0] op_sel_hi:[1,1,1]
	v_cvt_scalef32_pk_f32_fp4 v[22:23], v199, 1.0
	v_pk_fma_f32 v[52:53], v[18:19], s[68:69], v[52:53] op_sel:[0,1,0] op_sel_hi:[1,1,1]
	v_cvt_scalef32_pk_f32_fp4 v[30:31], v199, 1.0 op_sel:[1,0,0]
	v_pk_fma_f32 v[54:55], v[20:21], s[68:69], v[54:55] op_sel:[0,1,0] op_sel_hi:[1,1,1]
	v_cvt_scalef32_pk_f32_fp4 v[2:3], v199, 1.0 op_sel:[0,1,0]
	v_pk_fma_f32 v[56:57], v[22:23], s[68:69], v[56:57] op_sel:[0,1,0] op_sel_hi:[1,1,1]
	v_cvt_scalef32_pk_f32_fp4 v[6:7], v199, 1.0 op_sel:[1,1,0]
	v_pk_fma_f32 v[58:59], v[30:31], s[68:69], v[58:59] op_sel:[0,1,0] op_sel_hi:[1,1,1]
	v_pk_fma_f32 v[60:61], v[2:3], s[68:69], v[60:61] op_sel:[0,1,0] op_sel_hi:[1,1,1]
	v_pk_fma_f32 v[62:63], v[6:7], s[68:69], v[62:63] op_sel:[0,1,0] op_sel_hi:[1,1,1]
	s_waitcnt vmcnt(4)
	v_cvt_scalef32_pk_f32_fp4 v[160:161], v200, 1.0
	v_cvt_scalef32_pk_f32_fp4 v[162:163], v200, 1.0 op_sel:[1,0,0]
	v_cvt_scalef32_pk_f32_fp4 v[18:19], v200, 1.0 op_sel:[0,1,0]
	v_pk_fma_f32 v[32:33], v[160:161], s[70:71], v[32:33] op_sel_hi:[1,0,1]
	v_cvt_scalef32_pk_f32_fp4 v[20:21], v200, 1.0 op_sel:[1,1,0]
	v_pk_fma_f32 v[34:35], v[162:163], s[70:71], v[34:35] op_sel_hi:[1,0,1]
	v_cvt_scalef32_pk_f32_fp4 v[22:23], v201, 1.0
	v_pk_fma_f32 v[36:37], v[18:19], s[70:71], v[36:37] op_sel_hi:[1,0,1]
	v_cvt_scalef32_pk_f32_fp4 v[30:31], v201, 1.0 op_sel:[1,0,0]
	v_pk_fma_f32 v[38:39], v[20:21], s[70:71], v[38:39] op_sel_hi:[1,0,1]
	v_cvt_scalef32_pk_f32_fp4 v[2:3], v201, 1.0 op_sel:[0,1,0]
	v_pk_fma_f32 v[40:41], v[22:23], s[70:71], v[40:41] op_sel_hi:[1,0,1]
	v_cvt_scalef32_pk_f32_fp4 v[6:7], v201, 1.0 op_sel:[1,1,0]
	v_pk_fma_f32 v[42:43], v[30:31], s[70:71], v[42:43] op_sel_hi:[1,0,1]
	v_cvt_scalef32_pk_f32_fp4 v[160:161], v202, 1.0
	v_pk_fma_f32 v[44:45], v[2:3], s[70:71], v[44:45] op_sel_hi:[1,0,1]
	v_cvt_scalef32_pk_f32_fp4 v[162:163], v202, 1.0 op_sel:[1,0,0]
	v_pk_fma_f32 v[46:47], v[6:7], s[70:71], v[46:47] op_sel_hi:[1,0,1]
	v_cvt_scalef32_pk_f32_fp4 v[18:19], v202, 1.0 op_sel:[0,1,0]
	v_pk_fma_f32 v[48:49], v[160:161], s[70:71], v[48:49] op_sel_hi:[1,0,1]
	v_cvt_scalef32_pk_f32_fp4 v[20:21], v202, 1.0 op_sel:[1,1,0]
	v_pk_fma_f32 v[50:51], v[162:163], s[70:71], v[50:51] op_sel_hi:[1,0,1]
	v_cvt_scalef32_pk_f32_fp4 v[22:23], v203, 1.0
	v_pk_fma_f32 v[52:53], v[18:19], s[70:71], v[52:53] op_sel_hi:[1,0,1]
	v_cvt_scalef32_pk_f32_fp4 v[30:31], v203, 1.0 op_sel:[1,0,0]
	v_pk_fma_f32 v[54:55], v[20:21], s[70:71], v[54:55] op_sel_hi:[1,0,1]
	v_cvt_scalef32_pk_f32_fp4 v[2:3], v203, 1.0 op_sel:[0,1,0]
	v_pk_fma_f32 v[56:57], v[22:23], s[70:71], v[56:57] op_sel_hi:[1,0,1]
	v_cvt_scalef32_pk_f32_fp4 v[6:7], v203, 1.0 op_sel:[1,1,0]
	v_pk_fma_f32 v[58:59], v[30:31], s[70:71], v[58:59] op_sel_hi:[1,0,1]
	v_pk_fma_f32 v[60:61], v[2:3], s[70:71], v[60:61] op_sel_hi:[1,0,1]
	v_pk_fma_f32 v[62:63], v[6:7], s[70:71], v[62:63] op_sel_hi:[1,0,1]
	s_waitcnt vmcnt(0)
	v_cvt_scalef32_pk_f32_fp4 v[160:161], v240, 1.0
	v_cvt_scalef32_pk_f32_fp4 v[162:163], v240, 1.0 op_sel:[1,0,0]
	v_cvt_scalef32_pk_f32_fp4 v[18:19], v240, 1.0 op_sel:[0,1,0]
	v_pk_fma_f32 v[32:33], v[160:161], s[70:71], v[32:33] op_sel:[0,1,0] op_sel_hi:[1,1,1]
	v_cvt_scalef32_pk_f32_fp4 v[20:21], v240, 1.0 op_sel:[1,1,0]
	v_pk_fma_f32 v[34:35], v[162:163], s[70:71], v[34:35] op_sel:[0,1,0] op_sel_hi:[1,1,1]
	v_cvt_scalef32_pk_f32_fp4 v[22:23], v241, 1.0
	v_pk_fma_f32 v[36:37], v[18:19], s[70:71], v[36:37] op_sel:[0,1,0] op_sel_hi:[1,1,1]
	v_cvt_scalef32_pk_f32_fp4 v[30:31], v241, 1.0 op_sel:[1,0,0]
	v_pk_fma_f32 v[38:39], v[20:21], s[70:71], v[38:39] op_sel:[0,1,0] op_sel_hi:[1,1,1]
	v_cvt_scalef32_pk_f32_fp4 v[2:3], v241, 1.0 op_sel:[0,1,0]
	v_pk_fma_f32 v[40:41], v[22:23], s[70:71], v[40:41] op_sel:[0,1,0] op_sel_hi:[1,1,1]
	v_cvt_scalef32_pk_f32_fp4 v[6:7], v241, 1.0 op_sel:[1,1,0]
	v_pk_fma_f32 v[42:43], v[30:31], s[70:71], v[42:43] op_sel:[0,1,0] op_sel_hi:[1,1,1]
	v_cvt_scalef32_pk_f32_fp4 v[160:161], v242, 1.0
	v_pk_fma_f32 v[44:45], v[2:3], s[70:71], v[44:45] op_sel:[0,1,0] op_sel_hi:[1,1,1]
	v_cvt_scalef32_pk_f32_fp4 v[162:163], v242, 1.0 op_sel:[1,0,0]
	v_pk_fma_f32 v[46:47], v[6:7], s[70:71], v[46:47] op_sel:[0,1,0] op_sel_hi:[1,1,1]
	v_cvt_scalef32_pk_f32_fp4 v[18:19], v242, 1.0 op_sel:[0,1,0]
	v_pk_fma_f32 v[48:49], v[160:161], s[70:71], v[48:49] op_sel:[0,1,0] op_sel_hi:[1,1,1]
	v_cvt_scalef32_pk_f32_fp4 v[20:21], v242, 1.0 op_sel:[1,1,0]
	v_pk_fma_f32 v[50:51], v[162:163], s[70:71], v[50:51] op_sel:[0,1,0] op_sel_hi:[1,1,1]
	v_cvt_scalef32_pk_f32_fp4 v[22:23], v243, 1.0
	v_pk_fma_f32 v[52:53], v[18:19], s[70:71], v[52:53] op_sel:[0,1,0] op_sel_hi:[1,1,1]
	v_cvt_scalef32_pk_f32_fp4 v[30:31], v243, 1.0 op_sel:[1,0,0]
	v_pk_fma_f32 v[54:55], v[20:21], s[70:71], v[54:55] op_sel:[0,1,0] op_sel_hi:[1,1,1]
	v_cvt_scalef32_pk_f32_fp4 v[2:3], v243, 1.0 op_sel:[0,1,0]
	v_pk_fma_f32 v[56:57], v[22:23], s[70:71], v[56:57] op_sel:[0,1,0] op_sel_hi:[1,1,1]
	v_cvt_scalef32_pk_f32_fp4 v[6:7], v243, 1.0 op_sel:[1,1,0]
	v_pk_fma_f32 v[58:59], v[30:31], s[70:71], v[58:59] op_sel:[0,1,0] op_sel_hi:[1,1,1]
	v_pk_fma_f32 v[60:61], v[2:3], s[70:71], v[60:61] op_sel:[0,1,0] op_sel_hi:[1,1,1]
	v_pk_fma_f32 v[62:63], v[6:7], s[70:71], v[62:63] op_sel:[0,1,0] op_sel_hi:[1,1,1]
	v_lshlrev_b32_e32 v1, 13, v4
	v_lshl_add_u32 v1, v0, 6, v1
	v_add_u32_e32 v2, 0x1000, v1
	global_load_dwordx4 v[64:67], v1, s[92:93] offset:0
	global_load_dwordx4 v[68:71], v1, s[92:93] offset:16
	global_load_dwordx4 v[72:75], v1, s[92:93] offset:32
	global_load_dwordx4 v[76:79], v1, s[92:93] offset:48
	global_load_dwordx4 v[80:83], v2, s[92:93] offset:0
	global_load_dwordx4 v[84:87], v2, s[92:93] offset:16
	global_load_dwordx4 v[88:91], v2, s[92:93] offset:32
	global_load_dwordx4 v[92:95], v2, s[92:93] offset:48
	v_add_u32_e32 v4, s79, v4
	v_cmp_lt_i32_e32 vcc, s84, v4
	s_or_b64 s[60:61], vcc, s[60:61]
	s_waitcnt vmcnt(7)
	v_pk_add_f32 v[64:65], v[64:65], v[32:33]
	v_pk_add_f32 v[66:67], v[66:67], v[34:35]
	s_waitcnt vmcnt(6)
	v_pk_add_f32 v[68:69], v[68:69], v[36:37]
	v_pk_add_f32 v[70:71], v[70:71], v[38:39]
	s_waitcnt vmcnt(5)
	v_pk_add_f32 v[72:73], v[72:73], v[40:41]
	v_pk_add_f32 v[74:75], v[74:75], v[42:43]
	s_waitcnt vmcnt(4)
	v_pk_add_f32 v[76:77], v[76:77], v[44:45]
	v_pk_add_f32 v[78:79], v[78:79], v[46:47]
	s_waitcnt vmcnt(3)
	v_pk_add_f32 v[80:81], v[80:81], v[48:49]
	v_pk_add_f32 v[82:83], v[82:83], v[50:51]
	s_waitcnt vmcnt(2)
	v_pk_add_f32 v[84:85], v[84:85], v[52:53]
	v_pk_add_f32 v[86:87], v[86:87], v[54:55]
	s_waitcnt vmcnt(1)
	v_pk_add_f32 v[88:89], v[88:89], v[56:57]
	v_pk_add_f32 v[90:91], v[90:91], v[58:59]
	s_waitcnt vmcnt(0)
	v_pk_add_f32 v[92:93], v[92:93], v[60:61]
	v_pk_add_f32 v[94:95], v[94:95], v[62:63]
	global_store_dwordx4 v1, v[64:67], s[92:93] offset:0
	global_store_dwordx4 v1, v[68:71], s[92:93] offset:16
	global_store_dwordx4 v1, v[72:75], s[92:93] offset:32
	global_store_dwordx4 v1, v[76:79], s[92:93] offset:48
	global_store_dwordx4 v2, v[80:83], s[92:93] offset:0
	global_store_dwordx4 v2, v[84:87], s[92:93] offset:16
	global_store_dwordx4 v2, v[88:91], s[92:93] offset:32
	global_store_dwordx4 v2, v[92:95], s[92:93] offset:48
	s_andn2_b64 exec, exec, s[60:61]
	s_cbranch_execz .LBB0_930
	s_branch .LBB0_920
